# v49 + write-through split-K partials without L2 writeback + rstd prefetch as global loads without vmcnt(0) drains around the K-loop + attention q-tile loop waits counted (vmcnt 2/4) so the next Q tile
# speedup vs baseline: 1.0098x; 1.0098x over previous
.LBB0_194:
	s_cmp_eq_u32 s35, 28
	s_cselect_b64 s[4:5], -1, 0
	s_cmp_lg_u32 s35, 28
	s_cbranch_scc1 .LBB0_193
	global_load_dword v174, v[120:121], off
	global_load_dword v176, v[120:121], off offset:64
	global_load_dword v178, v[120:121], off offset:128
	global_load_dword v180, v[120:121], off offset:192
	global_load_dword v182, v[120:121], off offset:512
	global_load_dword v184, v[120:121], off offset:576
	global_load_dword v186, v[120:121], off offset:640
	global_load_dword v188, v[120:121], off offset:704
	s_branch .LBB0_193

.LBB0_198:
	s_waitcnt vmcnt(8)
	v_pk_mul_f32 v[114:115], v[174:175], v[114:115] op_sel_hi:[0,1]
	v_pk_mul_f32 v[112:113], v[174:175], v[112:113] op_sel_hi:[0,1]
	v_pk_mul_f32 v[118:119], v[174:175], v[118:119] op_sel_hi:[0,1]
	v_pk_mul_f32 v[116:117], v[174:175], v[116:117] op_sel_hi:[0,1]
	v_pk_mul_f32 v[122:123], v[174:175], v[106:107] op_sel_hi:[0,1]
	v_pk_mul_f32 v[120:121], v[174:175], v[104:105] op_sel_hi:[0,1]
	v_pk_mul_f32 v[126:127], v[174:175], v[98:99] op_sel_hi:[0,1]
	v_pk_mul_f32 v[124:125], v[174:175], v[96:97] op_sel_hi:[0,1]
	v_pk_mul_f32 v[110:111], v[176:177], v[110:111] op_sel_hi:[0,1]
	v_pk_mul_f32 v[108:109], v[176:177], v[108:109] op_sel_hi:[0,1]
	v_pk_mul_f32 v[106:107], v[176:177], v[102:103] op_sel_hi:[0,1]
	v_pk_mul_f32 v[104:105], v[176:177], v[100:101] op_sel_hi:[0,1]
	v_pk_mul_f32 v[102:103], v[176:177], v[90:91] op_sel_hi:[0,1]
	v_pk_mul_f32 v[100:101], v[176:177], v[88:89] op_sel_hi:[0,1]
	v_pk_mul_f32 v[98:99], v[176:177], v[82:83] op_sel_hi:[0,1]
	v_pk_mul_f32 v[96:97], v[176:177], v[80:81] op_sel_hi:[0,1]
	v_pk_mul_f32 v[94:95], v[178:179], v[94:95] op_sel_hi:[0,1]
	v_pk_mul_f32 v[92:93], v[178:179], v[92:93] op_sel_hi:[0,1]
	v_pk_mul_f32 v[90:91], v[178:179], v[86:87] op_sel_hi:[0,1]
	v_pk_mul_f32 v[88:89], v[178:179], v[84:85] op_sel_hi:[0,1]
	v_pk_mul_f32 v[86:87], v[178:179], v[74:75] op_sel_hi:[0,1]
	v_pk_mul_f32 v[84:85], v[178:179], v[72:73] op_sel_hi:[0,1]
	v_pk_mul_f32 v[82:83], v[178:179], v[66:67] op_sel_hi:[0,1]
	v_pk_mul_f32 v[80:81], v[178:179], v[64:65] op_sel_hi:[0,1]
	v_pk_mul_f32 v[78:79], v[180:181], v[78:79] op_sel_hi:[0,1]
	v_pk_mul_f32 v[76:77], v[180:181], v[76:77] op_sel_hi:[0,1]
	v_pk_mul_f32 v[74:75], v[180:181], v[70:71] op_sel_hi:[0,1]
	v_pk_mul_f32 v[72:73], v[180:181], v[68:69] op_sel_hi:[0,1]
	v_pk_mul_f32 v[70:71], v[180:181], v[62:63] op_sel_hi:[0,1]
	v_pk_mul_f32 v[68:69], v[180:181], v[60:61] op_sel_hi:[0,1]
	v_pk_mul_f32 v[66:67], v[180:181], v[58:59] op_sel_hi:[0,1]
	v_pk_mul_f32 v[64:65], v[180:181], v[56:57] op_sel_hi:[0,1]
	v_pk_mul_f32 v[62:63], v[182:183], v[54:55] op_sel_hi:[0,1]
	v_pk_mul_f32 v[60:61], v[182:183], v[52:53] op_sel_hi:[0,1]
	v_pk_mul_f32 v[58:59], v[182:183], v[50:51] op_sel_hi:[0,1]
	v_pk_mul_f32 v[56:57], v[182:183], v[48:49] op_sel_hi:[0,1]
	v_pk_mul_f32 v[54:55], v[182:183], v[42:43] op_sel_hi:[0,1]
	v_pk_mul_f32 v[52:53], v[182:183], v[40:41] op_sel_hi:[0,1]
	v_pk_mul_f32 v[50:51], v[182:183], v[34:35] op_sel_hi:[0,1]
	v_pk_mul_f32 v[48:49], v[182:183], v[32:33] op_sel_hi:[0,1]
	v_pk_mul_f32 v[46:47], v[184:185], v[46:47] op_sel_hi:[0,1]
	v_pk_mul_f32 v[44:45], v[184:185], v[44:45] op_sel_hi:[0,1]
	v_pk_mul_f32 v[42:43], v[184:185], v[38:39] op_sel_hi:[0,1]
	v_pk_mul_f32 v[40:41], v[184:185], v[36:37] op_sel_hi:[0,1]
	v_pk_mul_f32 v[38:39], v[184:185], v[26:27] op_sel_hi:[0,1]
	v_pk_mul_f32 v[36:37], v[184:185], v[24:25] op_sel_hi:[0,1]
	v_pk_mul_f32 v[34:35], v[184:185], v[18:19] op_sel_hi:[0,1]
	v_pk_mul_f32 v[32:33], v[184:185], v[16:17] op_sel_hi:[0,1]
	v_pk_mul_f32 v[30:31], v[186:187], v[30:31] op_sel_hi:[0,1]
	v_pk_mul_f32 v[28:29], v[186:187], v[28:29] op_sel_hi:[0,1]
	v_pk_mul_f32 v[26:27], v[186:187], v[22:23] op_sel_hi:[0,1]
	v_pk_mul_f32 v[24:25], v[186:187], v[20:21] op_sel_hi:[0,1]
	v_pk_mul_f32 v[22:23], v[186:187], v[14:15] op_sel_hi:[0,1]
	v_pk_mul_f32 v[20:21], v[186:187], v[12:13] op_sel_hi:[0,1]
	v_pk_mul_f32 v[18:19], v[186:187], v[10:11] op_sel_hi:[0,1]
	v_pk_mul_f32 v[16:17], v[186:187], v[8:9] op_sel_hi:[0,1]
	v_pk_mul_f32 v[14:15], v[188:189], v[134:135] op_sel_hi:[0,1]
	v_pk_mul_f32 v[12:13], v[188:189], v[132:133] op_sel_hi:[0,1]
	v_pk_mul_f32 v[10:11], v[188:189], v[130:131] op_sel_hi:[0,1]
	v_pk_mul_f32 v[8:9], v[188:189], v[128:129] op_sel_hi:[0,1]
	v_pk_mul_f32 v[6:7], v[188:189], v[6:7] op_sel_hi:[0,1]
	v_pk_mul_f32 v[4:5], v[188:189], v[4:5] op_sel_hi:[0,1]
	v_pk_mul_f32 v[2:3], v[188:189], v[2:3] op_sel_hi:[0,1]
	v_pk_mul_f32 v[0:1], v[188:189], v[0:1] op_sel_hi:[0,1]
	s_cmp_gt_i32 s10, 4
	s_mov_b64 s[0:1], -1
	s_cbranch_scc0 .LBB0_260
	s_cmp_lg_u32 s10, 5
	s_cbranch_scc0 .LBB0_233
	s_cmp_gt_u32 s10, 9
	s_cbranch_scc0 .LBB0_230
	s_cmp_gt_u32 s10, 17
	s_cbranch_scc0 .LBB0_227
	s_cmp_gt_u32 s10, 21
	s_cbranch_scc0 .LBB0_224
	s_cmp_gt_u32 s10, 25
	s_cbranch_scc0 .LBB0_205
	v_readlane_b32 s36, v254, 14
	v_lshl_add_u32 v152, s10, 8, v179
	v_readlane_b32 s50, v254, 28
	v_readlane_b32 s51, v254, 29
	s_mov_b32 s4, 0x437f0000
	v_readlane_b32 s0, v254, 60
	v_lshl_add_u64 v[132:133], v[152:153], 2, s[50:51]
	global_load_dwordx4 v[136:139], v[132:133], off offset:16
	global_load_dwordx4 v[140:143], v[132:133], off
	global_load_dwordx4 v[128:131], v[132:133], off offset:528
	s_nop 0
	global_load_dwordx4 v[132:135], v[132:133], off offset:512
	v_readlane_b32 s1, v254, 61
	s_movk_i32 s3, 0x1800
	v_readlane_b32 s37, v254, 15
	v_mov_b64_e32 v[192:193], s[0:1]
	v_mad_i64_i32 v[194:195], s[0:1], v190, s3, v[192:193]
	v_lshl_add_u64 v[194:195], v[194:195], 0, v[152:153]
	v_readlane_b32 s38, v254, 16
	v_readlane_b32 s39, v254, 17
	v_readlane_b32 s40, v254, 18
	v_readlane_b32 s41, v254, 19
	v_readlane_b32 s42, v254, 20
	v_readlane_b32 s43, v254, 21
	v_readlane_b32 s44, v254, 22
	v_readlane_b32 s45, v254, 23
	v_readlane_b32 s46, v254, 24
	v_readlane_b32 s47, v254, 25
	v_readlane_b32 s48, v254, 26
	v_readlane_b32 s49, v254, 27
	s_waitcnt vmcnt(3)
	v_pk_add_f32 v[200:201], v[116:117], v[136:137]
	s_waitcnt vmcnt(2)
	v_pk_add_f32 v[198:199], v[112:113], v[140:141]
	v_pk_add_f32 v[196:197], v[114:115], v[142:143]
	v_mul_f32_e32 v198, 0xbfb8aa3b, v198
	v_mul_f32_e32 v199, 0xbfb8aa3b, v199
	v_exp_f32_e32 v198, v198
	v_exp_f32_e32 v199, v199
	v_mul_f32_e32 v196, 0xbfb8aa3b, v196
	v_mul_f32_e32 v197, 0xbfb8aa3b, v197
	v_exp_f32_e32 v196, v196
	v_exp_f32_e32 v197, v197
	v_add_f32_e32 v198, 1.0, v198
	v_add_f32_e32 v199, 1.0, v199
	v_rcp_f32_e32 v198, v198
	v_rcp_f32_e32 v199, v199
	v_add_f32_e32 v196, 1.0, v196
	v_add_f32_e32 v197, 1.0, v197
	v_rcp_f32_e32 v196, v196
	v_rcp_f32_e32 v197, v197
	v_pk_fma_f32 v[198:199], v[198:199], s[4:5], 0.5 op_sel_hi:[1,0,0]
	v_pk_fma_f32 v[196:197], v[196:197], s[4:5], 0.5 op_sel_hi:[1,0,0]
	v_cvt_u32_f32_e32 v198, v198
	v_cvt_u32_f32_e32 v199, v199
	v_cvt_u32_f32_sdwa v196, v196 dst_sel:WORD_1 dst_unused:UNUSED_PAD src0_sel:DWORD
	v_cvt_u32_f32_sdwa v197, v197 dst_sel:BYTE_3 dst_unused:UNUSED_PAD src0_sel:DWORD
	v_lshl_or_b32 v198, v199, 8, v198
	v_or3_b32 v196, v198, v196, v197
	v_mul_f32_e32 v197, 0xbfb8aa3b, v200
	v_exp_f32_e32 v197, v197
	v_pk_add_f32 v[198:199], v[118:119], v[138:139]
	v_add_f32_e32 v197, 1.0, v197
	v_rcp_f32_e32 v200, v197
	v_mul_f32_e32 v197, 0xbfb8aa3b, v201
	v_exp_f32_e32 v197, v197
	s_nop 0
	v_add_f32_e32 v197, 1.0, v197
	v_rcp_f32_e32 v201, v197
	v_mul_f32_e32 v197, 0xbfb8aa3b, v198
	v_exp_f32_e32 v197, v197
	v_pk_fma_f32 v[200:201], v[200:201], s[4:5], 0.5 op_sel_hi:[1,0,0]
	v_add_f32_e32 v197, 1.0, v197
	v_rcp_f32_e32 v198, v197
	v_mul_f32_e32 v197, 0xbfb8aa3b, v199
	v_exp_f32_e32 v197, v197
	s_nop 0
	v_add_f32_e32 v197, 1.0, v197
	v_rcp_f32_e32 v199, v197
	v_cvt_u32_f32_e32 v197, v200
	v_cvt_u32_f32_e32 v200, v201
	v_pk_fma_f32 v[198:199], v[198:199], s[4:5], 0.5 op_sel_hi:[1,0,0]
	s_nop 0
	v_cvt_u32_f32_sdwa v198, v198 dst_sel:WORD_1 dst_unused:UNUSED_PAD src0_sel:DWORD
	v_cvt_u32_f32_sdwa v199, v199 dst_sel:BYTE_3 dst_unused:UNUSED_PAD src0_sel:DWORD
	v_lshl_or_b32 v197, v200, 8, v197
	s_waitcnt vmcnt(1)
	v_pk_add_f32 v[200:201], v[126:127], v[130:131]
	v_or3_b32 v197, v197, v198, v199
	s_waitcnt vmcnt(0)
	v_pk_add_f32 v[198:199], v[120:121], v[132:133]
	global_store_dwordx2 v[194:195], v[196:197], off
	v_pk_add_f32 v[196:197], v[122:123], v[134:135]
	v_mul_f32_e32 v198, 0xbfb8aa3b, v198
	v_mul_f32_e32 v199, 0xbfb8aa3b, v199
	v_exp_f32_e32 v198, v198
	v_exp_f32_e32 v199, v199
	v_mul_f32_e32 v196, 0xbfb8aa3b, v196
	v_mul_f32_e32 v197, 0xbfb8aa3b, v197
	v_exp_f32_e32 v196, v196
	v_exp_f32_e32 v197, v197
	v_add_f32_e32 v198, 1.0, v198
	v_add_f32_e32 v199, 1.0, v199
	v_rcp_f32_e32 v198, v198
	v_rcp_f32_e32 v199, v199
	v_add_f32_e32 v196, 1.0, v196
	v_add_f32_e32 v197, 1.0, v197
	v_rcp_f32_e32 v196, v196
	v_rcp_f32_e32 v197, v197
	v_pk_fma_f32 v[198:199], v[198:199], s[4:5], 0.5 op_sel_hi:[1,0,0]
	v_pk_fma_f32 v[196:197], v[196:197], s[4:5], 0.5 op_sel_hi:[1,0,0]
	v_cvt_u32_f32_e32 v198, v198
	v_cvt_u32_f32_e32 v199, v199
	v_cvt_u32_f32_sdwa v196, v196 dst_sel:WORD_1 dst_unused:UNUSED_PAD src0_sel:DWORD
	v_cvt_u32_f32_sdwa v197, v197 dst_sel:BYTE_3 dst_unused:UNUSED_PAD src0_sel:DWORD
	v_lshl_or_b32 v198, v199, 8, v198
	v_or3_b32 v196, v198, v196, v197
	v_pk_add_f32 v[198:199], v[124:125], v[128:129]
	s_nop 0
	v_mul_f32_e32 v197, 0xbfb8aa3b, v198
	v_exp_f32_e32 v197, v197
	s_nop 0
	v_add_f32_e32 v197, 1.0, v197
	v_rcp_f32_e32 v198, v197
	v_mul_f32_e32 v197, 0xbfb8aa3b, v199
	v_exp_f32_e32 v197, v197
	s_nop 0
	v_add_f32_e32 v197, 1.0, v197
	v_rcp_f32_e32 v199, v197
	v_mul_f32_e32 v197, 0xbfb8aa3b, v200
	v_exp_f32_e32 v197, v197
	v_pk_fma_f32 v[198:199], v[198:199], s[4:5], 0.5 op_sel_hi:[1,0,0]
	v_add_f32_e32 v197, 1.0, v197
	v_rcp_f32_e32 v200, v197
	v_mul_f32_e32 v197, 0xbfb8aa3b, v201
	v_exp_f32_e32 v197, v197
	s_nop 0
	v_add_f32_e32 v197, 1.0, v197
	v_rcp_f32_e32 v201, v197
	v_cvt_u32_f32_e32 v197, v198
	v_cvt_u32_f32_e32 v198, v199
	v_pk_fma_f32 v[200:201], v[200:201], s[4:5], 0.5 op_sel_hi:[1,0,0]
	s_nop 0
	v_cvt_u32_f32_sdwa v199, v201 dst_sel:BYTE_3 dst_unused:UNUSED_PAD src0_sel:DWORD
	v_lshl_or_b32 v197, v198, 8, v197
	v_cvt_u32_f32_sdwa v198, v200 dst_sel:WORD_1 dst_unused:UNUSED_PAD src0_sel:DWORD
	v_pk_add_f32 v[200:201], v[104:105], v[136:137]
	v_or3_b32 v197, v197, v198, v199
	v_pk_add_f32 v[198:199], v[108:109], v[140:141]
	global_store_dwordx2 v[194:195], v[196:197], off offset:128
	v_pk_add_f32 v[196:197], v[110:111], v[142:143]
	v_mul_f32_e32 v198, 0xbfb8aa3b, v198
	v_mul_f32_e32 v199, 0xbfb8aa3b, v199
	v_exp_f32_e32 v198, v198
	v_exp_f32_e32 v199, v199
	v_mul_f32_e32 v196, 0xbfb8aa3b, v196
	v_mul_f32_e32 v197, 0xbfb8aa3b, v197
	v_exp_f32_e32 v196, v196
	v_exp_f32_e32 v197, v197
	v_add_f32_e32 v198, 1.0, v198
	v_add_f32_e32 v199, 1.0, v199
	v_rcp_f32_e32 v198, v198
	v_rcp_f32_e32 v199, v199
	v_add_f32_e32 v196, 1.0, v196
	v_add_f32_e32 v197, 1.0, v197
	v_rcp_f32_e32 v196, v196
	v_rcp_f32_e32 v197, v197
	v_pk_fma_f32 v[198:199], v[198:199], s[4:5], 0.5 op_sel_hi:[1,0,0]
	v_or_b32_e32 v194, 16, v190
	v_cvt_u32_f32_e32 v198, v198
	v_pk_fma_f32 v[196:197], v[196:197], s[4:5], 0.5 op_sel_hi:[1,0,0]
	v_cvt_u32_f32_e32 v199, v199
	v_cvt_u32_f32_sdwa v196, v196 dst_sel:WORD_1 dst_unused:UNUSED_PAD src0_sel:DWORD
	v_cvt_u32_f32_sdwa v197, v197 dst_sel:BYTE_3 dst_unused:UNUSED_PAD src0_sel:DWORD
	v_mad_i64_i32 v[194:195], s[0:1], v194, s3, v[192:193]
	v_lshl_or_b32 v198, v199, 8, v198
	v_or3_b32 v196, v198, v196, v197
	v_mul_f32_e32 v197, 0xbfb8aa3b, v200
	v_exp_f32_e32 v197, v197
	v_pk_add_f32 v[198:199], v[106:107], v[138:139]
	v_lshl_add_u64 v[194:195], v[194:195], 0, v[152:153]
	v_add_f32_e32 v197, 1.0, v197
	v_rcp_f32_e32 v200, v197
	v_mul_f32_e32 v197, 0xbfb8aa3b, v201
	v_exp_f32_e32 v197, v197
	s_nop 0
	v_add_f32_e32 v197, 1.0, v197
	v_rcp_f32_e32 v201, v197
	v_mul_f32_e32 v197, 0xbfb8aa3b, v198
	v_exp_f32_e32 v197, v197
	v_pk_fma_f32 v[200:201], v[200:201], s[4:5], 0.5 op_sel_hi:[1,0,0]
	v_add_f32_e32 v197, 1.0, v197
	v_rcp_f32_e32 v198, v197
	v_mul_f32_e32 v197, 0xbfb8aa3b, v199
	v_exp_f32_e32 v197, v197
	s_nop 0
	v_add_f32_e32 v197, 1.0, v197
	v_rcp_f32_e32 v199, v197
	v_cvt_u32_f32_e32 v197, v200
	v_cvt_u32_f32_e32 v200, v201
	v_pk_fma_f32 v[198:199], v[198:199], s[4:5], 0.5 op_sel_hi:[1,0,0]
	s_nop 0
	v_cvt_u32_f32_sdwa v198, v198 dst_sel:WORD_1 dst_unused:UNUSED_PAD src0_sel:DWORD
	v_cvt_u32_f32_sdwa v199, v199 dst_sel:BYTE_3 dst_unused:UNUSED_PAD src0_sel:DWORD
	v_lshl_or_b32 v197, v200, 8, v197
	v_pk_add_f32 v[200:201], v[96:97], v[128:129]
	v_or3_b32 v197, v197, v198, v199
	v_pk_add_f32 v[198:199], v[100:101], v[132:133]
	global_store_dwordx2 v[194:195], v[196:197], off
	v_pk_add_f32 v[196:197], v[102:103], v[134:135]
	v_mul_f32_e32 v198, 0xbfb8aa3b, v198
	v_mul_f32_e32 v199, 0xbfb8aa3b, v199
	v_exp_f32_e32 v198, v198
	v_exp_f32_e32 v199, v199
	v_mul_f32_e32 v196, 0xbfb8aa3b, v196
	v_mul_f32_e32 v197, 0xbfb8aa3b, v197
	v_exp_f32_e32 v196, v196
	v_exp_f32_e32 v197, v197
	v_add_f32_e32 v198, 1.0, v198
	v_add_f32_e32 v199, 1.0, v199
	v_rcp_f32_e32 v198, v198
	v_rcp_f32_e32 v199, v199
	v_add_f32_e32 v196, 1.0, v196
	v_add_f32_e32 v197, 1.0, v197
	v_rcp_f32_e32 v196, v196
	v_rcp_f32_e32 v197, v197
	v_pk_fma_f32 v[198:199], v[198:199], s[4:5], 0.5 op_sel_hi:[1,0,0]
	v_pk_fma_f32 v[196:197], v[196:197], s[4:5], 0.5 op_sel_hi:[1,0,0]
	v_cvt_u32_f32_e32 v198, v198
	v_cvt_u32_f32_e32 v199, v199
	v_cvt_u32_f32_sdwa v196, v196 dst_sel:WORD_1 dst_unused:UNUSED_PAD src0_sel:DWORD
	v_cvt_u32_f32_sdwa v197, v197 dst_sel:BYTE_3 dst_unused:UNUSED_PAD src0_sel:DWORD
	v_lshl_or_b32 v198, v199, 8, v198
	v_or3_b32 v196, v198, v196, v197
	v_mul_f32_e32 v197, 0xbfb8aa3b, v200
	v_exp_f32_e32 v197, v197
	v_pk_add_f32 v[198:199], v[98:99], v[130:131]
	v_add_f32_e32 v197, 1.0, v197
	v_rcp_f32_e32 v200, v197
	v_mul_f32_e32 v197, 0xbfb8aa3b, v201
	v_exp_f32_e32 v197, v197
	s_nop 0
	v_add_f32_e32 v197, 1.0, v197
	v_rcp_f32_e32 v201, v197
	v_mul_f32_e32 v197, 0xbfb8aa3b, v198
	v_exp_f32_e32 v197, v197
	v_pk_fma_f32 v[200:201], v[200:201], s[4:5], 0.5 op_sel_hi:[1,0,0]
	v_add_f32_e32 v197, 1.0, v197
	v_rcp_f32_e32 v198, v197
	v_mul_f32_e32 v197, 0xbfb8aa3b, v199
	v_exp_f32_e32 v197, v197
	s_nop 0
	v_add_f32_e32 v197, 1.0, v197
	v_rcp_f32_e32 v199, v197
	v_cvt_u32_f32_e32 v197, v200
	v_cvt_u32_f32_e32 v200, v201
	v_pk_fma_f32 v[198:199], v[198:199], s[4:5], 0.5 op_sel_hi:[1,0,0]
	s_nop 0
	v_cvt_u32_f32_sdwa v198, v198 dst_sel:WORD_1 dst_unused:UNUSED_PAD src0_sel:DWORD
	v_cvt_u32_f32_sdwa v199, v199 dst_sel:BYTE_3 dst_unused:UNUSED_PAD src0_sel:DWORD
	v_lshl_or_b32 v197, v200, 8, v197
	v_pk_add_f32 v[200:201], v[88:89], v[136:137]
	v_or3_b32 v197, v197, v198, v199
	v_pk_add_f32 v[198:199], v[92:93], v[140:141]
	global_store_dwordx2 v[194:195], v[196:197], off offset:128
	v_pk_add_f32 v[196:197], v[94:95], v[142:143]
	v_mul_f32_e32 v198, 0xbfb8aa3b, v198
	v_mul_f32_e32 v199, 0xbfb8aa3b, v199
	v_exp_f32_e32 v198, v198
	v_exp_f32_e32 v199, v199
	v_mul_f32_e32 v196, 0xbfb8aa3b, v196
	v_mul_f32_e32 v197, 0xbfb8aa3b, v197
	v_exp_f32_e32 v196, v196
	v_exp_f32_e32 v197, v197
	v_add_f32_e32 v198, 1.0, v198
	v_add_f32_e32 v199, 1.0, v199
	v_rcp_f32_e32 v198, v198
	v_rcp_f32_e32 v199, v199
	v_add_f32_e32 v196, 1.0, v196
	v_add_f32_e32 v197, 1.0, v197
	v_rcp_f32_e32 v196, v196
	v_rcp_f32_e32 v197, v197
	v_pk_fma_f32 v[198:199], v[198:199], s[4:5], 0.5 op_sel_hi:[1,0,0]
	v_or_b32_e32 v194, 32, v190
	v_cvt_u32_f32_e32 v198, v198
	v_pk_fma_f32 v[196:197], v[196:197], s[4:5], 0.5 op_sel_hi:[1,0,0]
	v_cvt_u32_f32_e32 v199, v199
	v_cvt_u32_f32_sdwa v196, v196 dst_sel:WORD_1 dst_unused:UNUSED_PAD src0_sel:DWORD
	v_cvt_u32_f32_sdwa v197, v197 dst_sel:BYTE_3 dst_unused:UNUSED_PAD src0_sel:DWORD
	v_mad_i64_i32 v[194:195], s[0:1], v194, s3, v[192:193]
	v_lshl_or_b32 v198, v199, 8, v198
	v_or3_b32 v196, v198, v196, v197
	v_mul_f32_e32 v197, 0xbfb8aa3b, v200
	v_exp_f32_e32 v197, v197
	v_pk_add_f32 v[198:199], v[90:91], v[138:139]
	v_lshl_add_u64 v[194:195], v[194:195], 0, v[152:153]
	v_add_f32_e32 v197, 1.0, v197
	v_rcp_f32_e32 v200, v197
	v_mul_f32_e32 v197, 0xbfb8aa3b, v201
	v_exp_f32_e32 v197, v197
	s_nop 0
	v_add_f32_e32 v197, 1.0, v197
	v_rcp_f32_e32 v201, v197
	v_mul_f32_e32 v197, 0xbfb8aa3b, v198
	v_exp_f32_e32 v197, v197
	v_pk_fma_f32 v[200:201], v[200:201], s[4:5], 0.5 op_sel_hi:[1,0,0]
	v_add_f32_e32 v197, 1.0, v197
	v_rcp_f32_e32 v198, v197
	v_mul_f32_e32 v197, 0xbfb8aa3b, v199
	v_exp_f32_e32 v197, v197
	s_nop 0
	v_add_f32_e32 v197, 1.0, v197
	v_rcp_f32_e32 v199, v197
	v_cvt_u32_f32_e32 v197, v200
	v_cvt_u32_f32_e32 v200, v201
	v_pk_fma_f32 v[198:199], v[198:199], s[4:5], 0.5 op_sel_hi:[1,0,0]
	s_nop 0
	v_cvt_u32_f32_sdwa v198, v198 dst_sel:WORD_1 dst_unused:UNUSED_PAD src0_sel:DWORD
	v_cvt_u32_f32_sdwa v199, v199 dst_sel:BYTE_3 dst_unused:UNUSED_PAD src0_sel:DWORD
	v_lshl_or_b32 v197, v200, 8, v197
	v_pk_add_f32 v[200:201], v[80:81], v[128:129]
	v_or3_b32 v197, v197, v198, v199
	v_pk_add_f32 v[198:199], v[84:85], v[132:133]
	global_store_dwordx2 v[194:195], v[196:197], off
	v_pk_add_f32 v[196:197], v[86:87], v[134:135]
	v_mul_f32_e32 v198, 0xbfb8aa3b, v198
	v_mul_f32_e32 v199, 0xbfb8aa3b, v199
	v_exp_f32_e32 v198, v198
	v_exp_f32_e32 v199, v199
	v_mul_f32_e32 v196, 0xbfb8aa3b, v196
	v_mul_f32_e32 v197, 0xbfb8aa3b, v197
	v_exp_f32_e32 v196, v196
	v_exp_f32_e32 v197, v197
	v_add_f32_e32 v198, 1.0, v198
	v_add_f32_e32 v199, 1.0, v199
	v_rcp_f32_e32 v198, v198
	v_rcp_f32_e32 v199, v199
	v_add_f32_e32 v196, 1.0, v196
	v_add_f32_e32 v197, 1.0, v197
	v_rcp_f32_e32 v196, v196
	v_rcp_f32_e32 v197, v197
	v_pk_fma_f32 v[198:199], v[198:199], s[4:5], 0.5 op_sel_hi:[1,0,0]
	v_pk_fma_f32 v[196:197], v[196:197], s[4:5], 0.5 op_sel_hi:[1,0,0]
	v_cvt_u32_f32_e32 v198, v198
	v_cvt_u32_f32_e32 v199, v199
	v_cvt_u32_f32_sdwa v196, v196 dst_sel:WORD_1 dst_unused:UNUSED_PAD src0_sel:DWORD
	v_cvt_u32_f32_sdwa v197, v197 dst_sel:BYTE_3 dst_unused:UNUSED_PAD src0_sel:DWORD
	v_lshl_or_b32 v198, v199, 8, v198
	v_or3_b32 v196, v198, v196, v197
	v_mul_f32_e32 v197, 0xbfb8aa3b, v200
	v_exp_f32_e32 v197, v197
	v_pk_add_f32 v[198:199], v[82:83], v[130:131]
	v_add_f32_e32 v197, 1.0, v197
	v_rcp_f32_e32 v200, v197
	v_mul_f32_e32 v197, 0xbfb8aa3b, v201
	v_exp_f32_e32 v197, v197
	s_nop 0
	v_add_f32_e32 v197, 1.0, v197
	v_rcp_f32_e32 v201, v197
	v_mul_f32_e32 v197, 0xbfb8aa3b, v198
	v_exp_f32_e32 v197, v197
	v_pk_fma_f32 v[200:201], v[200:201], s[4:5], 0.5 op_sel_hi:[1,0,0]
	v_add_f32_e32 v197, 1.0, v197
	v_rcp_f32_e32 v198, v197
	v_mul_f32_e32 v197, 0xbfb8aa3b, v199
	v_exp_f32_e32 v197, v197
	s_nop 0
	v_add_f32_e32 v197, 1.0, v197
	v_rcp_f32_e32 v199, v197
	v_cvt_u32_f32_e32 v197, v200
	v_cvt_u32_f32_e32 v200, v201
	v_pk_fma_f32 v[198:199], v[198:199], s[4:5], 0.5 op_sel_hi:[1,0,0]
	s_nop 0
	v_cvt_u32_f32_sdwa v198, v198 dst_sel:WORD_1 dst_unused:UNUSED_PAD src0_sel:DWORD
	v_cvt_u32_f32_sdwa v199, v199 dst_sel:BYTE_3 dst_unused:UNUSED_PAD src0_sel:DWORD
	v_lshl_or_b32 v197, v200, 8, v197
	v_pk_add_f32 v[200:201], v[72:73], v[136:137]
	v_or3_b32 v197, v197, v198, v199
	v_pk_add_f32 v[198:199], v[76:77], v[140:141]
	global_store_dwordx2 v[194:195], v[196:197], off offset:128
	v_pk_add_f32 v[196:197], v[78:79], v[142:143]
	v_mul_f32_e32 v198, 0xbfb8aa3b, v198
	v_mul_f32_e32 v199, 0xbfb8aa3b, v199
	v_exp_f32_e32 v198, v198
	v_exp_f32_e32 v199, v199
	v_mul_f32_e32 v196, 0xbfb8aa3b, v196
	v_mul_f32_e32 v197, 0xbfb8aa3b, v197
	v_exp_f32_e32 v196, v196
	v_exp_f32_e32 v197, v197
	v_add_f32_e32 v198, 1.0, v198
	v_add_f32_e32 v199, 1.0, v199
	v_rcp_f32_e32 v198, v198
	v_rcp_f32_e32 v199, v199
	v_add_f32_e32 v196, 1.0, v196
	v_add_f32_e32 v197, 1.0, v197
	v_rcp_f32_e32 v196, v196
	v_rcp_f32_e32 v197, v197
	v_pk_fma_f32 v[198:199], v[198:199], s[4:5], 0.5 op_sel_hi:[1,0,0]
	v_or_b32_e32 v194, 48, v190
	v_cvt_u32_f32_e32 v198, v198
	v_pk_fma_f32 v[196:197], v[196:197], s[4:5], 0.5 op_sel_hi:[1,0,0]
	v_cvt_u32_f32_e32 v199, v199
	v_cvt_u32_f32_sdwa v196, v196 dst_sel:WORD_1 dst_unused:UNUSED_PAD src0_sel:DWORD
	v_cvt_u32_f32_sdwa v197, v197 dst_sel:BYTE_3 dst_unused:UNUSED_PAD src0_sel:DWORD
	v_mad_i64_i32 v[194:195], s[0:1], v194, s3, v[192:193]
	v_lshl_or_b32 v198, v199, 8, v198
	v_or3_b32 v196, v198, v196, v197
	v_mul_f32_e32 v197, 0xbfb8aa3b, v200
	v_exp_f32_e32 v197, v197
	v_pk_add_f32 v[198:199], v[74:75], v[138:139]
	v_lshl_add_u64 v[194:195], v[194:195], 0, v[152:153]
	v_add_f32_e32 v197, 1.0, v197
	v_rcp_f32_e32 v200, v197
	v_mul_f32_e32 v197, 0xbfb8aa3b, v201
	v_exp_f32_e32 v197, v197
	s_nop 0
	v_add_f32_e32 v197, 1.0, v197
	v_rcp_f32_e32 v201, v197
	v_mul_f32_e32 v197, 0xbfb8aa3b, v198
	v_exp_f32_e32 v197, v197
	v_pk_fma_f32 v[200:201], v[200:201], s[4:5], 0.5 op_sel_hi:[1,0,0]
	v_add_f32_e32 v197, 1.0, v197
	v_rcp_f32_e32 v198, v197
	v_mul_f32_e32 v197, 0xbfb8aa3b, v199
	v_exp_f32_e32 v197, v197
	s_nop 0
	v_add_f32_e32 v197, 1.0, v197
	v_rcp_f32_e32 v199, v197
	v_cvt_u32_f32_e32 v197, v200
	v_cvt_u32_f32_e32 v200, v201
	v_pk_fma_f32 v[198:199], v[198:199], s[4:5], 0.5 op_sel_hi:[1,0,0]
	s_nop 0
	v_cvt_u32_f32_sdwa v198, v198 dst_sel:WORD_1 dst_unused:UNUSED_PAD src0_sel:DWORD
	v_cvt_u32_f32_sdwa v199, v199 dst_sel:BYTE_3 dst_unused:UNUSED_PAD src0_sel:DWORD
	v_lshl_or_b32 v197, v200, 8, v197
	v_pk_add_f32 v[200:201], v[64:65], v[128:129]
	v_or3_b32 v197, v197, v198, v199
	v_pk_add_f32 v[198:199], v[68:69], v[132:133]
	global_store_dwordx2 v[194:195], v[196:197], off
	v_pk_add_f32 v[196:197], v[70:71], v[134:135]
	v_mul_f32_e32 v198, 0xbfb8aa3b, v198
	v_mul_f32_e32 v199, 0xbfb8aa3b, v199
	v_exp_f32_e32 v198, v198
	v_exp_f32_e32 v199, v199
	v_mul_f32_e32 v196, 0xbfb8aa3b, v196
	v_mul_f32_e32 v197, 0xbfb8aa3b, v197
	v_exp_f32_e32 v196, v196
	v_exp_f32_e32 v197, v197
	v_add_f32_e32 v198, 1.0, v198
	v_add_f32_e32 v199, 1.0, v199
	v_rcp_f32_e32 v198, v198
	v_rcp_f32_e32 v199, v199
	v_add_f32_e32 v196, 1.0, v196
	v_add_f32_e32 v197, 1.0, v197
	v_rcp_f32_e32 v196, v196
	v_rcp_f32_e32 v197, v197
	v_pk_fma_f32 v[198:199], v[198:199], s[4:5], 0.5 op_sel_hi:[1,0,0]
	v_pk_fma_f32 v[196:197], v[196:197], s[4:5], 0.5 op_sel_hi:[1,0,0]
	v_cvt_u32_f32_e32 v198, v198
	v_cvt_u32_f32_e32 v199, v199
	v_cvt_u32_f32_sdwa v196, v196 dst_sel:WORD_1 dst_unused:UNUSED_PAD src0_sel:DWORD
	v_cvt_u32_f32_sdwa v197, v197 dst_sel:BYTE_3 dst_unused:UNUSED_PAD src0_sel:DWORD
	v_lshl_or_b32 v198, v199, 8, v198
	v_or3_b32 v196, v198, v196, v197
	v_mul_f32_e32 v197, 0xbfb8aa3b, v200
	v_exp_f32_e32 v197, v197
	v_pk_add_f32 v[198:199], v[66:67], v[130:131]
	v_add_f32_e32 v197, 1.0, v197
	v_rcp_f32_e32 v200, v197
	v_mul_f32_e32 v197, 0xbfb8aa3b, v201
	v_exp_f32_e32 v197, v197
	s_nop 0
	v_add_f32_e32 v197, 1.0, v197
	v_rcp_f32_e32 v201, v197
	v_mul_f32_e32 v197, 0xbfb8aa3b, v198
	v_exp_f32_e32 v197, v197
	v_pk_fma_f32 v[200:201], v[200:201], s[4:5], 0.5 op_sel_hi:[1,0,0]
	v_add_f32_e32 v197, 1.0, v197
	v_rcp_f32_e32 v198, v197
	v_mul_f32_e32 v197, 0xbfb8aa3b, v199
	v_exp_f32_e32 v197, v197
	s_nop 0
	v_add_f32_e32 v197, 1.0, v197
	v_rcp_f32_e32 v199, v197
	v_cvt_u32_f32_e32 v197, v200
	v_cvt_u32_f32_e32 v200, v201
	v_pk_fma_f32 v[198:199], v[198:199], s[4:5], 0.5 op_sel_hi:[1,0,0]
	s_nop 0
	v_cvt_u32_f32_sdwa v198, v198 dst_sel:WORD_1 dst_unused:UNUSED_PAD src0_sel:DWORD
	v_cvt_u32_f32_sdwa v199, v199 dst_sel:BYTE_3 dst_unused:UNUSED_PAD src0_sel:DWORD
	v_lshl_or_b32 v197, v200, 8, v197
	v_pk_add_f32 v[200:201], v[56:57], v[136:137]
	v_or3_b32 v197, v197, v198, v199
	v_pk_add_f32 v[198:199], v[60:61], v[140:141]
	global_store_dwordx2 v[194:195], v[196:197], off offset:128
	v_pk_add_f32 v[196:197], v[62:63], v[142:143]
	v_mul_f32_e32 v198, 0xbfb8aa3b, v198
	v_mul_f32_e32 v199, 0xbfb8aa3b, v199
	v_exp_f32_e32 v198, v198
	v_exp_f32_e32 v199, v199
	v_mul_f32_e32 v196, 0xbfb8aa3b, v196
	v_mul_f32_e32 v197, 0xbfb8aa3b, v197
	v_exp_f32_e32 v196, v196
	v_exp_f32_e32 v197, v197
	v_add_f32_e32 v198, 1.0, v198
	v_add_f32_e32 v199, 1.0, v199
	v_rcp_f32_e32 v198, v198
	v_rcp_f32_e32 v199, v199
	v_add_f32_e32 v196, 1.0, v196
	v_add_f32_e32 v197, 1.0, v197
	v_rcp_f32_e32 v196, v196
	v_rcp_f32_e32 v197, v197
	v_pk_fma_f32 v[198:199], v[198:199], s[4:5], 0.5 op_sel_hi:[1,0,0]
	v_add_u32_e32 v194, 0x80, v190
	v_cvt_u32_f32_e32 v198, v198
	v_pk_fma_f32 v[196:197], v[196:197], s[4:5], 0.5 op_sel_hi:[1,0,0]
	v_cvt_u32_f32_e32 v199, v199
	v_cvt_u32_f32_sdwa v196, v196 dst_sel:WORD_1 dst_unused:UNUSED_PAD src0_sel:DWORD
	v_cvt_u32_f32_sdwa v197, v197 dst_sel:BYTE_3 dst_unused:UNUSED_PAD src0_sel:DWORD
	v_mad_i64_i32 v[194:195], s[0:1], v194, s3, v[192:193]
	v_lshl_or_b32 v198, v199, 8, v198
	v_or3_b32 v196, v198, v196, v197
	v_mul_f32_e32 v197, 0xbfb8aa3b, v200
	v_exp_f32_e32 v197, v197
	v_pk_add_f32 v[198:199], v[58:59], v[138:139]
	v_lshl_add_u64 v[194:195], v[194:195], 0, v[152:153]
	v_add_f32_e32 v197, 1.0, v197
	v_rcp_f32_e32 v200, v197
	v_mul_f32_e32 v197, 0xbfb8aa3b, v201
	v_exp_f32_e32 v197, v197
	s_nop 0
	v_add_f32_e32 v197, 1.0, v197
	v_rcp_f32_e32 v201, v197
	v_mul_f32_e32 v197, 0xbfb8aa3b, v198
	v_exp_f32_e32 v197, v197
	v_pk_fma_f32 v[200:201], v[200:201], s[4:5], 0.5 op_sel_hi:[1,0,0]
	v_add_f32_e32 v197, 1.0, v197
	v_rcp_f32_e32 v198, v197
	v_mul_f32_e32 v197, 0xbfb8aa3b, v199
	v_exp_f32_e32 v197, v197
	s_nop 0
	v_add_f32_e32 v197, 1.0, v197
	v_rcp_f32_e32 v199, v197
	v_cvt_u32_f32_e32 v197, v200
	v_cvt_u32_f32_e32 v200, v201
	v_pk_fma_f32 v[198:199], v[198:199], s[4:5], 0.5 op_sel_hi:[1,0,0]
	s_nop 0
	v_cvt_u32_f32_sdwa v198, v198 dst_sel:WORD_1 dst_unused:UNUSED_PAD src0_sel:DWORD
	v_cvt_u32_f32_sdwa v199, v199 dst_sel:BYTE_3 dst_unused:UNUSED_PAD src0_sel:DWORD
	v_lshl_or_b32 v197, v200, 8, v197
	v_pk_add_f32 v[200:201], v[48:49], v[128:129]
	v_or3_b32 v197, v197, v198, v199
	v_pk_add_f32 v[198:199], v[52:53], v[132:133]
	global_store_dwordx2 v[194:195], v[196:197], off
	v_pk_add_f32 v[196:197], v[54:55], v[134:135]
	v_mul_f32_e32 v198, 0xbfb8aa3b, v198
	v_mul_f32_e32 v199, 0xbfb8aa3b, v199
	v_exp_f32_e32 v198, v198
	v_exp_f32_e32 v199, v199
	v_mul_f32_e32 v196, 0xbfb8aa3b, v196
	v_mul_f32_e32 v197, 0xbfb8aa3b, v197
	v_exp_f32_e32 v196, v196
	v_exp_f32_e32 v197, v197
	v_add_f32_e32 v198, 1.0, v198
	v_add_f32_e32 v199, 1.0, v199
	v_rcp_f32_e32 v198, v198
	v_rcp_f32_e32 v199, v199
	v_add_f32_e32 v196, 1.0, v196
	v_add_f32_e32 v197, 1.0, v197
	v_rcp_f32_e32 v196, v196
	v_rcp_f32_e32 v197, v197
	v_pk_fma_f32 v[198:199], v[198:199], s[4:5], 0.5 op_sel_hi:[1,0,0]
	v_pk_fma_f32 v[196:197], v[196:197], s[4:5], 0.5 op_sel_hi:[1,0,0]
	v_cvt_u32_f32_e32 v198, v198
	v_cvt_u32_f32_e32 v199, v199
	v_cvt_u32_f32_sdwa v196, v196 dst_sel:WORD_1 dst_unused:UNUSED_PAD src0_sel:DWORD
	v_cvt_u32_f32_sdwa v197, v197 dst_sel:BYTE_3 dst_unused:UNUSED_PAD src0_sel:DWORD
	v_lshl_or_b32 v198, v199, 8, v198
	v_or3_b32 v196, v198, v196, v197
	v_mul_f32_e32 v197, 0xbfb8aa3b, v200
	v_exp_f32_e32 v197, v197
	v_pk_add_f32 v[198:199], v[50:51], v[130:131]
	v_add_f32_e32 v197, 1.0, v197
	v_rcp_f32_e32 v200, v197
	v_mul_f32_e32 v197, 0xbfb8aa3b, v201
	v_exp_f32_e32 v197, v197
	s_nop 0
	v_add_f32_e32 v197, 1.0, v197
	v_rcp_f32_e32 v201, v197
	v_mul_f32_e32 v197, 0xbfb8aa3b, v198
	v_exp_f32_e32 v197, v197
	v_pk_fma_f32 v[200:201], v[200:201], s[4:5], 0.5 op_sel_hi:[1,0,0]
	v_add_f32_e32 v197, 1.0, v197
	v_rcp_f32_e32 v198, v197
	v_mul_f32_e32 v197, 0xbfb8aa3b, v199
	v_exp_f32_e32 v197, v197
	s_nop 0
	v_add_f32_e32 v197, 1.0, v197
	v_rcp_f32_e32 v199, v197
	v_cvt_u32_f32_e32 v197, v200
	v_cvt_u32_f32_e32 v200, v201
	v_pk_fma_f32 v[198:199], v[198:199], s[4:5], 0.5 op_sel_hi:[1,0,0]
	s_nop 0
	v_cvt_u32_f32_sdwa v198, v198 dst_sel:WORD_1 dst_unused:UNUSED_PAD src0_sel:DWORD
	v_cvt_u32_f32_sdwa v199, v199 dst_sel:BYTE_3 dst_unused:UNUSED_PAD src0_sel:DWORD
	v_lshl_or_b32 v197, v200, 8, v197
	v_pk_add_f32 v[200:201], v[40:41], v[136:137]
	v_or3_b32 v197, v197, v198, v199
	v_pk_add_f32 v[198:199], v[44:45], v[140:141]
	global_store_dwordx2 v[194:195], v[196:197], off offset:128
	v_pk_add_f32 v[196:197], v[46:47], v[142:143]
	v_mul_f32_e32 v198, 0xbfb8aa3b, v198
	v_mul_f32_e32 v199, 0xbfb8aa3b, v199
	v_exp_f32_e32 v198, v198
	v_exp_f32_e32 v199, v199
	v_mul_f32_e32 v196, 0xbfb8aa3b, v196
	v_mul_f32_e32 v197, 0xbfb8aa3b, v197
	v_exp_f32_e32 v196, v196
	v_exp_f32_e32 v197, v197
	v_add_f32_e32 v198, 1.0, v198
	v_add_f32_e32 v199, 1.0, v199
	v_rcp_f32_e32 v198, v198
	v_rcp_f32_e32 v199, v199
	v_add_f32_e32 v196, 1.0, v196
	v_add_f32_e32 v197, 1.0, v197
	v_rcp_f32_e32 v196, v196
	v_rcp_f32_e32 v197, v197
	v_pk_fma_f32 v[198:199], v[198:199], s[4:5], 0.5 op_sel_hi:[1,0,0]
	v_add_u32_e32 v194, 0x90, v190
	v_cvt_u32_f32_e32 v198, v198
	v_pk_fma_f32 v[196:197], v[196:197], s[4:5], 0.5 op_sel_hi:[1,0,0]
	v_cvt_u32_f32_e32 v199, v199
	v_cvt_u32_f32_sdwa v196, v196 dst_sel:WORD_1 dst_unused:UNUSED_PAD src0_sel:DWORD
	v_cvt_u32_f32_sdwa v197, v197 dst_sel:BYTE_3 dst_unused:UNUSED_PAD src0_sel:DWORD
	v_mad_i64_i32 v[194:195], s[0:1], v194, s3, v[192:193]
	v_lshl_or_b32 v198, v199, 8, v198
	v_or3_b32 v196, v198, v196, v197
	v_mul_f32_e32 v197, 0xbfb8aa3b, v200
	v_exp_f32_e32 v197, v197
	v_pk_add_f32 v[198:199], v[42:43], v[138:139]
	v_lshl_add_u64 v[194:195], v[194:195], 0, v[152:153]
	v_add_f32_e32 v197, 1.0, v197
	v_rcp_f32_e32 v200, v197
	v_mul_f32_e32 v197, 0xbfb8aa3b, v201
	v_exp_f32_e32 v197, v197
	s_nop 0
	v_add_f32_e32 v197, 1.0, v197
	v_rcp_f32_e32 v201, v197
	v_mul_f32_e32 v197, 0xbfb8aa3b, v198
	v_exp_f32_e32 v197, v197
	v_pk_fma_f32 v[200:201], v[200:201], s[4:5], 0.5 op_sel_hi:[1,0,0]
	v_add_f32_e32 v197, 1.0, v197
	v_rcp_f32_e32 v198, v197
	v_mul_f32_e32 v197, 0xbfb8aa3b, v199
	v_exp_f32_e32 v197, v197
	s_nop 0
	v_add_f32_e32 v197, 1.0, v197
	v_rcp_f32_e32 v199, v197
	v_cvt_u32_f32_e32 v197, v200
	v_cvt_u32_f32_e32 v200, v201
	v_pk_fma_f32 v[198:199], v[198:199], s[4:5], 0.5 op_sel_hi:[1,0,0]
	s_nop 0
	v_cvt_u32_f32_sdwa v198, v198 dst_sel:WORD_1 dst_unused:UNUSED_PAD src0_sel:DWORD
	v_cvt_u32_f32_sdwa v199, v199 dst_sel:BYTE_3 dst_unused:UNUSED_PAD src0_sel:DWORD
	v_lshl_or_b32 v197, v200, 8, v197
	v_pk_add_f32 v[200:201], v[32:33], v[128:129]
	v_or3_b32 v197, v197, v198, v199
	v_pk_add_f32 v[198:199], v[36:37], v[132:133]
	global_store_dwordx2 v[194:195], v[196:197], off
	v_pk_add_f32 v[196:197], v[38:39], v[134:135]
	v_mul_f32_e32 v198, 0xbfb8aa3b, v198
	v_mul_f32_e32 v199, 0xbfb8aa3b, v199
	v_exp_f32_e32 v198, v198
	v_exp_f32_e32 v199, v199
	v_mul_f32_e32 v196, 0xbfb8aa3b, v196
	v_mul_f32_e32 v197, 0xbfb8aa3b, v197
	v_exp_f32_e32 v196, v196
	v_exp_f32_e32 v197, v197
	v_add_f32_e32 v198, 1.0, v198
	v_add_f32_e32 v199, 1.0, v199
	v_rcp_f32_e32 v198, v198
	v_rcp_f32_e32 v199, v199
	v_add_f32_e32 v196, 1.0, v196
	v_add_f32_e32 v197, 1.0, v197
	v_rcp_f32_e32 v196, v196
	v_rcp_f32_e32 v197, v197
	v_pk_fma_f32 v[198:199], v[198:199], s[4:5], 0.5 op_sel_hi:[1,0,0]
	v_pk_fma_f32 v[196:197], v[196:197], s[4:5], 0.5 op_sel_hi:[1,0,0]
	v_cvt_u32_f32_e32 v198, v198
	v_cvt_u32_f32_e32 v199, v199
	v_cvt_u32_f32_sdwa v196, v196 dst_sel:WORD_1 dst_unused:UNUSED_PAD src0_sel:DWORD
	v_cvt_u32_f32_sdwa v197, v197 dst_sel:BYTE_3 dst_unused:UNUSED_PAD src0_sel:DWORD
	v_lshl_or_b32 v198, v199, 8, v198
	v_or3_b32 v196, v198, v196, v197
	v_mul_f32_e32 v197, 0xbfb8aa3b, v200
	v_exp_f32_e32 v197, v197
	v_pk_add_f32 v[198:199], v[34:35], v[130:131]
	v_add_f32_e32 v197, 1.0, v197
	v_rcp_f32_e32 v200, v197
	v_mul_f32_e32 v197, 0xbfb8aa3b, v201
	v_exp_f32_e32 v197, v197
	s_nop 0
	v_add_f32_e32 v197, 1.0, v197
	v_rcp_f32_e32 v201, v197
	v_mul_f32_e32 v197, 0xbfb8aa3b, v198
	v_exp_f32_e32 v197, v197
	v_pk_fma_f32 v[200:201], v[200:201], s[4:5], 0.5 op_sel_hi:[1,0,0]
	v_add_f32_e32 v197, 1.0, v197
	v_rcp_f32_e32 v198, v197
	v_mul_f32_e32 v197, 0xbfb8aa3b, v199
	v_exp_f32_e32 v197, v197
	s_nop 0
	v_add_f32_e32 v197, 1.0, v197
	v_rcp_f32_e32 v199, v197
	v_cvt_u32_f32_e32 v197, v200
	v_cvt_u32_f32_e32 v200, v201
	v_pk_fma_f32 v[198:199], v[198:199], s[4:5], 0.5 op_sel_hi:[1,0,0]
	s_nop 0
	v_cvt_u32_f32_sdwa v198, v198 dst_sel:WORD_1 dst_unused:UNUSED_PAD src0_sel:DWORD
	v_cvt_u32_f32_sdwa v199, v199 dst_sel:BYTE_3 dst_unused:UNUSED_PAD src0_sel:DWORD
	v_lshl_or_b32 v197, v200, 8, v197
	v_pk_add_f32 v[200:201], v[24:25], v[136:137]
	v_pk_add_f32 v[136:137], v[8:9], v[136:137]
	v_or3_b32 v197, v197, v198, v199
	v_pk_add_f32 v[198:199], v[28:29], v[140:141]
	global_store_dwordx2 v[194:195], v[196:197], off offset:128
	v_pk_add_f32 v[196:197], v[30:31], v[142:143]
	v_mul_f32_e32 v198, 0xbfb8aa3b, v198
	v_mul_f32_e32 v199, 0xbfb8aa3b, v199
	v_exp_f32_e32 v198, v198
	v_exp_f32_e32 v199, v199
	v_mul_f32_e32 v196, 0xbfb8aa3b, v196
	v_mul_f32_e32 v197, 0xbfb8aa3b, v197
	v_exp_f32_e32 v196, v196
	v_exp_f32_e32 v197, v197
	v_add_f32_e32 v198, 1.0, v198
	v_add_f32_e32 v199, 1.0, v199
	v_rcp_f32_e32 v198, v198
	v_rcp_f32_e32 v199, v199
	v_add_f32_e32 v196, 1.0, v196
	v_add_f32_e32 v197, 1.0, v197
	v_rcp_f32_e32 v196, v196
	v_rcp_f32_e32 v197, v197
	v_pk_fma_f32 v[198:199], v[198:199], s[4:5], 0.5 op_sel_hi:[1,0,0]
	v_add_u32_e32 v194, 0xa0, v190
	v_cvt_u32_f32_e32 v198, v198
	v_pk_fma_f32 v[196:197], v[196:197], s[4:5], 0.5 op_sel_hi:[1,0,0]
	v_cvt_u32_f32_e32 v199, v199
	v_cvt_u32_f32_sdwa v196, v196 dst_sel:WORD_1 dst_unused:UNUSED_PAD src0_sel:DWORD
	v_cvt_u32_f32_sdwa v197, v197 dst_sel:BYTE_3 dst_unused:UNUSED_PAD src0_sel:DWORD
	v_mad_i64_i32 v[194:195], s[0:1], v194, s3, v[192:193]
	v_lshl_or_b32 v198, v199, 8, v198
	v_or3_b32 v196, v198, v196, v197
	v_mul_f32_e32 v197, 0xbfb8aa3b, v200
	v_exp_f32_e32 v197, v197
	v_pk_add_f32 v[198:199], v[26:27], v[138:139]
	v_lshl_add_u64 v[194:195], v[194:195], 0, v[152:153]
	v_pk_add_f32 v[140:141], v[12:13], v[140:141]
	v_add_f32_e32 v197, 1.0, v197
	v_rcp_f32_e32 v200, v197
	v_mul_f32_e32 v197, 0xbfb8aa3b, v201
	v_exp_f32_e32 v197, v197
	v_mul_f32_e32 v140, 0xbfb8aa3b, v140
	v_mul_f32_e32 v141, 0xbfb8aa3b, v141
	v_mul_f32_e32 v136, 0xbfb8aa3b, v136
	v_add_f32_e32 v197, 1.0, v197
	v_rcp_f32_e32 v201, v197
	v_mul_f32_e32 v197, 0xbfb8aa3b, v198
	v_exp_f32_e32 v197, v197
	v_mul_f32_e32 v137, 0xbfb8aa3b, v137
	v_pk_fma_f32 v[200:201], v[200:201], s[4:5], 0.5 op_sel_hi:[1,0,0]
	v_exp_f32_e32 v140, v140
	v_add_f32_e32 v197, 1.0, v197
	v_rcp_f32_e32 v198, v197
	v_mul_f32_e32 v197, 0xbfb8aa3b, v199
	v_exp_f32_e32 v197, v197
	v_exp_f32_e32 v141, v141
	v_exp_f32_e32 v136, v136
	v_exp_f32_e32 v137, v137
	v_add_f32_e32 v197, 1.0, v197
	v_rcp_f32_e32 v199, v197
	v_cvt_u32_f32_e32 v197, v200
	v_cvt_u32_f32_e32 v200, v201
	v_pk_add_f32 v[142:143], v[14:15], v[142:143]
	v_pk_fma_f32 v[198:199], v[198:199], s[4:5], 0.5 op_sel_hi:[1,0,0]
	v_pk_add_f32 v[138:139], v[10:11], v[138:139]
	v_cvt_u32_f32_sdwa v198, v198 dst_sel:WORD_1 dst_unused:UNUSED_PAD src0_sel:DWORD
	v_cvt_u32_f32_sdwa v199, v199 dst_sel:BYTE_3 dst_unused:UNUSED_PAD src0_sel:DWORD
	v_lshl_or_b32 v197, v200, 8, v197
	v_pk_add_f32 v[200:201], v[16:17], v[128:129]
	v_pk_add_f32 v[128:129], v[0:1], v[128:129]
	v_or3_b32 v197, v197, v198, v199
	v_pk_add_f32 v[198:199], v[20:21], v[132:133]
	global_store_dwordx2 v[194:195], v[196:197], off
	v_pk_add_f32 v[196:197], v[22:23], v[134:135]
	v_mul_f32_e32 v198, 0xbfb8aa3b, v198
	v_mul_f32_e32 v199, 0xbfb8aa3b, v199
	v_exp_f32_e32 v198, v198
	v_exp_f32_e32 v199, v199
	v_mul_f32_e32 v196, 0xbfb8aa3b, v196
	v_mul_f32_e32 v197, 0xbfb8aa3b, v197
	v_exp_f32_e32 v196, v196
	v_exp_f32_e32 v197, v197
	v_add_f32_e32 v198, 1.0, v198
	v_add_f32_e32 v199, 1.0, v199
	v_rcp_f32_e32 v198, v198
	v_rcp_f32_e32 v199, v199
	v_add_f32_e32 v196, 1.0, v196
	v_add_f32_e32 v197, 1.0, v197
	v_rcp_f32_e32 v196, v196
	v_rcp_f32_e32 v197, v197
	v_pk_fma_f32 v[198:199], v[198:199], s[4:5], 0.5 op_sel_hi:[1,0,0]
	v_pk_add_f32 v[132:133], v[4:5], v[132:133]
	v_cvt_u32_f32_e32 v198, v198
	v_pk_fma_f32 v[196:197], v[196:197], s[4:5], 0.5 op_sel_hi:[1,0,0]
	v_cvt_u32_f32_e32 v199, v199
	v_cvt_u32_f32_sdwa v196, v196 dst_sel:WORD_1 dst_unused:UNUSED_PAD src0_sel:DWORD
	v_cvt_u32_f32_sdwa v197, v197 dst_sel:BYTE_3 dst_unused:UNUSED_PAD src0_sel:DWORD
	v_mul_f32_e32 v132, 0xbfb8aa3b, v132
	v_lshl_or_b32 v198, v199, 8, v198
	v_mul_f32_e32 v133, 0xbfb8aa3b, v133
	v_or3_b32 v196, v198, v196, v197
	v_mul_f32_e32 v197, 0xbfb8aa3b, v200
	v_exp_f32_e32 v197, v197
	v_pk_add_f32 v[198:199], v[18:19], v[130:131]
	v_mul_f32_e32 v128, 0xbfb8aa3b, v128
	v_mul_f32_e32 v129, 0xbfb8aa3b, v129
	v_add_f32_e32 v197, 1.0, v197
	v_rcp_f32_e32 v200, v197
	v_mul_f32_e32 v197, 0xbfb8aa3b, v201
	v_exp_f32_e32 v197, v197
	v_exp_f32_e32 v132, v132
	v_exp_f32_e32 v133, v133
	v_exp_f32_e32 v128, v128
	v_add_f32_e32 v197, 1.0, v197
	v_rcp_f32_e32 v201, v197
	v_mul_f32_e32 v197, 0xbfb8aa3b, v198
	v_exp_f32_e32 v197, v197
	v_exp_f32_e32 v129, v129
	v_pk_add_f32 v[134:135], v[6:7], v[134:135]
	v_pk_add_f32 v[130:131], v[2:3], v[130:131]
	v_add_f32_e32 v197, 1.0, v197
	v_rcp_f32_e32 v198, v197
	v_mul_f32_e32 v197, 0xbfb8aa3b, v199
	v_exp_f32_e32 v197, v197
	v_mul_f32_e32 v142, 0xbfb8aa3b, v142
	v_mul_f32_e32 v143, 0xbfb8aa3b, v143
	v_mul_f32_e32 v138, 0xbfb8aa3b, v138
	v_mul_f32_e32 v139, 0xbfb8aa3b, v139
	v_mul_f32_e32 v134, 0xbfb8aa3b, v134
	v_mul_f32_e32 v135, 0xbfb8aa3b, v135
	v_mul_f32_e32 v130, 0xbfb8aa3b, v130
	v_mul_f32_e32 v131, 0xbfb8aa3b, v131
	v_add_f32_e32 v140, 1.0, v140
	v_add_f32_e32 v141, 1.0, v141
	v_exp_f32_e32 v142, v142
	v_exp_f32_e32 v143, v143
	v_add_f32_e32 v136, 1.0, v136
	v_add_f32_e32 v137, 1.0, v137
	v_exp_f32_e32 v138, v138
	v_exp_f32_e32 v139, v139
	v_add_f32_e32 v132, 1.0, v132
	v_add_f32_e32 v133, 1.0, v133
	v_exp_f32_e32 v134, v134
	v_exp_f32_e32 v135, v135
	v_add_f32_e32 v128, 1.0, v128
	v_add_f32_e32 v129, 1.0, v129
	v_exp_f32_e32 v130, v130
	v_exp_f32_e32 v131, v131
	v_add_f32_e32 v197, 1.0, v197
	v_rcp_f32_e32 v140, v140
	v_rcp_f32_e32 v141, v141
	v_rcp_f32_e32 v136, v136
	v_rcp_f32_e32 v137, v137
	v_rcp_f32_e32 v132, v132
	v_rcp_f32_e32 v133, v133
	v_rcp_f32_e32 v128, v128
	v_rcp_f32_e32 v129, v129
	v_rcp_f32_e32 v199, v197
	v_add_f32_e32 v142, 1.0, v142
	v_add_f32_e32 v143, 1.0, v143
	v_add_f32_e32 v138, 1.0, v138
	v_add_f32_e32 v139, 1.0, v139
	v_add_f32_e32 v134, 1.0, v134
	v_add_f32_e32 v135, 1.0, v135
	v_add_f32_e32 v130, 1.0, v130
	v_add_f32_e32 v131, 1.0, v131
	v_pk_fma_f32 v[200:201], v[200:201], s[4:5], 0.5 op_sel_hi:[1,0,0]
	v_rcp_f32_e32 v142, v142
	v_rcp_f32_e32 v143, v143
	v_pk_fma_f32 v[140:141], v[140:141], s[4:5], 0.5 op_sel_hi:[1,0,0]
	v_rcp_f32_e32 v138, v138
	v_rcp_f32_e32 v139, v139
	v_pk_fma_f32 v[136:137], v[136:137], s[4:5], 0.5 op_sel_hi:[1,0,0]
	v_rcp_f32_e32 v134, v134
	v_rcp_f32_e32 v135, v135
	v_pk_fma_f32 v[132:133], v[132:133], s[4:5], 0.5 op_sel_hi:[1,0,0]
	v_rcp_f32_e32 v130, v130
	v_rcp_f32_e32 v131, v131
	v_pk_fma_f32 v[128:129], v[128:129], s[4:5], 0.5 op_sel_hi:[1,0,0]
	v_pk_fma_f32 v[198:199], v[198:199], s[4:5], 0.5 op_sel_hi:[1,0,0]
	v_cvt_u32_f32_e32 v197, v200
	v_cvt_u32_f32_e32 v200, v201
	v_cvt_u32_f32_e32 v140, v140
	v_cvt_u32_f32_e32 v141, v141
	v_cvt_u32_f32_e32 v136, v136
	v_cvt_u32_f32_e32 v137, v137
	v_cvt_u32_f32_e32 v132, v132
	v_cvt_u32_f32_e32 v133, v133
	v_cvt_u32_f32_e32 v128, v128
	v_cvt_u32_f32_e32 v129, v129
	v_cvt_u32_f32_sdwa v198, v198 dst_sel:WORD_1 dst_unused:UNUSED_PAD src0_sel:DWORD
	v_cvt_u32_f32_sdwa v199, v199 dst_sel:BYTE_3 dst_unused:UNUSED_PAD src0_sel:DWORD
	v_pk_fma_f32 v[142:143], v[142:143], s[4:5], 0.5 op_sel_hi:[1,0,0]
	v_pk_fma_f32 v[138:139], v[138:139], s[4:5], 0.5 op_sel_hi:[1,0,0]
	v_pk_fma_f32 v[134:135], v[134:135], s[4:5], 0.5 op_sel_hi:[1,0,0]
	v_pk_fma_f32 v[130:131], v[130:131], s[4:5], 0.5 op_sel_hi:[1,0,0]
	v_lshl_or_b32 v197, v200, 8, v197
	v_lshl_or_b32 v140, v141, 8, v140
	v_cvt_u32_f32_sdwa v141, v142 dst_sel:WORD_1 dst_unused:UNUSED_PAD src0_sel:DWORD
	v_cvt_u32_f32_sdwa v142, v143 dst_sel:BYTE_3 dst_unused:UNUSED_PAD src0_sel:DWORD
	v_lshl_or_b32 v136, v137, 8, v136
	v_cvt_u32_f32_sdwa v137, v138 dst_sel:WORD_1 dst_unused:UNUSED_PAD src0_sel:DWORD
	v_cvt_u32_f32_sdwa v138, v139 dst_sel:BYTE_3 dst_unused:UNUSED_PAD src0_sel:DWORD
	v_lshl_or_b32 v132, v133, 8, v132
	v_cvt_u32_f32_sdwa v133, v134 dst_sel:WORD_1 dst_unused:UNUSED_PAD src0_sel:DWORD
	v_cvt_u32_f32_sdwa v134, v135 dst_sel:BYTE_3 dst_unused:UNUSED_PAD src0_sel:DWORD
	v_lshl_or_b32 v128, v129, 8, v128
	v_cvt_u32_f32_sdwa v129, v130 dst_sel:WORD_1 dst_unused:UNUSED_PAD src0_sel:DWORD
	v_cvt_u32_f32_sdwa v130, v131 dst_sel:BYTE_3 dst_unused:UNUSED_PAD src0_sel:DWORD
	v_or3_b32 v197, v197, v198, v199
	global_store_dwordx2 v[194:195], v[196:197], off offset:128
	v_add_u32_e32 v194, 0xb0, v190
	v_mad_i64_i32 v[192:193], s[0:1], v194, s3, v[192:193]
	v_lshl_add_u64 v[192:193], v[192:193], 0, v[152:153]
	v_or3_b32 v140, v140, v141, v142
	v_or3_b32 v141, v136, v137, v138
	v_or3_b32 v132, v132, v133, v134
	v_or3_b32 v133, v128, v129, v130
	global_store_dwordx2 v[192:193], v[140:141], off
	global_store_dwordx2 v[192:193], v[132:133], off offset:128
	s_mov_b64 s[0:1], 0

.LBB0_433:
	ds_read_b128 v[70:73], v19
	ds_read_b128 v[74:77], v19 offset:64
	v_add_u32_e32 v20, 0x900, v19
	v_cmp_gt_u32_e32 vcc, 7, v34
	s_and_b64 vcc, s[4:5], vcc
	s_waitcnt lgkmcnt(1)
	v_mfma_f32_16x16x32_bf16 v[70:73], v[70:73], v[8:11], 0
	s_waitcnt lgkmcnt(0)
	v_mfma_f32_16x16x32_bf16 v[70:73], v[74:77], v[12:15], v[70:73]
	ds_read_b128 v[74:77], v19 offset:2304
	ds_read_b128 v[78:81], v19 offset:2368
	s_waitcnt lgkmcnt(1)
	v_mfma_f32_16x16x32_bf16 v[74:77], v[74:77], v[8:11], 0
	s_waitcnt lgkmcnt(0)
	v_mfma_f32_16x16x32_bf16 v[74:77], v[78:81], v[12:15], v[74:77]
	ds_read_b128 v[78:81], v19 offset:4608
	ds_read_b128 v[82:85], v19 offset:4672
	s_waitcnt lgkmcnt(1)
	v_mfma_f32_16x16x32_bf16 v[78:81], v[78:81], v[8:11], 0
	s_waitcnt lgkmcnt(0)
	v_mfma_f32_16x16x32_bf16 v[78:81], v[82:85], v[12:15], v[78:81]
	ds_read_b128 v[82:85], v19 offset:6912
	ds_read_b128 v[86:89], v19 offset:6976
	s_waitcnt lgkmcnt(1)
	v_mfma_f32_16x16x32_bf16 v[82:85], v[82:85], v[8:11], 0
	s_waitcnt lgkmcnt(0)
	v_mfma_f32_16x16x32_bf16 v[82:85], v[86:89], v[12:15], v[82:85]
	ds_read_b128 v[86:89], v19 offset:9216
	ds_read_b128 v[90:93], v19 offset:9280
	s_waitcnt lgkmcnt(1)
	v_mfma_f32_16x16x32_bf16 v[86:89], v[86:89], v[8:11], 0
	s_waitcnt lgkmcnt(0)
	v_mfma_f32_16x16x32_bf16 v[86:89], v[90:93], v[12:15], v[86:89]
	ds_read_b128 v[90:93], v19 offset:11520
	ds_read_b128 v[94:97], v19 offset:11584
	s_waitcnt lgkmcnt(1)
	v_mfma_f32_16x16x32_bf16 v[90:93], v[90:93], v[8:11], 0
	s_waitcnt lgkmcnt(0)
	v_mfma_f32_16x16x32_bf16 v[90:93], v[94:97], v[12:15], v[90:93]
	ds_read_b128 v[94:97], v19 offset:13824
	ds_read_b128 v[98:101], v19 offset:13888
	s_waitcnt lgkmcnt(1)
	v_mfma_f32_16x16x32_bf16 v[94:97], v[94:97], v[8:11], 0
	s_waitcnt lgkmcnt(0)
	v_mfma_f32_16x16x32_bf16 v[94:97], v[98:101], v[12:15], v[94:97]
	ds_read_b128 v[98:101], v19 offset:16128
	ds_read_b128 v[102:105], v19 offset:16192
	s_waitcnt lgkmcnt(1)
	v_mfma_f32_16x16x32_bf16 v[98:101], v[98:101], v[8:11], 0
	s_waitcnt lgkmcnt(0)
	v_mfma_f32_16x16x32_bf16 v[98:101], v[102:105], v[12:15], v[98:101]
	ds_read_b128 v[102:105], v19 offset:18432
	ds_read_b128 v[106:109], v19 offset:18496
	v_add_f32_e32 v19, v40, v73
	v_cndmask_b32_e64 v19, v33, v19, s[12:13]
	s_waitcnt lgkmcnt(1)
	v_mfma_f32_16x16x32_bf16 v[8:11], v[102:105], v[8:11], 0
	v_cndmask_b32_e64 v19, v19, v33, s[4:5]
	v_add_f32_e32 v73, v44, v77
	v_cndmask_b32_e32 v73, v73, v33, vcc
	s_waitcnt lgkmcnt(0)
	v_mfma_f32_16x16x32_bf16 v[8:11], v[106:109], v[12:15], v[8:11]
	v_add_f32_e32 v12, v37, v70
	v_add_f32_e32 v13, v38, v71
	v_cndmask_b32_e64 v12, v33, v12, s[6:7]
	v_cndmask_b32_e64 v13, v33, v13, s[8:9]
	v_add_f32_e32 v15, v39, v72
	v_cndmask_b32_e64 v12, v12, v33, s[4:5]
	v_cndmask_b32_e64 v13, v13, v33, s[4:5]
	v_cndmask_b32_e64 v15, v33, v15, s[10:11]
	s_waitcnt vmcnt(2)
	v_max3_f32 v14, v24, v12, v13
	v_cndmask_b32_e64 v15, v15, v33, s[4:5]
	v_add_f32_e32 v70, v41, v74
	v_add_f32_e32 v71, v42, v75
	v_add_f32_e32 v72, v43, v76
	v_max3_f32 v14, v14, v15, v19
	v_cndmask_b32_e32 v70, v70, v33, vcc
	v_cndmask_b32_e32 v71, v71, v33, vcc
	v_cndmask_b32_e32 v72, v72, v33, vcc
	v_cmp_gt_u32_e32 vcc, 6, v34
	v_max3_f32 v14, v14, v70, v71
	s_and_b64 vcc, s[4:5], vcc
	v_add_f32_e32 v74, v45, v78
	v_add_f32_e32 v75, v46, v79
	v_add_f32_e32 v76, v47, v80
	v_add_f32_e32 v77, v48, v81
	v_max3_f32 v14, v14, v72, v73
	v_cndmask_b32_e32 v74, v74, v33, vcc
	v_cndmask_b32_e32 v75, v75, v33, vcc
	v_cndmask_b32_e32 v76, v76, v33, vcc
	v_cndmask_b32_e32 v77, v77, v33, vcc
	v_cmp_gt_u32_e32 vcc, 5, v34
	v_max3_f32 v14, v14, v74, v75
	s_and_b64 vcc, s[4:5], vcc
	v_add_f32_e32 v78, v49, v82
	v_add_f32_e32 v79, v50, v83
	v_add_f32_e32 v80, v51, v84
	v_add_f32_e32 v81, v52, v85
	v_max3_f32 v14, v14, v76, v77
	v_cndmask_b32_e32 v78, v78, v33, vcc
	v_cndmask_b32_e32 v79, v79, v33, vcc
	v_cndmask_b32_e32 v80, v80, v33, vcc
	v_cndmask_b32_e32 v81, v81, v33, vcc
	v_cmp_gt_u32_e32 vcc, 4, v34
	v_max3_f32 v14, v14, v78, v79
	s_and_b64 vcc, s[4:5], vcc
	v_add_f32_e32 v82, v53, v86
	v_add_f32_e32 v83, v54, v87
	v_add_f32_e32 v84, v55, v88
	v_add_f32_e32 v85, v56, v89
	v_max3_f32 v14, v14, v80, v81
	v_cndmask_b32_e32 v82, v82, v33, vcc
	v_cndmask_b32_e32 v83, v83, v33, vcc
	v_cndmask_b32_e32 v84, v84, v33, vcc
	v_cndmask_b32_e32 v85, v85, v33, vcc
	v_cmp_gt_u32_e32 vcc, 3, v34
	v_max3_f32 v14, v14, v82, v83
	s_and_b64 vcc, s[4:5], vcc
	v_add_f32_e32 v86, v57, v90
	v_add_f32_e32 v87, v58, v91
	v_add_f32_e32 v88, v59, v92
	v_add_f32_e32 v89, v60, v93
	v_max3_f32 v14, v14, v84, v85
	v_cndmask_b32_e32 v86, v86, v33, vcc
	v_cndmask_b32_e32 v87, v87, v33, vcc
	v_cndmask_b32_e32 v88, v88, v33, vcc
	v_cndmask_b32_e32 v89, v89, v33, vcc
	v_cmp_gt_u32_e32 vcc, 2, v34
	v_max3_f32 v14, v14, v86, v87
	s_and_b64 vcc, s[4:5], vcc
	v_add_f32_e32 v90, v61, v94
	v_add_f32_e32 v91, v62, v95
	v_max3_f32 v14, v14, v88, v89
	v_cndmask_b32_e32 v90, v90, v33, vcc
	v_cndmask_b32_e32 v91, v91, v33, vcc
	v_add_f32_e32 v92, v63, v96
	v_add_f32_e32 v93, v64, v97
	v_or_b32_e32 v94, s30, v34
	v_max3_f32 v14, v14, v90, v91
	v_cndmask_b32_e32 v92, v92, v33, vcc
	v_cndmask_b32_e32 v93, v93, v33, vcc
	v_cmp_eq_u32_e32 vcc, 0, v94
	v_add_f32_e32 v94, v65, v98
	v_add_f32_e32 v95, v66, v99
	v_max3_f32 v14, v14, v92, v93
	v_cndmask_b32_e32 v94, v94, v33, vcc
	v_cndmask_b32_e32 v95, v95, v33, vcc
	v_add_f32_e32 v96, v67, v100
	v_add_f32_e32 v97, v68, v101
	v_max3_f32 v14, v14, v94, v95
	v_cndmask_b32_e32 v96, v96, v33, vcc
	v_cndmask_b32_e32 v97, v97, v33, vcc
	v_add_f32_e32 v8, v25, v8
	v_add_f32_e32 v9, v26, v9
	v_add_f32_e32 v10, v27, v10
	v_max3_f32 v14, v14, v96, v97
	v_cndmask_b32_e64 v8, v8, v33, s[6:7]
	v_cndmask_b32_e64 v9, v9, v33, s[8:9]
	v_cndmask_b32_e64 v98, v10, v33, s[10:11]
	v_add_f32_e32 v10, v28, v11
	v_max3_f32 v14, v14, v8, v9
	v_cndmask_b32_e64 v99, v10, v33, s[12:13]
	v_max3_f32 v10, v14, v98, v99
	ds_bpermute_b32 v11, v35, v10
	s_add_u32 s78, s78, 0x8000
	s_addc_u32 s79, s79, 0
	v_add_u32_e32 v34, 1, v34
	s_cmp_lg_u32 s78, 0x20000
	s_waitcnt lgkmcnt(0)
	v_max_f32_e32 v11, v11, v11
	v_max_f32_e32 v10, v10, v11
	ds_bpermute_b32 v11, v36, v10
	s_waitcnt lgkmcnt(0)
	v_max_f32_e32 v11, v11, v11
	v_max_f32_e32 v100, v10, v11
	v_sub_f32_e32 v11, v13, v100
	v_mul_f32_e32 v11, 0x3fb8aa3b, v11
	v_exp_f32_e32 v102, v11
	v_sub_f32_e32 v11, v15, v100
	v_mul_f32_e32 v11, 0x3fb8aa3b, v11
	v_exp_f32_e32 v103, v11
	v_sub_f32_e32 v11, v19, v100
	v_mul_f32_e32 v11, 0x3fb8aa3b, v11
	v_exp_f32_e32 v104, v11
	v_sub_f32_e32 v11, v70, v100
	v_mul_f32_e32 v11, 0x3fb8aa3b, v11
	v_exp_f32_e32 v105, v11
	v_sub_f32_e32 v11, v71, v100
	v_mul_f32_e32 v11, 0x3fb8aa3b, v11
	v_exp_f32_e32 v106, v11
	v_sub_f32_e32 v11, v72, v100
	v_mul_f32_e32 v11, 0x3fb8aa3b, v11
	v_exp_f32_e32 v107, v11
	v_sub_f32_e32 v11, v73, v100
	v_mul_f32_e32 v11, 0x3fb8aa3b, v11
	v_exp_f32_e32 v73, v11
	v_sub_f32_e32 v11, v74, v100
	v_mul_f32_e32 v11, 0x3fb8aa3b, v11
	v_exp_f32_e32 v108, v11
	v_sub_f32_e32 v11, v75, v100
	v_mul_f32_e32 v11, 0x3fb8aa3b, v11
	v_exp_f32_e32 v109, v11
	v_sub_f32_e32 v11, v76, v100
	v_mul_f32_e32 v11, 0x3fb8aa3b, v11
	v_exp_f32_e32 v110, v11
	v_sub_f32_e32 v11, v77, v100
	v_mul_f32_e32 v11, 0x3fb8aa3b, v11
	v_exp_f32_e32 v111, v11
	v_sub_f32_e32 v11, v78, v100
	v_mul_f32_e32 v11, 0x3fb8aa3b, v11
	v_exp_f32_e32 v112, v11
	v_sub_f32_e32 v11, v79, v100
	v_mul_f32_e32 v11, 0x3fb8aa3b, v11
	v_exp_f32_e32 v113, v11
	v_sub_f32_e32 v11, v80, v100
	v_mul_f32_e32 v11, 0x3fb8aa3b, v11
	v_exp_f32_e32 v114, v11
	v_sub_f32_e32 v11, v81, v100
	v_sub_f32_e32 v10, v12, v100
	v_mul_f32_e32 v11, 0x3fb8aa3b, v11
	v_mul_f32_e32 v10, 0x3fb8aa3b, v10
	v_exp_f32_e32 v115, v11
	v_sub_f32_e32 v11, v82, v100
	v_exp_f32_e32 v101, v10
	v_mul_f32_e32 v11, 0x3fb8aa3b, v11
	v_exp_f32_e32 v71, v11
	v_sub_f32_e32 v11, v83, v100
	v_mul_f32_e32 v11, 0x3fb8aa3b, v11
	v_exp_f32_e32 v116, v11
	v_sub_f32_e32 v11, v84, v100
	v_add_f32_e32 v10, 0, v101
	v_mul_f32_e32 v11, 0x3fb8aa3b, v11
	v_add_f32_e32 v10, v102, v10
	v_exp_f32_e32 v117, v11
	v_sub_f32_e32 v11, v85, v100
	v_add_f32_e32 v10, v103, v10
	v_mul_f32_e32 v11, 0x3fb8aa3b, v11
	v_add_f32_e32 v10, v104, v10
	v_exp_f32_e32 v118, v11
	v_sub_f32_e32 v11, v86, v100
	v_add_f32_e32 v10, v105, v10
	v_mul_f32_e32 v11, 0x3fb8aa3b, v11
	v_add_f32_e32 v10, v106, v10
	v_exp_f32_e32 v119, v11
	v_sub_f32_e32 v11, v87, v100
	v_add_f32_e32 v10, v107, v10
	v_mul_f32_e32 v11, 0x3fb8aa3b, v11
	v_add_f32_e32 v10, v73, v10
	v_exp_f32_e32 v120, v11
	v_sub_f32_e32 v11, v88, v100
	v_add_f32_e32 v10, v108, v10
	v_mul_f32_e32 v11, 0x3fb8aa3b, v11
	v_add_f32_e32 v10, v109, v10
	v_exp_f32_e32 v121, v11
	v_sub_f32_e32 v11, v89, v100
	v_add_f32_e32 v10, v110, v10
	v_mul_f32_e32 v11, 0x3fb8aa3b, v11
	v_add_f32_e32 v10, v111, v10
	v_exp_f32_e32 v122, v11
	v_sub_f32_e32 v11, v90, v100
	v_add_f32_e32 v10, v112, v10
	v_mul_f32_e32 v11, 0x3fb8aa3b, v11
	v_add_f32_e32 v10, v113, v10
	v_exp_f32_e32 v14, v11
	v_sub_f32_e32 v11, v91, v100
	v_add_f32_e32 v10, v114, v10
	v_mul_f32_e32 v11, 0x3fb8aa3b, v11
	v_add_f32_e32 v10, v115, v10
	v_exp_f32_e32 v15, v11
	v_sub_f32_e32 v11, v92, v100
	v_add_f32_e32 v10, v71, v10
	v_mul_f32_e32 v11, 0x3fb8aa3b, v11
	v_add_f32_e32 v10, v116, v10
	v_exp_f32_e32 v70, v11
	v_sub_f32_e32 v11, v93, v100
	v_add_f32_e32 v10, v117, v10
	v_mul_f32_e32 v11, 0x3fb8aa3b, v11
	v_add_f32_e32 v10, v118, v10
	v_exp_f32_e32 v72, v11
	v_sub_f32_e32 v11, v94, v100
	v_add_f32_e32 v10, v119, v10
	v_mul_f32_e32 v11, 0x3fb8aa3b, v11
	v_add_f32_e32 v10, v120, v10
	v_exp_f32_e32 v123, v11
	v_sub_f32_e32 v11, v95, v100
	v_add_f32_e32 v10, v121, v10
	v_mul_f32_e32 v11, 0x3fb8aa3b, v11
	v_add_f32_e32 v10, v122, v10
	v_exp_f32_e32 v124, v11
	v_sub_f32_e32 v11, v96, v100
	v_add_f32_e32 v10, v14, v10
	v_mul_f32_e32 v11, 0x3fb8aa3b, v11
	v_add_f32_e32 v10, v15, v10
	v_exp_f32_e32 v125, v11
	v_sub_f32_e32 v11, v97, v100
	v_add_f32_e32 v10, v70, v10
	v_mul_f32_e32 v11, 0x3fb8aa3b, v11
	v_add_f32_e32 v10, v72, v10
	v_exp_f32_e32 v126, v11
	v_add_f32_e32 v10, v123, v10
	v_add_f32_e32 v10, v124, v10
	v_sub_f32_e32 v8, v8, v100
	v_add_f32_e32 v10, v125, v10
	v_mul_f32_e32 v8, 0x3fb8aa3b, v8
	v_add_f32_e32 v11, v126, v10
	v_exp_f32_e32 v10, v8
	v_sub_f32_e32 v9, v9, v100
	v_mul_f32_e32 v9, 0x3fb8aa3b, v9
	s_nop 1
	v_cvt_pk_bf16_f32 v74, v101, v102
	v_add_f32_e32 v8, v10, v11
	v_exp_f32_e32 v11, v9
	v_sub_f32_e32 v9, v98, v100
	v_mul_f32_e32 v9, 0x3fb8aa3b, v9
	v_exp_f32_e32 v12, v9
	v_sub_f32_e32 v9, v99, v100
	v_mul_f32_e32 v9, 0x3fb8aa3b, v9
	v_exp_f32_e32 v13, v9
	v_add_f32_e32 v8, v11, v8
	v_add_f32_e32 v8, v12, v8
	v_add_u32_e32 v98, 0x2000, v69
	v_add_f32_e32 v8, v13, v8
	ds_bpermute_b32 v9, v35, v8
	v_add_u32_e32 v99, 0x4000, v69
	s_nop 1
	v_cvt_pk_bf16_f32 v75, v103, v104
	s_nop 1
	v_cvt_pk_bf16_f32 v76, v105, v106
	s_nop 1
	v_cvt_pk_bf16_f32 v77, v107, v73
	s_waitcnt lgkmcnt(0)
	v_add_f32_e32 v8, v8, v9
	ds_bpermute_b32 v9, v36, v8
	ds_read2_b64 v[78:81], v69 offset1:4
	ds_read2_b64 v[82:85], v98 offset0:32 offset1:36
	ds_read2_b64 v[86:89], v99 offset0:64 offset1:68
	s_waitcnt lgkmcnt(2)
	v_mfma_f32_16x16x32_bf16 v[78:81], v[78:81], v[74:77], 0
	v_add_f32_e32 v8, v8, v9
	v_sub_f32_e32 v9, v24, v100
	v_add_u32_e32 v100, 0x6000, v69
	ds_read2_b64 v[90:93], v100 offset0:96 offset1:100
	s_waitcnt lgkmcnt(2)
	v_mfma_f32_16x16x32_bf16 v[82:85], v[82:85], v[74:77], 0
	v_mul_f32_e32 v9, 0x3fb8aa3b, v9
	v_exp_f32_e32 v9, v9
	v_ashrrev_i32_e32 v19, 31, v18
	s_waitcnt lgkmcnt(1)
	v_mfma_f32_16x16x32_bf16 v[86:89], v[86:89], v[74:77], 0
	v_add_f32_e32 v8, v9, v8
	v_add_u32_e32 v9, 32, v69
	s_waitcnt lgkmcnt(0)
	v_mfma_f32_16x16x32_bf16 v[74:77], v[90:93], v[74:77], 0
	s_nop 1
	v_cvt_pk_bf16_f32 v90, v108, v109
	s_nop 1
	v_cvt_pk_bf16_f32 v91, v110, v111
	s_nop 1
	v_cvt_pk_bf16_f32 v92, v112, v113
	s_nop 1
	v_cvt_pk_bf16_f32 v93, v114, v115
	ds_read2_b64 v[94:97], v69 offset0:8 offset1:12
	s_waitcnt lgkmcnt(0)
	v_mfma_f32_16x16x32_bf16 v[78:81], v[94:97], v[90:93], v[78:81]
	ds_read2_b64 v[94:97], v98 offset0:40 offset1:44
	s_waitcnt lgkmcnt(0)
	v_mfma_f32_16x16x32_bf16 v[82:85], v[94:97], v[90:93], v[82:85]
	ds_read2_b64 v[94:97], v99 offset0:72 offset1:76
	s_waitcnt lgkmcnt(0)
	v_mfma_f32_16x16x32_bf16 v[86:89], v[94:97], v[90:93], v[86:89]
	ds_read2_b64 v[94:97], v100 offset0:104 offset1:108
	s_waitcnt lgkmcnt(0)
	v_mfma_f32_16x16x32_bf16 v[74:77], v[94:97], v[90:93], v[74:77]
	s_nop 1
	v_cvt_pk_bf16_f32 v90, v71, v116
	s_nop 1
	v_cvt_pk_bf16_f32 v91, v117, v118
	s_nop 1
	v_cvt_pk_bf16_f32 v92, v119, v120
	s_nop 1
	v_cvt_pk_bf16_f32 v93, v121, v122
	ds_read2_b64 v[94:97], v69 offset0:16 offset1:20
	s_waitcnt lgkmcnt(0)
	v_mfma_f32_16x16x32_bf16 v[78:81], v[94:97], v[90:93], v[78:81]
	ds_read2_b64 v[94:97], v98 offset0:48 offset1:52
	s_waitcnt lgkmcnt(0)
	v_mfma_f32_16x16x32_bf16 v[82:85], v[94:97], v[90:93], v[82:85]
	ds_read2_b64 v[94:97], v99 offset0:80 offset1:84
	s_waitcnt lgkmcnt(0)
	v_mfma_f32_16x16x32_bf16 v[86:89], v[94:97], v[90:93], v[86:89]
	ds_read2_b64 v[94:97], v100 offset0:112 offset1:116
	s_waitcnt lgkmcnt(0)
	v_mfma_f32_16x16x32_bf16 v[74:77], v[94:97], v[90:93], v[74:77]
	s_nop 1
	v_cvt_pk_bf16_f32 v90, v14, v15
	s_nop 1
	v_cvt_pk_bf16_f32 v91, v70, v72
	s_nop 1
	v_cvt_pk_bf16_f32 v92, v123, v124
	s_nop 1
	v_cvt_pk_bf16_f32 v93, v125, v126
	ds_read2_b64 v[70:73], v69 offset0:24 offset1:28
	s_waitcnt lgkmcnt(0)
	v_mfma_f32_16x16x32_bf16 v[70:73], v[70:73], v[90:93], v[78:81]
	s_nop 2
	ds_read2_b64 v[78:81], v98 offset0:56 offset1:60
	v_div_scale_f32 v14, s[56:57], v8, v8, 1.0
	s_waitcnt lgkmcnt(0)
	v_mfma_f32_16x16x32_bf16 v[78:81], v[78:81], v[90:93], v[82:85]
	s_nop 2
	ds_read2_b64 v[82:85], v99 offset0:88 offset1:92
	v_rcp_f32_e32 v15, v14
	s_waitcnt lgkmcnt(0)
	v_mfma_f32_16x16x32_bf16 v[82:85], v[82:85], v[90:93], v[86:89]
	s_nop 2
	ds_read2_b64 v[86:89], v100 offset0:120 offset1:124
	s_nop 1
	v_cvt_pk_bf16_f32 v10, v10, v11
	s_nop 1
	v_cvt_pk_bf16_f32 v11, v12, v13
	s_waitcnt lgkmcnt(0)
	v_mfma_f32_16x16x32_bf16 v[74:77], v[86:89], v[90:93], v[74:77]
	s_nop 1
	v_cvt_pk_bf16_f32 v12, v21, v21
	s_nop 1
	v_cvt_pk_bf16_f32 v13, v21, v21
	ds_read_b64 v[86:87], v69 offset:256
	s_waitcnt lgkmcnt(0)
	v_mov_b32_e32 v88, v86
	v_mov_b32_e32 v89, v87
	s_nop 1
	v_mfma_f32_16x16x32_bf16 v[70:73], v[86:89], v[10:13], v[70:73]
	ds_read_b64 v[86:87], v69 offset:8704
	s_waitcnt lgkmcnt(0)
	v_mov_b32_e32 v88, v86
	v_mov_b32_e32 v89, v87
	s_nop 1
	v_mfma_f32_16x16x32_bf16 v[78:81], v[86:89], v[10:13], v[78:81]
	ds_read_b64 v[86:87], v69 offset:17152
	s_waitcnt lgkmcnt(0)
	v_mov_b32_e32 v88, v86
	v_mov_b32_e32 v89, v87
	s_nop 1
	v_mfma_f32_16x16x32_bf16 v[82:85], v[86:89], v[10:13], v[82:85]
	ds_read_b64 v[86:87], v69 offset:25600
	v_fma_f32 v69, -v14, v15, 1.0
	v_fmac_f32_e32 v15, v69, v15
	v_div_scale_f32 v69, vcc, 1.0, v8, 1.0
	s_waitcnt lgkmcnt(0)
	v_mov_b32_e32 v88, v86
	v_mov_b32_e32 v89, v87
	s_nop 1
	v_mfma_f32_16x16x32_bf16 v[10:13], v[86:89], v[10:13], v[74:77]
	s_nop 2
	v_mul_f32_e32 v74, v69, v15
	v_fma_f32 v75, -v14, v74, v69
	v_fmac_f32_e32 v74, v75, v15
	v_fma_f32 v14, -v14, v74, v69
	v_div_fmas_f32 v14, v14, v15, v74
	v_div_fixup_f32 v8, v14, v8, 1.0
	v_lshlrev_b64 v[14:15], 11, v[18:19]
	v_pk_mul_f32 v[72:73], v[8:9], v[72:73] op_sel_hi:[0,1]
	v_pk_mul_f32 v[70:71], v[8:9], v[70:71] op_sel_hi:[0,1]
	s_nop 1
	v_cvt_pk_bf16_f32 v70, v70, v71
	s_nop 1
	v_cvt_pk_bf16_f32 v71, v72, v73
	v_lshl_add_u64 v[14:15], v[16:17], 0, v[14:15]
	v_pk_mul_f32 v[72:73], v[8:9], v[78:79] op_sel_hi:[0,1]
	global_store_dwordx2 v[14:15], v[70:71], off
	v_pk_mul_f32 v[70:71], v[8:9], v[80:81] op_sel_hi:[0,1]
	s_nop 1
	v_cvt_pk_bf16_f32 v72, v72, v73
	s_nop 1
	v_cvt_pk_bf16_f32 v73, v70, v71
	global_store_dwordx2 v[14:15], v[72:73], off offset:32
	v_pk_mul_f32 v[72:73], v[8:9], v[82:83] op_sel_hi:[0,1]
	v_pk_mul_f32 v[10:11], v[8:9], v[10:11] op_sel_hi:[0,1]
	v_pk_mul_f32 v[70:71], v[8:9], v[84:85] op_sel_hi:[0,1]
	s_nop 1
	v_cvt_pk_bf16_f32 v72, v72, v73
	s_nop 1
	v_cvt_pk_bf16_f32 v73, v70, v71
	global_store_dwordx2 v[14:15], v[72:73], off offset:64
	v_pk_mul_f32 v[12:13], v[8:9], v[12:13] op_sel_hi:[0,1]
	s_nop 1
	v_cvt_pk_bf16_f32 v10, v10, v11
	s_nop 1
	v_cvt_pk_bf16_f32 v11, v12, v13
	global_store_dwordx2 v[14:15], v[10:11], off offset:96
	v_mov_b32_e32 v69, v9
	s_waitcnt vmcnt(4)
	v_mov_b64_e32 v[10:11], v[6:7]
	v_mov_b64_e32 v[14:15], v[2:3]
	v_add_u32_e32 v18, 16, v18
	v_mov_b32_e32 v19, v20
	v_mov_b64_e32 v[8:9], v[4:5]
	v_mov_b64_e32 v[12:13], v[0:1]
	s_cbranch_scc0 .LBB0_419

.LBB0_911:
	s_cmp_eq_u32 s74, 28
	s_cselect_b64 s[14:15], -1, 0
	s_cmp_lg_u32 s74, 28
	s_cbranch_scc1 .LBB0_910
	global_load_dword v144, v[162:163], off
	global_load_dword v146, v[162:163], off offset:64
	global_load_dword v148, v[162:163], off offset:128
	global_load_dword v150, v[162:163], off offset:192
	global_load_dword v152, v[162:163], off offset:512
	global_load_dword v154, v[162:163], off offset:576
	global_load_dword v156, v[162:163], off offset:640
	global_load_dword v158, v[162:163], off offset:704
	s_branch .LBB0_910

.LBB0_915:
	s_waitcnt vmcnt(8)
	v_pk_mul_f32 v[162:163], v[144:145], v[126:127] op_sel_hi:[0,1]
	v_pk_mul_f32 v[164:165], v[144:145], v[124:125] op_sel_hi:[0,1]
	v_pk_mul_f32 v[124:125], v[144:145], v[106:107] op_sel_hi:[0,1]
	v_pk_mul_f32 v[106:107], v[146:147], v[114:115] op_sel_hi:[0,1]
	v_pk_mul_f32 v[114:115], v[146:147], v[92:93] op_sel_hi:[0,1]
	v_pk_mul_f32 v[92:93], v[148:149], v[74:75] op_sel_hi:[0,1]
	v_pk_mul_f32 v[74:75], v[150:151], v[82:83] op_sel_hi:[0,1]
	v_pk_mul_f32 v[82:83], v[150:151], v[68:69] op_sel_hi:[0,1]
	v_pk_mul_f32 v[68:69], v[152:153], v[46:47] op_sel_hi:[0,1]
	v_pk_mul_f32 v[46:47], v[154:155], v[24:25] op_sel_hi:[0,1]
	v_pk_mul_f32 v[24:25], v[156:157], v[32:33] op_sel_hi:[0,1]
	v_pk_mul_f32 v[32:33], v[156:157], v[14:15] op_sel_hi:[0,1]
	v_pk_mul_f32 v[14:15], v[158:159], v[20:21] op_sel_hi:[0,1]
	v_mul_f32_e32 v20, 0xbfb8aa3b, v162
	v_mul_f32_e32 v21, 0xbfb8aa3b, v163
	v_exp_f32_e32 v20, v20
	v_exp_f32_e32 v21, v21
	v_pk_mul_f32 v[122:123], v[144:145], v[122:123] op_sel_hi:[0,1]
	v_pk_mul_f32 v[166:167], v[144:145], v[110:111] op_sel_hi:[0,1]
	v_pk_mul_f32 v[168:169], v[144:145], v[108:109] op_sel_hi:[0,1]
	v_pk_mul_f32 v[126:127], v[144:145], v[104:105] op_sel_hi:[0,1]
	v_pk_mul_f32 v[104:105], v[146:147], v[112:113] op_sel_hi:[0,1]
	v_pk_mul_f32 v[112:113], v[146:147], v[94:95] op_sel_hi:[0,1]
	v_pk_mul_f32 v[108:109], v[146:147], v[90:91] op_sel_hi:[0,1]
	v_pk_mul_f32 v[110:111], v[146:147], v[88:89] op_sel_hi:[0,1]
	v_pk_mul_f32 v[90:91], v[148:149], v[98:99] op_sel_hi:[0,1]
	v_pk_mul_f32 v[88:89], v[148:149], v[96:97] op_sel_hi:[0,1]
	v_pk_mul_f32 v[96:97], v[148:149], v[78:79] op_sel_hi:[0,1]
	v_pk_mul_f32 v[98:99], v[148:149], v[76:77] op_sel_hi:[0,1]
	v_pk_mul_f32 v[94:95], v[148:149], v[72:73] op_sel_hi:[0,1]
	v_pk_mul_f32 v[72:73], v[150:151], v[80:81] op_sel_hi:[0,1]
	v_pk_mul_f32 v[80:81], v[150:151], v[70:71] op_sel_hi:[0,1]
	v_pk_mul_f32 v[76:77], v[150:151], v[66:67] op_sel_hi:[0,1]
	v_pk_mul_f32 v[78:79], v[150:151], v[64:65] op_sel_hi:[0,1]
	v_pk_mul_f32 v[64:65], v[152:153], v[62:63] op_sel_hi:[0,1]
	v_pk_mul_f32 v[66:67], v[152:153], v[60:61] op_sel_hi:[0,1]
	v_pk_mul_f32 v[70:71], v[152:153], v[44:45] op_sel_hi:[0,1]
	v_pk_mul_f32 v[60:61], v[152:153], v[42:43] op_sel_hi:[0,1]
	v_pk_mul_f32 v[62:63], v[152:153], v[40:41] op_sel_hi:[0,1]
	v_pk_mul_f32 v[54:55], v[154:155], v[54:55] op_sel_hi:[0,1]
	v_pk_mul_f32 v[52:53], v[154:155], v[52:53] op_sel_hi:[0,1]
	v_pk_mul_f32 v[42:43], v[154:155], v[50:51] op_sel_hi:[0,1]
	v_pk_mul_f32 v[40:41], v[154:155], v[48:49] op_sel_hi:[0,1]
	v_pk_mul_f32 v[48:49], v[154:155], v[30:31] op_sel_hi:[0,1]
	v_pk_mul_f32 v[50:51], v[154:155], v[28:29] op_sel_hi:[0,1]
	v_pk_mul_f32 v[44:45], v[154:155], v[26:27] op_sel_hi:[0,1]
	v_add_f32_e32 v20, 1.0, v20
	v_add_f32_e32 v21, 1.0, v21
	v_mul_f32_e32 v155, 0xbfb8aa3b, v122
	v_rcp_f32_e32 v20, v20
	v_rcp_f32_e32 v21, v21
	v_exp_f32_e32 v155, v155
	v_pk_mul_f32 v[120:121], v[144:145], v[120:121] op_sel_hi:[0,1]
	v_pk_mul_f32 v[30:31], v[156:157], v[8:9] op_sel_hi:[0,1]
	v_pk_mul_f32 v[8:9], v[158:159], v[16:17] op_sel_hi:[0,1]
	v_mul_f32_e32 v16, 0xbfb8aa3b, v164
	v_mul_f32_e32 v17, 0xbfb8aa3b, v165
	v_pk_mul_f32 v[20:21], v[162:163], v[20:21]
	v_add_f32_e32 v155, 1.0, v155
	v_pk_mul_f32 v[26:27], v[156:157], v[34:35] op_sel_hi:[0,1]
	v_pk_mul_f32 v[34:35], v[156:157], v[12:13] op_sel_hi:[0,1]
	v_pk_mul_f32 v[12:13], v[158:159], v[22:23] op_sel_hi:[0,1]
	v_exp_f32_e32 v16, v16
	v_exp_f32_e32 v17, v17
	v_pk_mul_f32 v[22:23], v[20:21], v[166:167]
	v_mul_f32_e32 v20, 0xbfb8aa3b, v120
	v_mul_f32_e32 v21, 0xbfb8aa3b, v121
	v_rcp_f32_e32 v162, v155
	v_mul_f32_e32 v155, 0xbfb8aa3b, v123
	v_exp_f32_e32 v20, v20
	v_exp_f32_e32 v21, v21
	v_exp_f32_e32 v155, v155
	v_add_f32_e32 v16, 1.0, v16
	v_add_f32_e32 v17, 1.0, v17
	v_rcp_f32_e32 v16, v16
	v_rcp_f32_e32 v17, v17
	v_add_f32_e32 v20, 1.0, v20
	v_add_f32_e32 v21, 1.0, v21
	v_add_f32_e32 v155, 1.0, v155
	v_rcp_f32_e32 v20, v20
	v_rcp_f32_e32 v21, v21
	v_rcp_f32_e32 v163, v155
	v_pk_mul_f32 v[16:17], v[164:165], v[16:17]
	v_pk_mul_f32 v[28:29], v[156:157], v[10:11] op_sel_hi:[0,1]
	v_pk_mul_f32 v[10:11], v[158:159], v[18:19] op_sel_hi:[0,1]
	v_lshl_or_b32 v18, s65, 7, v151
	v_pk_mul_f32 v[16:17], v[16:17], v[168:169]
	v_pk_mul_f32 v[122:123], v[122:123], v[162:163]
	v_pk_mul_f32 v[20:21], v[120:121], v[20:21]
	v_ashrrev_i32_e32 v19, 31, v18
	v_pk_mul_f32 v[120:121], v[122:123], v[124:125]
	v_pk_mul_f32 v[122:123], v[20:21], v[126:127]
	s_nop 1
	v_cvt_pk_bf16_f32 v20, v16, v17
	v_mov_b64_e32 v[16:17], s[4:5]
	s_nop 1
	v_cvt_pk_bf16_f32 v21, v22, v23
	s_nop 1
	v_cvt_pk_bf16_f32 v22, v122, v123
	s_nop 1
	v_cvt_pk_bf16_f32 v23, v120, v121
	v_mad_i64_i32 v[120:121], s[14:15], v160, s64, v[16:17]
	v_lshlrev_b64 v[18:19], 1, v[18:19]
	v_pk_mul_f32 v[118:119], v[146:147], v[118:119] op_sel_hi:[0,1]
	v_lshl_add_u64 v[120:121], v[120:121], 0, v[18:19]
	global_store_dwordx4 v[120:121], v[20:23], off
	v_pk_mul_f32 v[116:117], v[146:147], v[116:117] op_sel_hi:[0,1]
	v_pk_mul_f32 v[102:103], v[148:149], v[102:103] op_sel_hi:[0,1]
	v_mul_f32_e32 v22, 0xbfb8aa3b, v118
	v_mul_f32_e32 v23, 0xbfb8aa3b, v119
	v_exp_f32_e32 v22, v22
	v_exp_f32_e32 v23, v23
	v_mul_f32_e32 v20, 0xbfb8aa3b, v116
	v_mul_f32_e32 v21, 0xbfb8aa3b, v117
	v_exp_f32_e32 v20, v20
	v_exp_f32_e32 v21, v21
	v_add_f32_e32 v22, 1.0, v22
	v_add_f32_e32 v23, 1.0, v23
	v_rcp_f32_e32 v22, v22
	v_rcp_f32_e32 v23, v23
	v_add_f32_e32 v20, 1.0, v20
	v_add_f32_e32 v21, 1.0, v21
	v_rcp_f32_e32 v20, v20
	v_rcp_f32_e32 v21, v21
	v_pk_mul_f32 v[22:23], v[118:119], v[22:23]
	v_pk_mul_f32 v[100:101], v[148:149], v[100:101] op_sel_hi:[0,1]
	v_pk_mul_f32 v[22:23], v[22:23], v[112:113]
	v_mul_f32_e32 v112, 0xbfb8aa3b, v104
	v_mul_f32_e32 v113, 0xbfb8aa3b, v105
	v_exp_f32_e32 v112, v112
	v_exp_f32_e32 v113, v113
	v_pk_mul_f32 v[20:21], v[116:117], v[20:21]
	v_pk_mul_f32 v[86:87], v[150:151], v[86:87] op_sel_hi:[0,1]
	v_pk_mul_f32 v[20:21], v[20:21], v[114:115]
	v_mul_f32_e32 v114, 0xbfb8aa3b, v106
	v_mul_f32_e32 v115, 0xbfb8aa3b, v107
	v_exp_f32_e32 v114, v114
	v_exp_f32_e32 v115, v115
	v_add_f32_e32 v112, 1.0, v112
	v_add_f32_e32 v113, 1.0, v113
	v_rcp_f32_e32 v112, v112
	v_rcp_f32_e32 v113, v113
	v_add_f32_e32 v114, 1.0, v114
	v_add_f32_e32 v115, 1.0, v115
	v_rcp_f32_e32 v114, v114
	v_rcp_f32_e32 v115, v115
	v_pk_mul_f32 v[104:105], v[104:105], v[112:113]
	s_nop 1
	v_cvt_pk_bf16_f32 v20, v20, v21
	s_nop 1
	v_cvt_pk_bf16_f32 v21, v22, v23
	v_pk_mul_f32 v[106:107], v[106:107], v[114:115]
	v_pk_mul_f32 v[104:105], v[104:105], v[110:111]
	v_pk_mul_f32 v[106:107], v[106:107], v[108:109]
	s_nop 1
	v_cvt_pk_bf16_f32 v22, v104, v105
	v_or_b32_e32 v104, 16, v160
	v_mad_i64_i32 v[104:105], s[14:15], v104, s64, v[16:17]
	s_nop 1
	v_cvt_pk_bf16_f32 v23, v106, v107
	v_lshl_add_u64 v[104:105], v[104:105], 0, v[18:19]
	global_store_dwordx4 v[104:105], v[20:23], off
	v_pk_mul_f32 v[84:85], v[150:151], v[84:85] op_sel_hi:[0,1]
	v_pk_mul_f32 v[56:57], v[152:153], v[56:57] op_sel_hi:[0,1]
	v_mul_f32_e32 v22, 0xbfb8aa3b, v102
	v_mul_f32_e32 v23, 0xbfb8aa3b, v103
	v_exp_f32_e32 v22, v22
	v_exp_f32_e32 v23, v23
	v_mul_f32_e32 v20, 0xbfb8aa3b, v100
	v_mul_f32_e32 v21, 0xbfb8aa3b, v101
	v_exp_f32_e32 v20, v20
	v_exp_f32_e32 v21, v21
	v_add_f32_e32 v22, 1.0, v22
	v_add_f32_e32 v23, 1.0, v23
	v_rcp_f32_e32 v22, v22
	v_rcp_f32_e32 v23, v23
	v_add_f32_e32 v20, 1.0, v20
	v_add_f32_e32 v21, 1.0, v21
	v_rcp_f32_e32 v20, v20
	v_rcp_f32_e32 v21, v21
	v_pk_mul_f32 v[22:23], v[102:103], v[22:23]
	v_pk_mul_f32 v[58:59], v[152:153], v[58:59] op_sel_hi:[0,1]
	v_pk_mul_f32 v[22:23], v[22:23], v[96:97]
	v_mul_f32_e32 v96, 0xbfb8aa3b, v88
	v_mul_f32_e32 v97, 0xbfb8aa3b, v89
	v_exp_f32_e32 v96, v96
	v_exp_f32_e32 v97, v97
	v_pk_mul_f32 v[20:21], v[100:101], v[20:21]
	v_pk_mul_f32 v[38:39], v[156:157], v[38:39] op_sel_hi:[0,1]
	v_pk_mul_f32 v[20:21], v[20:21], v[98:99]
	v_mul_f32_e32 v98, 0xbfb8aa3b, v90
	v_mul_f32_e32 v99, 0xbfb8aa3b, v91
	v_exp_f32_e32 v98, v98
	v_exp_f32_e32 v99, v99
	v_add_f32_e32 v96, 1.0, v96
	v_add_f32_e32 v97, 1.0, v97
	v_rcp_f32_e32 v96, v96
	v_rcp_f32_e32 v97, v97
	v_add_f32_e32 v98, 1.0, v98
	v_add_f32_e32 v99, 1.0, v99
	v_rcp_f32_e32 v98, v98
	v_rcp_f32_e32 v99, v99
	v_pk_mul_f32 v[88:89], v[88:89], v[96:97]
	s_nop 1
	v_cvt_pk_bf16_f32 v20, v20, v21
	s_nop 1
	v_cvt_pk_bf16_f32 v21, v22, v23
	v_pk_mul_f32 v[90:91], v[90:91], v[98:99]
	v_pk_mul_f32 v[88:89], v[88:89], v[94:95]
	v_pk_mul_f32 v[90:91], v[90:91], v[92:93]
	s_nop 1
	v_cvt_pk_bf16_f32 v22, v88, v89
	v_or_b32_e32 v88, 32, v160
	v_mad_i64_i32 v[88:89], s[14:15], v88, s64, v[16:17]
	s_nop 1
	v_cvt_pk_bf16_f32 v23, v90, v91
	v_lshl_add_u64 v[88:89], v[88:89], 0, v[18:19]
	global_store_dwordx4 v[88:89], v[20:23], off
	v_pk_mul_f32 v[36:37], v[156:157], v[36:37] op_sel_hi:[0,1]
	v_pk_mul_f32 v[6:7], v[158:159], v[6:7] op_sel_hi:[0,1]
	v_mul_f32_e32 v22, 0xbfb8aa3b, v86
	v_mul_f32_e32 v23, 0xbfb8aa3b, v87
	v_exp_f32_e32 v22, v22
	v_exp_f32_e32 v23, v23
	v_mul_f32_e32 v20, 0xbfb8aa3b, v84
	v_mul_f32_e32 v21, 0xbfb8aa3b, v85
	v_exp_f32_e32 v20, v20
	v_exp_f32_e32 v21, v21
	v_add_f32_e32 v22, 1.0, v22
	v_add_f32_e32 v23, 1.0, v23
	v_rcp_f32_e32 v22, v22
	v_rcp_f32_e32 v23, v23
	v_add_f32_e32 v20, 1.0, v20
	v_add_f32_e32 v21, 1.0, v21
	v_rcp_f32_e32 v20, v20
	v_rcp_f32_e32 v21, v21
	v_pk_mul_f32 v[22:23], v[86:87], v[22:23]
	v_pk_mul_f32 v[4:5], v[158:159], v[4:5] op_sel_hi:[0,1]
	v_pk_mul_f32 v[22:23], v[22:23], v[80:81]
	v_mul_f32_e32 v80, 0xbfb8aa3b, v72
	v_mul_f32_e32 v81, 0xbfb8aa3b, v73
	v_exp_f32_e32 v80, v80
	v_exp_f32_e32 v81, v81
	v_pk_mul_f32 v[20:21], v[84:85], v[20:21]
	v_pk_mul_f32 v[2:3], v[158:159], v[2:3] op_sel_hi:[0,1]
	v_pk_mul_f32 v[20:21], v[20:21], v[82:83]
	v_mul_f32_e32 v82, 0xbfb8aa3b, v74
	v_mul_f32_e32 v83, 0xbfb8aa3b, v75
	v_exp_f32_e32 v82, v82
	v_exp_f32_e32 v83, v83
	v_add_f32_e32 v80, 1.0, v80
	v_add_f32_e32 v81, 1.0, v81
	v_rcp_f32_e32 v80, v80
	v_rcp_f32_e32 v81, v81
	v_add_f32_e32 v82, 1.0, v82
	v_add_f32_e32 v83, 1.0, v83
	v_rcp_f32_e32 v82, v82
	v_rcp_f32_e32 v83, v83
	v_pk_mul_f32 v[72:73], v[72:73], v[80:81]
	s_nop 1
	v_cvt_pk_bf16_f32 v20, v20, v21
	s_nop 1
	v_cvt_pk_bf16_f32 v21, v22, v23
	v_pk_mul_f32 v[74:75], v[74:75], v[82:83]
	v_pk_mul_f32 v[72:73], v[72:73], v[78:79]
	v_pk_mul_f32 v[74:75], v[74:75], v[76:77]
	s_nop 1
	v_cvt_pk_bf16_f32 v22, v72, v73
	v_or_b32_e32 v72, 48, v160
	v_mad_i64_i32 v[72:73], s[14:15], v72, s64, v[16:17]
	s_nop 1
	v_cvt_pk_bf16_f32 v23, v74, v75
	v_lshl_add_u64 v[72:73], v[72:73], 0, v[18:19]
	global_store_dwordx4 v[72:73], v[20:23], off
	v_add_u32_e32 v72, 0x80, v160
	v_pk_mul_f32 v[0:1], v[158:159], v[0:1] op_sel_hi:[0,1]
	v_mul_f32_e32 v22, 0xbfb8aa3b, v64
	v_mul_f32_e32 v23, 0xbfb8aa3b, v65
	v_exp_f32_e32 v22, v22
	v_exp_f32_e32 v23, v23
	v_mul_f32_e32 v20, 0xbfb8aa3b, v66
	v_mul_f32_e32 v21, 0xbfb8aa3b, v67
	v_exp_f32_e32 v20, v20
	v_exp_f32_e32 v21, v21
	v_add_f32_e32 v22, 1.0, v22
	v_add_f32_e32 v23, 1.0, v23
	v_rcp_f32_e32 v22, v22
	v_rcp_f32_e32 v23, v23
	v_add_f32_e32 v20, 1.0, v20
	v_add_f32_e32 v21, 1.0, v21
	v_rcp_f32_e32 v20, v20
	v_rcp_f32_e32 v21, v21
	v_pk_mul_f32 v[22:23], v[64:65], v[22:23]
	v_mul_f32_e32 v64, 0xbfb8aa3b, v56
	v_mul_f32_e32 v65, 0xbfb8aa3b, v57
	v_exp_f32_e32 v64, v64
	v_exp_f32_e32 v65, v65
	v_pk_mul_f32 v[20:21], v[66:67], v[20:21]
	v_mul_f32_e32 v66, 0xbfb8aa3b, v58
	v_mul_f32_e32 v67, 0xbfb8aa3b, v59
	v_exp_f32_e32 v66, v66
	v_exp_f32_e32 v67, v67
	v_add_f32_e32 v64, 1.0, v64
	v_add_f32_e32 v65, 1.0, v65
	v_rcp_f32_e32 v64, v64
	v_rcp_f32_e32 v65, v65
	v_add_f32_e32 v66, 1.0, v66
	v_add_f32_e32 v67, 1.0, v67
	v_rcp_f32_e32 v66, v66
	v_rcp_f32_e32 v67, v67
	v_pk_mul_f32 v[56:57], v[56:57], v[64:65]
	v_pk_mul_f32 v[22:23], v[22:23], v[68:69]
	v_pk_mul_f32 v[20:21], v[20:21], v[70:71]
	v_pk_mul_f32 v[56:57], v[56:57], v[62:63]
	v_pk_mul_f32 v[58:59], v[58:59], v[66:67]
	s_nop 1
	v_cvt_pk_bf16_f32 v20, v20, v21
	s_nop 1
	v_cvt_pk_bf16_f32 v21, v22, v23
	s_nop 1
	v_cvt_pk_bf16_f32 v22, v56, v57
	v_mad_i64_i32 v[56:57], s[14:15], v72, s64, v[16:17]
	v_pk_mul_f32 v[58:59], v[58:59], v[60:61]
	v_lshl_add_u64 v[56:57], v[56:57], 0, v[18:19]
	s_nop 1
	v_cvt_pk_bf16_f32 v23, v58, v59
	global_store_dwordx4 v[56:57], v[20:23], off
	s_andn2_b64 vcc, exec, s[8:9]
	s_nop 0
	v_mul_f32_e32 v22, 0xbfb8aa3b, v54
	v_mul_f32_e32 v23, 0xbfb8aa3b, v55
	v_exp_f32_e32 v22, v22
	v_exp_f32_e32 v23, v23
	v_mul_f32_e32 v20, 0xbfb8aa3b, v52
	v_mul_f32_e32 v21, 0xbfb8aa3b, v53
	v_exp_f32_e32 v20, v20
	v_exp_f32_e32 v21, v21
	v_add_f32_e32 v22, 1.0, v22
	v_add_f32_e32 v23, 1.0, v23
	v_rcp_f32_e32 v22, v22
	v_rcp_f32_e32 v23, v23
	v_add_f32_e32 v20, 1.0, v20
	v_add_f32_e32 v21, 1.0, v21
	v_rcp_f32_e32 v20, v20
	v_rcp_f32_e32 v21, v21
	v_pk_mul_f32 v[22:23], v[54:55], v[22:23]
	v_pk_mul_f32 v[20:21], v[52:53], v[20:21]
	v_pk_mul_f32 v[22:23], v[22:23], v[48:49]
	v_mul_f32_e32 v48, 0xbfb8aa3b, v40
	v_mul_f32_e32 v49, 0xbfb8aa3b, v41
	v_exp_f32_e32 v48, v48
	v_exp_f32_e32 v49, v49
	v_pk_mul_f32 v[20:21], v[20:21], v[50:51]
	v_mul_f32_e32 v50, 0xbfb8aa3b, v42
	v_mul_f32_e32 v51, 0xbfb8aa3b, v43
	v_exp_f32_e32 v50, v50
	v_exp_f32_e32 v51, v51
	v_add_f32_e32 v48, 1.0, v48
	v_add_f32_e32 v49, 1.0, v49
	v_rcp_f32_e32 v48, v48
	v_rcp_f32_e32 v49, v49
	v_add_f32_e32 v50, 1.0, v50
	v_add_f32_e32 v51, 1.0, v51
	v_rcp_f32_e32 v50, v50
	v_rcp_f32_e32 v51, v51
	v_pk_mul_f32 v[40:41], v[40:41], v[48:49]
	s_nop 1
	v_cvt_pk_bf16_f32 v20, v20, v21
	s_nop 1
	v_cvt_pk_bf16_f32 v21, v22, v23
	v_pk_mul_f32 v[42:43], v[42:43], v[50:51]
	v_pk_mul_f32 v[40:41], v[40:41], v[46:47]
	v_pk_mul_f32 v[42:43], v[42:43], v[44:45]
	s_nop 1
	v_cvt_pk_bf16_f32 v22, v40, v41
	v_add_u32_e32 v40, 0x90, v160
	v_mad_i64_i32 v[40:41], s[14:15], v40, s64, v[16:17]
	s_nop 1
	v_cvt_pk_bf16_f32 v23, v42, v43
	v_lshl_add_u64 v[40:41], v[40:41], 0, v[18:19]
	global_store_dwordx4 v[40:41], v[20:23], off
	s_nop 1
	v_mul_f32_e32 v22, 0xbfb8aa3b, v38
	v_mul_f32_e32 v23, 0xbfb8aa3b, v39
	v_exp_f32_e32 v22, v22
	v_exp_f32_e32 v23, v23
	v_mul_f32_e32 v20, 0xbfb8aa3b, v36
	v_mul_f32_e32 v21, 0xbfb8aa3b, v37
	v_exp_f32_e32 v20, v20
	v_exp_f32_e32 v21, v21
	v_add_f32_e32 v22, 1.0, v22
	v_add_f32_e32 v23, 1.0, v23
	v_rcp_f32_e32 v22, v22
	v_rcp_f32_e32 v23, v23
	v_add_f32_e32 v20, 1.0, v20
	v_add_f32_e32 v21, 1.0, v21
	v_rcp_f32_e32 v20, v20
	v_rcp_f32_e32 v21, v21
	v_pk_mul_f32 v[22:23], v[38:39], v[22:23]
	v_pk_mul_f32 v[20:21], v[36:37], v[20:21]
	v_pk_mul_f32 v[22:23], v[22:23], v[32:33]
	v_mul_f32_e32 v32, 0xbfb8aa3b, v24
	v_mul_f32_e32 v33, 0xbfb8aa3b, v25
	v_exp_f32_e32 v32, v32
	v_exp_f32_e32 v33, v33
	v_pk_mul_f32 v[20:21], v[20:21], v[34:35]
	v_mul_f32_e32 v34, 0xbfb8aa3b, v26
	v_mul_f32_e32 v35, 0xbfb8aa3b, v27
	v_exp_f32_e32 v34, v34
	v_exp_f32_e32 v35, v35
	v_add_f32_e32 v32, 1.0, v32
	v_add_f32_e32 v33, 1.0, v33
	v_rcp_f32_e32 v32, v32
	v_rcp_f32_e32 v33, v33
	v_add_f32_e32 v34, 1.0, v34
	v_add_f32_e32 v35, 1.0, v35
	v_rcp_f32_e32 v34, v34
	v_rcp_f32_e32 v35, v35
	v_pk_mul_f32 v[24:25], v[24:25], v[32:33]
	s_nop 1
	v_cvt_pk_bf16_f32 v20, v20, v21
	s_nop 1
	v_cvt_pk_bf16_f32 v21, v22, v23
	v_pk_mul_f32 v[26:27], v[26:27], v[34:35]
	v_pk_mul_f32 v[24:25], v[24:25], v[30:31]
	v_pk_mul_f32 v[26:27], v[26:27], v[28:29]
	s_nop 1
	v_cvt_pk_bf16_f32 v22, v24, v25
	v_add_u32_e32 v24, 0xa0, v160
	v_mad_i64_i32 v[24:25], s[14:15], v24, s64, v[16:17]
	s_nop 1
	v_cvt_pk_bf16_f32 v23, v26, v27
	v_lshl_add_u64 v[24:25], v[24:25], 0, v[18:19]
	global_store_dwordx4 v[24:25], v[20:23], off
	s_nop 1
	v_mul_f32_e32 v20, 0xbfb8aa3b, v14
	v_mul_f32_e32 v21, 0xbfb8aa3b, v15
	v_mul_f32_e32 v22, 0xbfb8aa3b, v12
	v_mul_f32_e32 v23, 0xbfb8aa3b, v13
	v_exp_f32_e32 v20, v20
	v_exp_f32_e32 v21, v21
	v_exp_f32_e32 v22, v22
	v_exp_f32_e32 v23, v23
	v_add_f32_e32 v20, 1.0, v20
	v_add_f32_e32 v21, 1.0, v21
	v_add_f32_e32 v22, 1.0, v22
	v_add_f32_e32 v23, 1.0, v23
	v_rcp_f32_e32 v20, v20
	v_rcp_f32_e32 v21, v21
	v_rcp_f32_e32 v22, v22
	v_rcp_f32_e32 v23, v23
	v_pk_mul_f32 v[14:15], v[14:15], v[20:21]
	s_nop 0
	v_pk_mul_f32 v[4:5], v[14:15], v[4:5]
	v_pk_mul_f32 v[12:13], v[12:13], v[22:23]
	v_mul_f32_e32 v14, 0xbfb8aa3b, v10
	v_pk_mul_f32 v[6:7], v[12:13], v[6:7]
	v_mul_f32_e32 v12, 0xbfb8aa3b, v8
	v_mul_f32_e32 v13, 0xbfb8aa3b, v9
	v_mul_f32_e32 v15, 0xbfb8aa3b, v11
	v_exp_f32_e32 v12, v12
	v_exp_f32_e32 v13, v13
	v_exp_f32_e32 v14, v14
	v_exp_f32_e32 v15, v15
	v_add_f32_e32 v12, 1.0, v12
	v_add_f32_e32 v13, 1.0, v13
	v_add_f32_e32 v14, 1.0, v14
	v_add_f32_e32 v15, 1.0, v15
	v_rcp_f32_e32 v12, v12
	v_rcp_f32_e32 v13, v13
	v_rcp_f32_e32 v14, v14
	v_rcp_f32_e32 v15, v15
	v_pk_mul_f32 v[8:9], v[8:9], v[12:13]
	v_pk_mul_f32 v[10:11], v[10:11], v[14:15]
	s_nop 0
	v_pk_mul_f32 v[10:11], v[10:11], v[2:3]
	v_pk_mul_f32 v[2:3], v[8:9], v[0:1]
	s_nop 1
	v_cvt_pk_bf16_f32 v0, v4, v5
	v_add_u32_e32 v4, 0xb0, v160
	v_mad_i64_i32 v[4:5], s[14:15], v4, s64, v[16:17]
	v_lshl_add_u64 v[4:5], v[4:5], 0, v[18:19]
	s_mov_b64 s[14:15], -1
	s_nop 1
	v_cvt_pk_bf16_f32 v1, v6, v7
	s_nop 1
	v_cvt_pk_bf16_f32 v2, v2, v3
	s_nop 1
	v_cvt_pk_bf16_f32 v3, v10, v11
	global_store_dwordx4 v[4:5], v[0:3], off
	s_cbranch_vccnz .LBB0_902
	s_andn2_b64 vcc, exec, s[2:3]
	s_cbranch_vccnz .LBB0_901
	s_barrier
	s_branch .LBB0_901

.LBB0_1177:
	s_cmp_eq_u32 s57, 28
	s_cselect_b64 s[8:9], -1, 0
	s_cmp_lg_u32 s57, 28
	s_cbranch_scc1 .LBB0_1176
	global_load_dword v174, v[120:121], off
	global_load_dword v176, v[120:121], off offset:64
	global_load_dword v178, v[120:121], off offset:128
	global_load_dword v180, v[120:121], off offset:192
	global_load_dword v182, v[120:121], off offset:512
	global_load_dword v184, v[120:121], off offset:576
	global_load_dword v186, v[120:121], off offset:640
	global_load_dword v188, v[120:121], off offset:704
	s_branch .LBB0_1176

.LBB0_1181:
	s_waitcnt vmcnt(8)
	v_pk_mul_f32 v[114:115], v[174:175], v[114:115] op_sel_hi:[0,1]
	v_pk_mul_f32 v[112:113], v[174:175], v[112:113] op_sel_hi:[0,1]
	v_pk_mul_f32 v[118:119], v[174:175], v[118:119] op_sel_hi:[0,1]
	v_pk_mul_f32 v[116:117], v[174:175], v[116:117] op_sel_hi:[0,1]
	v_pk_mul_f32 v[122:123], v[174:175], v[106:107] op_sel_hi:[0,1]
	v_pk_mul_f32 v[120:121], v[174:175], v[104:105] op_sel_hi:[0,1]
	v_pk_mul_f32 v[126:127], v[174:175], v[98:99] op_sel_hi:[0,1]
	v_pk_mul_f32 v[124:125], v[174:175], v[96:97] op_sel_hi:[0,1]
	v_pk_mul_f32 v[110:111], v[176:177], v[110:111] op_sel_hi:[0,1]
	v_pk_mul_f32 v[108:109], v[176:177], v[108:109] op_sel_hi:[0,1]
	v_pk_mul_f32 v[106:107], v[176:177], v[102:103] op_sel_hi:[0,1]
	v_pk_mul_f32 v[104:105], v[176:177], v[100:101] op_sel_hi:[0,1]
	v_pk_mul_f32 v[102:103], v[176:177], v[90:91] op_sel_hi:[0,1]
	v_pk_mul_f32 v[100:101], v[176:177], v[88:89] op_sel_hi:[0,1]
	v_pk_mul_f32 v[98:99], v[176:177], v[82:83] op_sel_hi:[0,1]
	v_pk_mul_f32 v[96:97], v[176:177], v[80:81] op_sel_hi:[0,1]
	v_pk_mul_f32 v[94:95], v[178:179], v[94:95] op_sel_hi:[0,1]
	v_pk_mul_f32 v[92:93], v[178:179], v[92:93] op_sel_hi:[0,1]
	v_pk_mul_f32 v[90:91], v[178:179], v[86:87] op_sel_hi:[0,1]
	v_pk_mul_f32 v[88:89], v[178:179], v[84:85] op_sel_hi:[0,1]
	v_pk_mul_f32 v[86:87], v[178:179], v[74:75] op_sel_hi:[0,1]
	v_pk_mul_f32 v[84:85], v[178:179], v[72:73] op_sel_hi:[0,1]
	v_pk_mul_f32 v[82:83], v[178:179], v[66:67] op_sel_hi:[0,1]
	v_pk_mul_f32 v[80:81], v[178:179], v[64:65] op_sel_hi:[0,1]
	v_pk_mul_f32 v[78:79], v[180:181], v[78:79] op_sel_hi:[0,1]
	v_pk_mul_f32 v[76:77], v[180:181], v[76:77] op_sel_hi:[0,1]
	v_pk_mul_f32 v[74:75], v[180:181], v[70:71] op_sel_hi:[0,1]
	v_pk_mul_f32 v[72:73], v[180:181], v[68:69] op_sel_hi:[0,1]
	v_pk_mul_f32 v[70:71], v[180:181], v[62:63] op_sel_hi:[0,1]
	v_pk_mul_f32 v[68:69], v[180:181], v[60:61] op_sel_hi:[0,1]
	v_pk_mul_f32 v[66:67], v[180:181], v[58:59] op_sel_hi:[0,1]
	v_pk_mul_f32 v[64:65], v[180:181], v[56:57] op_sel_hi:[0,1]
	v_pk_mul_f32 v[62:63], v[182:183], v[54:55] op_sel_hi:[0,1]
	v_pk_mul_f32 v[60:61], v[182:183], v[52:53] op_sel_hi:[0,1]
	v_pk_mul_f32 v[58:59], v[182:183], v[50:51] op_sel_hi:[0,1]
	v_pk_mul_f32 v[56:57], v[182:183], v[48:49] op_sel_hi:[0,1]
	v_pk_mul_f32 v[54:55], v[182:183], v[42:43] op_sel_hi:[0,1]
	v_pk_mul_f32 v[52:53], v[182:183], v[40:41] op_sel_hi:[0,1]
	v_pk_mul_f32 v[50:51], v[182:183], v[34:35] op_sel_hi:[0,1]
	v_pk_mul_f32 v[48:49], v[182:183], v[32:33] op_sel_hi:[0,1]
	v_pk_mul_f32 v[46:47], v[184:185], v[46:47] op_sel_hi:[0,1]
	v_pk_mul_f32 v[44:45], v[184:185], v[44:45] op_sel_hi:[0,1]
	v_pk_mul_f32 v[42:43], v[184:185], v[38:39] op_sel_hi:[0,1]
	v_pk_mul_f32 v[40:41], v[184:185], v[36:37] op_sel_hi:[0,1]
	v_pk_mul_f32 v[38:39], v[184:185], v[26:27] op_sel_hi:[0,1]
	v_pk_mul_f32 v[36:37], v[184:185], v[24:25] op_sel_hi:[0,1]
	v_pk_mul_f32 v[34:35], v[184:185], v[18:19] op_sel_hi:[0,1]
	v_pk_mul_f32 v[32:33], v[184:185], v[16:17] op_sel_hi:[0,1]
	v_pk_mul_f32 v[30:31], v[186:187], v[30:31] op_sel_hi:[0,1]
	v_pk_mul_f32 v[28:29], v[186:187], v[28:29] op_sel_hi:[0,1]
	v_pk_mul_f32 v[26:27], v[186:187], v[22:23] op_sel_hi:[0,1]
	v_pk_mul_f32 v[24:25], v[186:187], v[20:21] op_sel_hi:[0,1]
	v_pk_mul_f32 v[22:23], v[186:187], v[14:15] op_sel_hi:[0,1]
	v_pk_mul_f32 v[20:21], v[186:187], v[12:13] op_sel_hi:[0,1]
	v_pk_mul_f32 v[18:19], v[186:187], v[10:11] op_sel_hi:[0,1]
	v_pk_mul_f32 v[16:17], v[186:187], v[8:9] op_sel_hi:[0,1]
	v_pk_mul_f32 v[14:15], v[188:189], v[134:135] op_sel_hi:[0,1]
	v_pk_mul_f32 v[12:13], v[188:189], v[132:133] op_sel_hi:[0,1]
	v_pk_mul_f32 v[10:11], v[188:189], v[130:131] op_sel_hi:[0,1]
	v_pk_mul_f32 v[8:9], v[188:189], v[128:129] op_sel_hi:[0,1]
	v_pk_mul_f32 v[6:7], v[188:189], v[6:7] op_sel_hi:[0,1]
	v_pk_mul_f32 v[4:5], v[188:189], v[4:5] op_sel_hi:[0,1]
	v_pk_mul_f32 v[2:3], v[188:189], v[2:3] op_sel_hi:[0,1]
	v_pk_mul_f32 v[0:1], v[188:189], v[0:1] op_sel_hi:[0,1]
	s_cmp_gt_i32 s14, 4
	s_mov_b64 s[0:1], -1
	s_cbranch_scc0 .LBB0_1243
	s_cmp_lg_u32 s14, 5
	s_cbranch_scc0 .LBB0_1216
	s_cmp_gt_u32 s14, 9
	s_cbranch_scc0 .LBB0_1213
	s_cmp_gt_u32 s14, 17
	s_cbranch_scc0 .LBB0_1210
	s_cmp_gt_u32 s14, 21
	s_cbranch_scc0 .LBB0_1207
	s_cmp_gt_u32 s14, 25
	s_cbranch_scc0 .LBB0_1188
	v_readlane_b32 s0, v255, 19
	v_lshl_add_u32 v152, s14, 8, v175
	v_readlane_b32 s1, v255, 20
	s_movk_i32 s5, 0x1800
	s_nop 0
	v_lshl_add_u64 v[132:133], v[152:153], 2, s[0:1]
	global_load_dwordx4 v[136:139], v[132:133], off offset:16
	global_load_dwordx4 v[140:143], v[132:133], off
	global_load_dwordx4 v[128:131], v[132:133], off offset:528
	s_nop 0
	global_load_dwordx4 v[132:135], v[132:133], off offset:512
	v_readlane_b32 s0, v255, 17
	v_readlane_b32 s1, v255, 18
	s_waitcnt vmcnt(3)
	v_pk_add_f32 v[200:201], v[116:117], v[136:137]
	s_waitcnt vmcnt(2)
	v_pk_add_f32 v[198:199], v[112:113], v[140:141]
	v_pk_add_f32 v[196:197], v[114:115], v[142:143]
	v_mul_f32_e32 v189, 0xbfb8aa3b, v198
	v_exp_f32_e32 v189, v189
	v_mov_b64_e32 v[192:193], s[0:1]
	v_mad_i64_i32 v[194:195], s[0:1], v190, s5, v[192:193]
	v_add_f32_e32 v189, 1.0, v189
	v_rcp_f32_e32 v198, v189
	v_mul_f32_e32 v189, 0xbfb8aa3b, v199
	v_exp_f32_e32 v189, v189
	v_lshl_add_u64 v[194:195], v[194:195], 0, v[152:153]
	v_add_f32_e32 v189, 1.0, v189
	v_rcp_f32_e32 v199, v189
	v_mul_f32_e32 v189, 0xbfb8aa3b, v196
	v_exp_f32_e32 v189, v189
	v_pk_fma_f32 v[198:199], v[198:199], s[94:95], 0.5 op_sel_hi:[1,0,0]
	v_add_f32_e32 v189, 1.0, v189
	v_rcp_f32_e32 v196, v189
	v_mul_f32_e32 v189, 0xbfb8aa3b, v197
	v_exp_f32_e32 v189, v189
	s_nop 0
	v_add_f32_e32 v189, 1.0, v189
	v_rcp_f32_e32 v197, v189
	v_cvt_u32_f32_e32 v189, v198
	v_cvt_u32_f32_e32 v198, v199
	v_pk_fma_f32 v[196:197], v[196:197], s[94:95], 0.5 op_sel_hi:[1,0,0]
	s_nop 0
	v_cvt_u32_f32_sdwa v196, v196 dst_sel:WORD_1 dst_unused:UNUSED_PAD src0_sel:DWORD
	v_cvt_u32_f32_sdwa v197, v197 dst_sel:BYTE_3 dst_unused:UNUSED_PAD src0_sel:DWORD
	v_lshl_or_b32 v189, v198, 8, v189
	v_pk_add_f32 v[198:199], v[118:119], v[138:139]
	v_or3_b32 v196, v189, v196, v197
	v_mul_f32_e32 v189, 0xbfb8aa3b, v200
	v_exp_f32_e32 v189, v189
	s_nop 0
	v_add_f32_e32 v189, 1.0, v189
	v_rcp_f32_e32 v200, v189
	v_mul_f32_e32 v189, 0xbfb8aa3b, v201
	v_exp_f32_e32 v189, v189
	s_nop 0
	v_add_f32_e32 v189, 1.0, v189
	v_rcp_f32_e32 v201, v189
	v_mul_f32_e32 v189, 0xbfb8aa3b, v198
	v_exp_f32_e32 v189, v189
	v_pk_fma_f32 v[200:201], v[200:201], s[94:95], 0.5 op_sel_hi:[1,0,0]
	s_nop 0
	v_cvt_u32_f32_e32 v197, v201
	v_add_f32_e32 v189, 1.0, v189
	v_rcp_f32_e32 v198, v189
	v_mul_f32_e32 v189, 0xbfb8aa3b, v199
	v_exp_f32_e32 v189, v189
	s_nop 0
	v_add_f32_e32 v189, 1.0, v189
	v_rcp_f32_e32 v199, v189
	v_cvt_u32_f32_e32 v189, v200
	s_waitcnt vmcnt(1)
	v_pk_add_f32 v[200:201], v[126:127], v[130:131]
	v_pk_fma_f32 v[198:199], v[198:199], s[94:95], 0.5 op_sel_hi:[1,0,0]
	v_lshl_or_b32 v189, v197, 8, v189
	v_cvt_u32_f32_sdwa v197, v198 dst_sel:WORD_1 dst_unused:UNUSED_PAD src0_sel:DWORD
	v_cvt_u32_f32_sdwa v198, v199 dst_sel:BYTE_3 dst_unused:UNUSED_PAD src0_sel:DWORD
	s_nop 0
	v_or3_b32 v197, v189, v197, v198
	s_waitcnt vmcnt(0)
	v_pk_add_f32 v[198:199], v[120:121], v[132:133]
	global_store_dwordx2 v[194:195], v[196:197], off
	v_mul_f32_e32 v189, 0xbfb8aa3b, v198
	v_exp_f32_e32 v189, v189
	v_pk_add_f32 v[196:197], v[122:123], v[134:135]
	v_add_f32_e32 v189, 1.0, v189
	v_rcp_f32_e32 v198, v189
	v_mul_f32_e32 v189, 0xbfb8aa3b, v199
	v_exp_f32_e32 v189, v189
	s_nop 0
	v_add_f32_e32 v189, 1.0, v189
	v_rcp_f32_e32 v199, v189
	v_mul_f32_e32 v189, 0xbfb8aa3b, v196
	v_exp_f32_e32 v189, v189
	v_pk_fma_f32 v[198:199], v[198:199], s[94:95], 0.5 op_sel_hi:[1,0,0]
	v_add_f32_e32 v189, 1.0, v189
	v_rcp_f32_e32 v196, v189
	v_mul_f32_e32 v189, 0xbfb8aa3b, v197
	v_exp_f32_e32 v189, v189
	s_nop 0
	v_add_f32_e32 v189, 1.0, v189
	v_rcp_f32_e32 v197, v189
	v_cvt_u32_f32_e32 v189, v198
	v_cvt_u32_f32_e32 v198, v199
	v_pk_fma_f32 v[196:197], v[196:197], s[94:95], 0.5 op_sel_hi:[1,0,0]
	s_nop 0
	v_cvt_u32_f32_sdwa v196, v196 dst_sel:WORD_1 dst_unused:UNUSED_PAD src0_sel:DWORD
	v_cvt_u32_f32_sdwa v197, v197 dst_sel:BYTE_3 dst_unused:UNUSED_PAD src0_sel:DWORD
	v_lshl_or_b32 v189, v198, 8, v189
	v_pk_add_f32 v[198:199], v[124:125], v[128:129]
	v_or3_b32 v196, v189, v196, v197
	v_mul_f32_e32 v189, 0xbfb8aa3b, v198
	v_exp_f32_e32 v189, v189
	s_nop 0
	v_add_f32_e32 v189, 1.0, v189
	v_rcp_f32_e32 v198, v189
	v_mul_f32_e32 v189, 0xbfb8aa3b, v199
	v_exp_f32_e32 v189, v189
	s_nop 0
	v_add_f32_e32 v189, 1.0, v189
	v_rcp_f32_e32 v199, v189
	v_mul_f32_e32 v189, 0xbfb8aa3b, v200
	v_exp_f32_e32 v189, v189
	v_pk_fma_f32 v[198:199], v[198:199], s[94:95], 0.5 op_sel_hi:[1,0,0]
	s_nop 0
	v_cvt_u32_f32_e32 v197, v199
	v_add_f32_e32 v189, 1.0, v189
	v_rcp_f32_e32 v200, v189
	v_mul_f32_e32 v189, 0xbfb8aa3b, v201
	v_exp_f32_e32 v189, v189
	s_nop 0
	v_add_f32_e32 v189, 1.0, v189
	v_rcp_f32_e32 v201, v189
	v_cvt_u32_f32_e32 v189, v198
	v_pk_fma_f32 v[200:201], v[200:201], s[94:95], 0.5 op_sel_hi:[1,0,0]
	v_lshl_or_b32 v189, v197, 8, v189
	v_cvt_u32_f32_sdwa v197, v200 dst_sel:WORD_1 dst_unused:UNUSED_PAD src0_sel:DWORD
	v_cvt_u32_f32_sdwa v198, v201 dst_sel:BYTE_3 dst_unused:UNUSED_PAD src0_sel:DWORD
	v_pk_add_f32 v[200:201], v[104:105], v[136:137]
	v_or3_b32 v197, v189, v197, v198
	v_or_b32_e32 v189, 16, v190
	v_pk_add_f32 v[198:199], v[108:109], v[140:141]
	global_store_dwordx2 v[194:195], v[196:197], off offset:128
	v_mad_i64_i32 v[194:195], s[0:1], v189, s5, v[192:193]
	v_mul_f32_e32 v189, 0xbfb8aa3b, v198
	v_exp_f32_e32 v189, v189
	v_pk_add_f32 v[196:197], v[110:111], v[142:143]
	v_lshl_add_u64 v[194:195], v[194:195], 0, v[152:153]
	v_add_f32_e32 v189, 1.0, v189
	v_rcp_f32_e32 v198, v189
	v_mul_f32_e32 v189, 0xbfb8aa3b, v199
	v_exp_f32_e32 v189, v189
	s_nop 0
	v_add_f32_e32 v189, 1.0, v189
	v_rcp_f32_e32 v199, v189
	v_mul_f32_e32 v189, 0xbfb8aa3b, v196
	v_exp_f32_e32 v189, v189
	v_pk_fma_f32 v[198:199], v[198:199], s[94:95], 0.5 op_sel_hi:[1,0,0]
	v_add_f32_e32 v189, 1.0, v189
	v_rcp_f32_e32 v196, v189
	v_mul_f32_e32 v189, 0xbfb8aa3b, v197
	v_exp_f32_e32 v189, v189
	s_nop 0
	v_add_f32_e32 v189, 1.0, v189
	v_rcp_f32_e32 v197, v189
	v_cvt_u32_f32_e32 v189, v198
	v_cvt_u32_f32_e32 v198, v199
	v_pk_fma_f32 v[196:197], v[196:197], s[94:95], 0.5 op_sel_hi:[1,0,0]
	s_nop 0
	v_cvt_u32_f32_sdwa v196, v196 dst_sel:WORD_1 dst_unused:UNUSED_PAD src0_sel:DWORD
	v_cvt_u32_f32_sdwa v197, v197 dst_sel:BYTE_3 dst_unused:UNUSED_PAD src0_sel:DWORD
	v_lshl_or_b32 v189, v198, 8, v189
	v_pk_add_f32 v[198:199], v[106:107], v[138:139]
	v_or3_b32 v196, v189, v196, v197
	v_mul_f32_e32 v189, 0xbfb8aa3b, v200
	v_exp_f32_e32 v189, v189
	s_nop 0
	v_add_f32_e32 v189, 1.0, v189
	v_rcp_f32_e32 v200, v189
	v_mul_f32_e32 v189, 0xbfb8aa3b, v201
	v_exp_f32_e32 v189, v189
	s_nop 0
	v_add_f32_e32 v189, 1.0, v189
	v_rcp_f32_e32 v201, v189
	v_mul_f32_e32 v189, 0xbfb8aa3b, v198
	v_exp_f32_e32 v189, v189
	v_pk_fma_f32 v[200:201], v[200:201], s[94:95], 0.5 op_sel_hi:[1,0,0]
	s_nop 0
	v_cvt_u32_f32_e32 v197, v201
	v_add_f32_e32 v189, 1.0, v189
	v_rcp_f32_e32 v198, v189
	v_mul_f32_e32 v189, 0xbfb8aa3b, v199
	v_exp_f32_e32 v189, v189
	s_nop 0
	v_add_f32_e32 v189, 1.0, v189
	v_rcp_f32_e32 v199, v189
	v_cvt_u32_f32_e32 v189, v200
	v_pk_add_f32 v[200:201], v[96:97], v[128:129]
	v_pk_fma_f32 v[198:199], v[198:199], s[94:95], 0.5 op_sel_hi:[1,0,0]
	v_lshl_or_b32 v189, v197, 8, v189
	v_cvt_u32_f32_sdwa v197, v198 dst_sel:WORD_1 dst_unused:UNUSED_PAD src0_sel:DWORD
	v_cvt_u32_f32_sdwa v198, v199 dst_sel:BYTE_3 dst_unused:UNUSED_PAD src0_sel:DWORD
	s_nop 0
	v_or3_b32 v197, v189, v197, v198
	v_pk_add_f32 v[198:199], v[100:101], v[132:133]
	global_store_dwordx2 v[194:195], v[196:197], off
	v_mul_f32_e32 v189, 0xbfb8aa3b, v198
	v_exp_f32_e32 v189, v189
	v_pk_add_f32 v[196:197], v[102:103], v[134:135]
	v_add_f32_e32 v189, 1.0, v189
	v_rcp_f32_e32 v198, v189
	v_mul_f32_e32 v189, 0xbfb8aa3b, v199
	v_exp_f32_e32 v189, v189
	s_nop 0
	v_add_f32_e32 v189, 1.0, v189
	v_rcp_f32_e32 v199, v189
	v_mul_f32_e32 v189, 0xbfb8aa3b, v196
	v_exp_f32_e32 v189, v189
	v_pk_fma_f32 v[198:199], v[198:199], s[94:95], 0.5 op_sel_hi:[1,0,0]
	v_add_f32_e32 v189, 1.0, v189
	v_rcp_f32_e32 v196, v189
	v_mul_f32_e32 v189, 0xbfb8aa3b, v197
	v_exp_f32_e32 v189, v189
	s_nop 0
	v_add_f32_e32 v189, 1.0, v189
	v_rcp_f32_e32 v197, v189
	v_cvt_u32_f32_e32 v189, v198
	v_cvt_u32_f32_e32 v198, v199
	v_pk_fma_f32 v[196:197], v[196:197], s[94:95], 0.5 op_sel_hi:[1,0,0]
	s_nop 0
	v_cvt_u32_f32_sdwa v196, v196 dst_sel:WORD_1 dst_unused:UNUSED_PAD src0_sel:DWORD
	v_cvt_u32_f32_sdwa v197, v197 dst_sel:BYTE_3 dst_unused:UNUSED_PAD src0_sel:DWORD
	v_lshl_or_b32 v189, v198, 8, v189
	v_pk_add_f32 v[198:199], v[98:99], v[130:131]
	v_or3_b32 v196, v189, v196, v197
	v_mul_f32_e32 v189, 0xbfb8aa3b, v200
	v_exp_f32_e32 v189, v189
	s_nop 0
	v_add_f32_e32 v189, 1.0, v189
	v_rcp_f32_e32 v200, v189
	v_mul_f32_e32 v189, 0xbfb8aa3b, v201
	v_exp_f32_e32 v189, v189
	s_nop 0
	v_add_f32_e32 v189, 1.0, v189
	v_rcp_f32_e32 v201, v189
	v_mul_f32_e32 v189, 0xbfb8aa3b, v198
	v_exp_f32_e32 v189, v189
	v_pk_fma_f32 v[200:201], v[200:201], s[94:95], 0.5 op_sel_hi:[1,0,0]
	s_nop 0
	v_cvt_u32_f32_e32 v197, v201
	v_add_f32_e32 v189, 1.0, v189
	v_rcp_f32_e32 v198, v189
	v_mul_f32_e32 v189, 0xbfb8aa3b, v199
	v_exp_f32_e32 v189, v189
	s_nop 0
	v_add_f32_e32 v189, 1.0, v189
	v_rcp_f32_e32 v199, v189
	v_cvt_u32_f32_e32 v189, v200
	v_pk_add_f32 v[200:201], v[88:89], v[136:137]
	v_pk_fma_f32 v[198:199], v[198:199], s[94:95], 0.5 op_sel_hi:[1,0,0]
	v_lshl_or_b32 v189, v197, 8, v189
	v_cvt_u32_f32_sdwa v197, v198 dst_sel:WORD_1 dst_unused:UNUSED_PAD src0_sel:DWORD
	v_cvt_u32_f32_sdwa v198, v199 dst_sel:BYTE_3 dst_unused:UNUSED_PAD src0_sel:DWORD
	s_nop 0
	v_or3_b32 v197, v189, v197, v198
	v_or_b32_e32 v189, 32, v190
	v_pk_add_f32 v[198:199], v[92:93], v[140:141]
	global_store_dwordx2 v[194:195], v[196:197], off offset:128
	v_mad_i64_i32 v[194:195], s[0:1], v189, s5, v[192:193]
	v_mul_f32_e32 v189, 0xbfb8aa3b, v198
	v_exp_f32_e32 v189, v189
	v_pk_add_f32 v[196:197], v[94:95], v[142:143]
	v_lshl_add_u64 v[194:195], v[194:195], 0, v[152:153]
	v_add_f32_e32 v189, 1.0, v189
	v_rcp_f32_e32 v198, v189
	v_mul_f32_e32 v189, 0xbfb8aa3b, v199
	v_exp_f32_e32 v189, v189
	s_nop 0
	v_add_f32_e32 v189, 1.0, v189
	v_rcp_f32_e32 v199, v189
	v_mul_f32_e32 v189, 0xbfb8aa3b, v196
	v_exp_f32_e32 v189, v189
	v_pk_fma_f32 v[198:199], v[198:199], s[94:95], 0.5 op_sel_hi:[1,0,0]
	v_add_f32_e32 v189, 1.0, v189
	v_rcp_f32_e32 v196, v189
	v_mul_f32_e32 v189, 0xbfb8aa3b, v197
	v_exp_f32_e32 v189, v189
	s_nop 0
	v_add_f32_e32 v189, 1.0, v189
	v_rcp_f32_e32 v197, v189
	v_cvt_u32_f32_e32 v189, v198
	v_cvt_u32_f32_e32 v198, v199
	v_pk_fma_f32 v[196:197], v[196:197], s[94:95], 0.5 op_sel_hi:[1,0,0]
	s_nop 0
	v_cvt_u32_f32_sdwa v196, v196 dst_sel:WORD_1 dst_unused:UNUSED_PAD src0_sel:DWORD
	v_cvt_u32_f32_sdwa v197, v197 dst_sel:BYTE_3 dst_unused:UNUSED_PAD src0_sel:DWORD
	v_lshl_or_b32 v189, v198, 8, v189
	v_pk_add_f32 v[198:199], v[90:91], v[138:139]
	v_or3_b32 v196, v189, v196, v197
	v_mul_f32_e32 v189, 0xbfb8aa3b, v200
	v_exp_f32_e32 v189, v189
	s_nop 0
	v_add_f32_e32 v189, 1.0, v189
	v_rcp_f32_e32 v200, v189
	v_mul_f32_e32 v189, 0xbfb8aa3b, v201
	v_exp_f32_e32 v189, v189
	s_nop 0
	v_add_f32_e32 v189, 1.0, v189
	v_rcp_f32_e32 v201, v189
	v_mul_f32_e32 v189, 0xbfb8aa3b, v198
	v_exp_f32_e32 v189, v189
	v_pk_fma_f32 v[200:201], v[200:201], s[94:95], 0.5 op_sel_hi:[1,0,0]
	s_nop 0
	v_cvt_u32_f32_e32 v197, v201
	v_add_f32_e32 v189, 1.0, v189
	v_rcp_f32_e32 v198, v189
	v_mul_f32_e32 v189, 0xbfb8aa3b, v199
	v_exp_f32_e32 v189, v189
	s_nop 0
	v_add_f32_e32 v189, 1.0, v189
	v_rcp_f32_e32 v199, v189
	v_cvt_u32_f32_e32 v189, v200
	v_pk_add_f32 v[200:201], v[80:81], v[128:129]
	v_pk_fma_f32 v[198:199], v[198:199], s[94:95], 0.5 op_sel_hi:[1,0,0]
	v_lshl_or_b32 v189, v197, 8, v189
	v_cvt_u32_f32_sdwa v197, v198 dst_sel:WORD_1 dst_unused:UNUSED_PAD src0_sel:DWORD
	v_cvt_u32_f32_sdwa v198, v199 dst_sel:BYTE_3 dst_unused:UNUSED_PAD src0_sel:DWORD
	s_nop 0
	v_or3_b32 v197, v189, v197, v198
	v_pk_add_f32 v[198:199], v[84:85], v[132:133]
	global_store_dwordx2 v[194:195], v[196:197], off
	v_mul_f32_e32 v189, 0xbfb8aa3b, v198
	v_exp_f32_e32 v189, v189
	v_pk_add_f32 v[196:197], v[86:87], v[134:135]
	v_add_f32_e32 v189, 1.0, v189
	v_rcp_f32_e32 v198, v189
	v_mul_f32_e32 v189, 0xbfb8aa3b, v199
	v_exp_f32_e32 v189, v189
	s_nop 0
	v_add_f32_e32 v189, 1.0, v189
	v_rcp_f32_e32 v199, v189
	v_mul_f32_e32 v189, 0xbfb8aa3b, v196
	v_exp_f32_e32 v189, v189
	v_pk_fma_f32 v[198:199], v[198:199], s[94:95], 0.5 op_sel_hi:[1,0,0]
	v_add_f32_e32 v189, 1.0, v189
	v_rcp_f32_e32 v196, v189
	v_mul_f32_e32 v189, 0xbfb8aa3b, v197
	v_exp_f32_e32 v189, v189
	s_nop 0
	v_add_f32_e32 v189, 1.0, v189
	v_rcp_f32_e32 v197, v189
	v_cvt_u32_f32_e32 v189, v198
	v_cvt_u32_f32_e32 v198, v199
	v_pk_fma_f32 v[196:197], v[196:197], s[94:95], 0.5 op_sel_hi:[1,0,0]
	s_nop 0
	v_cvt_u32_f32_sdwa v196, v196 dst_sel:WORD_1 dst_unused:UNUSED_PAD src0_sel:DWORD
	v_cvt_u32_f32_sdwa v197, v197 dst_sel:BYTE_3 dst_unused:UNUSED_PAD src0_sel:DWORD
	v_lshl_or_b32 v189, v198, 8, v189
	v_pk_add_f32 v[198:199], v[82:83], v[130:131]
	v_or3_b32 v196, v189, v196, v197
	v_mul_f32_e32 v189, 0xbfb8aa3b, v200
	v_exp_f32_e32 v189, v189
	s_nop 0
	v_add_f32_e32 v189, 1.0, v189
	v_rcp_f32_e32 v200, v189
	v_mul_f32_e32 v189, 0xbfb8aa3b, v201
	v_exp_f32_e32 v189, v189
	s_nop 0
	v_add_f32_e32 v189, 1.0, v189
	v_rcp_f32_e32 v201, v189
	v_mul_f32_e32 v189, 0xbfb8aa3b, v198
	v_exp_f32_e32 v189, v189
	v_pk_fma_f32 v[200:201], v[200:201], s[94:95], 0.5 op_sel_hi:[1,0,0]
	s_nop 0
	v_cvt_u32_f32_e32 v197, v201
	v_add_f32_e32 v189, 1.0, v189
	v_rcp_f32_e32 v198, v189
	v_mul_f32_e32 v189, 0xbfb8aa3b, v199
	v_exp_f32_e32 v189, v189
	s_nop 0
	v_add_f32_e32 v189, 1.0, v189
	v_rcp_f32_e32 v199, v189
	v_cvt_u32_f32_e32 v189, v200
	v_pk_add_f32 v[200:201], v[72:73], v[136:137]
	v_pk_fma_f32 v[198:199], v[198:199], s[94:95], 0.5 op_sel_hi:[1,0,0]
	v_lshl_or_b32 v189, v197, 8, v189
	v_cvt_u32_f32_sdwa v197, v198 dst_sel:WORD_1 dst_unused:UNUSED_PAD src0_sel:DWORD
	v_cvt_u32_f32_sdwa v198, v199 dst_sel:BYTE_3 dst_unused:UNUSED_PAD src0_sel:DWORD
	s_nop 0
	v_or3_b32 v197, v189, v197, v198
	v_or_b32_e32 v189, 48, v190
	v_pk_add_f32 v[198:199], v[76:77], v[140:141]
	global_store_dwordx2 v[194:195], v[196:197], off offset:128
	v_mad_i64_i32 v[194:195], s[0:1], v189, s5, v[192:193]
	v_mul_f32_e32 v189, 0xbfb8aa3b, v198
	v_exp_f32_e32 v189, v189
	v_pk_add_f32 v[196:197], v[78:79], v[142:143]
	v_lshl_add_u64 v[194:195], v[194:195], 0, v[152:153]
	v_add_f32_e32 v189, 1.0, v189
	v_rcp_f32_e32 v198, v189
	v_mul_f32_e32 v189, 0xbfb8aa3b, v199
	v_exp_f32_e32 v189, v189
	s_nop 0
	v_add_f32_e32 v189, 1.0, v189
	v_rcp_f32_e32 v199, v189
	v_mul_f32_e32 v189, 0xbfb8aa3b, v196
	v_exp_f32_e32 v189, v189
	v_pk_fma_f32 v[198:199], v[198:199], s[94:95], 0.5 op_sel_hi:[1,0,0]
	v_add_f32_e32 v189, 1.0, v189
	v_rcp_f32_e32 v196, v189
	v_mul_f32_e32 v189, 0xbfb8aa3b, v197
	v_exp_f32_e32 v189, v189
	s_nop 0
	v_add_f32_e32 v189, 1.0, v189
	v_rcp_f32_e32 v197, v189
	v_cvt_u32_f32_e32 v189, v198
	v_cvt_u32_f32_e32 v198, v199
	v_pk_fma_f32 v[196:197], v[196:197], s[94:95], 0.5 op_sel_hi:[1,0,0]
	s_nop 0
	v_cvt_u32_f32_sdwa v196, v196 dst_sel:WORD_1 dst_unused:UNUSED_PAD src0_sel:DWORD
	v_cvt_u32_f32_sdwa v197, v197 dst_sel:BYTE_3 dst_unused:UNUSED_PAD src0_sel:DWORD
	v_lshl_or_b32 v189, v198, 8, v189
	v_pk_add_f32 v[198:199], v[74:75], v[138:139]
	v_or3_b32 v196, v189, v196, v197
	v_mul_f32_e32 v189, 0xbfb8aa3b, v200
	v_exp_f32_e32 v189, v189
	s_nop 0
	v_add_f32_e32 v189, 1.0, v189
	v_rcp_f32_e32 v200, v189
	v_mul_f32_e32 v189, 0xbfb8aa3b, v201
	v_exp_f32_e32 v189, v189
	s_nop 0
	v_add_f32_e32 v189, 1.0, v189
	v_rcp_f32_e32 v201, v189
	v_mul_f32_e32 v189, 0xbfb8aa3b, v198
	v_exp_f32_e32 v189, v189
	v_pk_fma_f32 v[200:201], v[200:201], s[94:95], 0.5 op_sel_hi:[1,0,0]
	s_nop 0
	v_cvt_u32_f32_e32 v197, v201
	v_add_f32_e32 v189, 1.0, v189
	v_rcp_f32_e32 v198, v189
	v_mul_f32_e32 v189, 0xbfb8aa3b, v199
	v_exp_f32_e32 v189, v189
	s_nop 0
	v_add_f32_e32 v189, 1.0, v189
	v_rcp_f32_e32 v199, v189
	v_cvt_u32_f32_e32 v189, v200
	v_pk_add_f32 v[200:201], v[64:65], v[128:129]
	v_pk_fma_f32 v[198:199], v[198:199], s[94:95], 0.5 op_sel_hi:[1,0,0]
	v_lshl_or_b32 v189, v197, 8, v189
	v_cvt_u32_f32_sdwa v197, v198 dst_sel:WORD_1 dst_unused:UNUSED_PAD src0_sel:DWORD
	v_cvt_u32_f32_sdwa v198, v199 dst_sel:BYTE_3 dst_unused:UNUSED_PAD src0_sel:DWORD
	s_nop 0
	v_or3_b32 v197, v189, v197, v198
	v_pk_add_f32 v[198:199], v[68:69], v[132:133]
	global_store_dwordx2 v[194:195], v[196:197], off
	v_mul_f32_e32 v189, 0xbfb8aa3b, v198
	v_exp_f32_e32 v189, v189
	v_pk_add_f32 v[196:197], v[70:71], v[134:135]
	v_add_f32_e32 v189, 1.0, v189
	v_rcp_f32_e32 v198, v189
	v_mul_f32_e32 v189, 0xbfb8aa3b, v199
	v_exp_f32_e32 v189, v189
	s_nop 0
	v_add_f32_e32 v189, 1.0, v189
	v_rcp_f32_e32 v199, v189
	v_mul_f32_e32 v189, 0xbfb8aa3b, v196
	v_exp_f32_e32 v189, v189
	v_pk_fma_f32 v[198:199], v[198:199], s[94:95], 0.5 op_sel_hi:[1,0,0]
	v_add_f32_e32 v189, 1.0, v189
	v_rcp_f32_e32 v196, v189
	v_mul_f32_e32 v189, 0xbfb8aa3b, v197
	v_exp_f32_e32 v189, v189
	s_nop 0
	v_add_f32_e32 v189, 1.0, v189
	v_rcp_f32_e32 v197, v189
	v_cvt_u32_f32_e32 v189, v198
	v_cvt_u32_f32_e32 v198, v199
	v_pk_fma_f32 v[196:197], v[196:197], s[94:95], 0.5 op_sel_hi:[1,0,0]
	s_nop 0
	v_cvt_u32_f32_sdwa v196, v196 dst_sel:WORD_1 dst_unused:UNUSED_PAD src0_sel:DWORD
	v_cvt_u32_f32_sdwa v197, v197 dst_sel:BYTE_3 dst_unused:UNUSED_PAD src0_sel:DWORD
	v_lshl_or_b32 v189, v198, 8, v189
	v_pk_add_f32 v[198:199], v[66:67], v[130:131]
	v_or3_b32 v196, v189, v196, v197
	v_mul_f32_e32 v189, 0xbfb8aa3b, v200
	v_exp_f32_e32 v189, v189
	s_nop 0
	v_add_f32_e32 v189, 1.0, v189
	v_rcp_f32_e32 v200, v189
	v_mul_f32_e32 v189, 0xbfb8aa3b, v201
	v_exp_f32_e32 v189, v189
	s_nop 0
	v_add_f32_e32 v189, 1.0, v189
	v_rcp_f32_e32 v201, v189
	v_mul_f32_e32 v189, 0xbfb8aa3b, v198
	v_exp_f32_e32 v189, v189
	v_pk_fma_f32 v[200:201], v[200:201], s[94:95], 0.5 op_sel_hi:[1,0,0]
	s_nop 0
	v_cvt_u32_f32_e32 v197, v201
	v_add_f32_e32 v189, 1.0, v189
	v_rcp_f32_e32 v198, v189
	v_mul_f32_e32 v189, 0xbfb8aa3b, v199
	v_exp_f32_e32 v189, v189
	s_nop 0
	v_add_f32_e32 v189, 1.0, v189
	v_rcp_f32_e32 v199, v189
	v_cvt_u32_f32_e32 v189, v200
	v_pk_add_f32 v[200:201], v[56:57], v[136:137]
	v_pk_fma_f32 v[198:199], v[198:199], s[94:95], 0.5 op_sel_hi:[1,0,0]
	v_lshl_or_b32 v189, v197, 8, v189
	v_cvt_u32_f32_sdwa v197, v198 dst_sel:WORD_1 dst_unused:UNUSED_PAD src0_sel:DWORD
	v_cvt_u32_f32_sdwa v198, v199 dst_sel:BYTE_3 dst_unused:UNUSED_PAD src0_sel:DWORD
	s_nop 0
	v_or3_b32 v197, v189, v197, v198
	v_add_u32_e32 v189, 0x80, v190
	v_pk_add_f32 v[198:199], v[60:61], v[140:141]
	global_store_dwordx2 v[194:195], v[196:197], off offset:128
	v_mad_i64_i32 v[194:195], s[0:1], v189, s5, v[192:193]
	v_mul_f32_e32 v189, 0xbfb8aa3b, v198
	v_exp_f32_e32 v189, v189
	v_pk_add_f32 v[196:197], v[62:63], v[142:143]
	v_lshl_add_u64 v[194:195], v[194:195], 0, v[152:153]
	v_add_f32_e32 v189, 1.0, v189
	v_rcp_f32_e32 v198, v189
	v_mul_f32_e32 v189, 0xbfb8aa3b, v199
	v_exp_f32_e32 v189, v189
	s_nop 0
	v_add_f32_e32 v189, 1.0, v189
	v_rcp_f32_e32 v199, v189
	v_mul_f32_e32 v189, 0xbfb8aa3b, v196
	v_exp_f32_e32 v189, v189
	v_pk_fma_f32 v[198:199], v[198:199], s[94:95], 0.5 op_sel_hi:[1,0,0]
	v_add_f32_e32 v189, 1.0, v189
	v_rcp_f32_e32 v196, v189
	v_mul_f32_e32 v189, 0xbfb8aa3b, v197
	v_exp_f32_e32 v189, v189
	s_nop 0
	v_add_f32_e32 v189, 1.0, v189
	v_rcp_f32_e32 v197, v189
	v_cvt_u32_f32_e32 v189, v198
	v_cvt_u32_f32_e32 v198, v199
	v_pk_fma_f32 v[196:197], v[196:197], s[94:95], 0.5 op_sel_hi:[1,0,0]
	s_nop 0
	v_cvt_u32_f32_sdwa v196, v196 dst_sel:WORD_1 dst_unused:UNUSED_PAD src0_sel:DWORD
	v_cvt_u32_f32_sdwa v197, v197 dst_sel:BYTE_3 dst_unused:UNUSED_PAD src0_sel:DWORD
	v_lshl_or_b32 v189, v198, 8, v189
	v_pk_add_f32 v[198:199], v[58:59], v[138:139]
	v_or3_b32 v196, v189, v196, v197
	v_mul_f32_e32 v189, 0xbfb8aa3b, v200
	v_exp_f32_e32 v189, v189
	s_nop 0
	v_add_f32_e32 v189, 1.0, v189
	v_rcp_f32_e32 v200, v189
	v_mul_f32_e32 v189, 0xbfb8aa3b, v201
	v_exp_f32_e32 v189, v189
	s_nop 0
	v_add_f32_e32 v189, 1.0, v189
	v_rcp_f32_e32 v201, v189
	v_mul_f32_e32 v189, 0xbfb8aa3b, v198
	v_exp_f32_e32 v189, v189
	v_pk_fma_f32 v[200:201], v[200:201], s[94:95], 0.5 op_sel_hi:[1,0,0]
	s_nop 0
	v_cvt_u32_f32_e32 v197, v201
	v_add_f32_e32 v189, 1.0, v189
	v_rcp_f32_e32 v198, v189
	v_mul_f32_e32 v189, 0xbfb8aa3b, v199
	v_exp_f32_e32 v189, v189
	s_nop 0
	v_add_f32_e32 v189, 1.0, v189
	v_rcp_f32_e32 v199, v189
	v_cvt_u32_f32_e32 v189, v200
	v_pk_add_f32 v[200:201], v[48:49], v[128:129]
	v_pk_fma_f32 v[198:199], v[198:199], s[94:95], 0.5 op_sel_hi:[1,0,0]
	v_lshl_or_b32 v189, v197, 8, v189
	v_cvt_u32_f32_sdwa v197, v198 dst_sel:WORD_1 dst_unused:UNUSED_PAD src0_sel:DWORD
	v_cvt_u32_f32_sdwa v198, v199 dst_sel:BYTE_3 dst_unused:UNUSED_PAD src0_sel:DWORD
	s_nop 0
	v_or3_b32 v197, v189, v197, v198
	v_pk_add_f32 v[198:199], v[52:53], v[132:133]
	global_store_dwordx2 v[194:195], v[196:197], off
	v_mul_f32_e32 v189, 0xbfb8aa3b, v198
	v_exp_f32_e32 v189, v189
	v_pk_add_f32 v[196:197], v[54:55], v[134:135]
	v_add_f32_e32 v189, 1.0, v189
	v_rcp_f32_e32 v198, v189
	v_mul_f32_e32 v189, 0xbfb8aa3b, v199
	v_exp_f32_e32 v189, v189
	s_nop 0
	v_add_f32_e32 v189, 1.0, v189
	v_rcp_f32_e32 v199, v189
	v_mul_f32_e32 v189, 0xbfb8aa3b, v196
	v_exp_f32_e32 v189, v189
	v_pk_fma_f32 v[198:199], v[198:199], s[94:95], 0.5 op_sel_hi:[1,0,0]
	v_add_f32_e32 v189, 1.0, v189
	v_rcp_f32_e32 v196, v189
	v_mul_f32_e32 v189, 0xbfb8aa3b, v197
	v_exp_f32_e32 v189, v189
	s_nop 0
	v_add_f32_e32 v189, 1.0, v189
	v_rcp_f32_e32 v197, v189
	v_cvt_u32_f32_e32 v189, v198
	v_cvt_u32_f32_e32 v198, v199
	v_pk_fma_f32 v[196:197], v[196:197], s[94:95], 0.5 op_sel_hi:[1,0,0]
	s_nop 0
	v_cvt_u32_f32_sdwa v196, v196 dst_sel:WORD_1 dst_unused:UNUSED_PAD src0_sel:DWORD
	v_cvt_u32_f32_sdwa v197, v197 dst_sel:BYTE_3 dst_unused:UNUSED_PAD src0_sel:DWORD
	v_lshl_or_b32 v189, v198, 8, v189
	v_pk_add_f32 v[198:199], v[50:51], v[130:131]
	v_or3_b32 v196, v189, v196, v197
	v_mul_f32_e32 v189, 0xbfb8aa3b, v200
	v_exp_f32_e32 v189, v189
	s_nop 0
	v_add_f32_e32 v189, 1.0, v189
	v_rcp_f32_e32 v200, v189
	v_mul_f32_e32 v189, 0xbfb8aa3b, v201
	v_exp_f32_e32 v189, v189
	s_nop 0
	v_add_f32_e32 v189, 1.0, v189
	v_rcp_f32_e32 v201, v189
	v_mul_f32_e32 v189, 0xbfb8aa3b, v198
	v_exp_f32_e32 v189, v189
	v_pk_fma_f32 v[200:201], v[200:201], s[94:95], 0.5 op_sel_hi:[1,0,0]
	s_nop 0
	v_cvt_u32_f32_e32 v197, v201
	v_add_f32_e32 v189, 1.0, v189
	v_rcp_f32_e32 v198, v189
	v_mul_f32_e32 v189, 0xbfb8aa3b, v199
	v_exp_f32_e32 v189, v189
	s_nop 0
	v_add_f32_e32 v189, 1.0, v189
	v_rcp_f32_e32 v199, v189
	v_cvt_u32_f32_e32 v189, v200
	v_pk_add_f32 v[200:201], v[40:41], v[136:137]
	v_pk_fma_f32 v[198:199], v[198:199], s[94:95], 0.5 op_sel_hi:[1,0,0]
	v_lshl_or_b32 v189, v197, 8, v189
	v_cvt_u32_f32_sdwa v197, v198 dst_sel:WORD_1 dst_unused:UNUSED_PAD src0_sel:DWORD
	v_cvt_u32_f32_sdwa v198, v199 dst_sel:BYTE_3 dst_unused:UNUSED_PAD src0_sel:DWORD
	s_nop 0
	v_or3_b32 v197, v189, v197, v198
	v_add_u32_e32 v189, 0x90, v190
	v_pk_add_f32 v[198:199], v[44:45], v[140:141]
	global_store_dwordx2 v[194:195], v[196:197], off offset:128
	v_mad_i64_i32 v[194:195], s[0:1], v189, s5, v[192:193]
	v_mul_f32_e32 v189, 0xbfb8aa3b, v198
	v_exp_f32_e32 v189, v189
	v_pk_add_f32 v[196:197], v[46:47], v[142:143]
	v_lshl_add_u64 v[194:195], v[194:195], 0, v[152:153]
	v_add_f32_e32 v189, 1.0, v189
	v_rcp_f32_e32 v198, v189
	v_mul_f32_e32 v189, 0xbfb8aa3b, v199
	v_exp_f32_e32 v189, v189
	s_nop 0
	v_add_f32_e32 v189, 1.0, v189
	v_rcp_f32_e32 v199, v189
	v_mul_f32_e32 v189, 0xbfb8aa3b, v196
	v_exp_f32_e32 v189, v189
	v_pk_fma_f32 v[198:199], v[198:199], s[94:95], 0.5 op_sel_hi:[1,0,0]
	v_add_f32_e32 v189, 1.0, v189
	v_rcp_f32_e32 v196, v189
	v_mul_f32_e32 v189, 0xbfb8aa3b, v197
	v_exp_f32_e32 v189, v189
	s_nop 0
	v_add_f32_e32 v189, 1.0, v189
	v_rcp_f32_e32 v197, v189
	v_cvt_u32_f32_e32 v189, v198
	v_cvt_u32_f32_e32 v198, v199
	v_pk_fma_f32 v[196:197], v[196:197], s[94:95], 0.5 op_sel_hi:[1,0,0]
	s_nop 0
	v_cvt_u32_f32_sdwa v196, v196 dst_sel:WORD_1 dst_unused:UNUSED_PAD src0_sel:DWORD
	v_cvt_u32_f32_sdwa v197, v197 dst_sel:BYTE_3 dst_unused:UNUSED_PAD src0_sel:DWORD
	v_lshl_or_b32 v189, v198, 8, v189
	v_pk_add_f32 v[198:199], v[42:43], v[138:139]
	v_or3_b32 v196, v189, v196, v197
	v_mul_f32_e32 v189, 0xbfb8aa3b, v200
	v_exp_f32_e32 v189, v189
	s_nop 0
	v_add_f32_e32 v189, 1.0, v189
	v_rcp_f32_e32 v200, v189
	v_mul_f32_e32 v189, 0xbfb8aa3b, v201
	v_exp_f32_e32 v189, v189
	s_nop 0
	v_add_f32_e32 v189, 1.0, v189
	v_rcp_f32_e32 v201, v189
	v_mul_f32_e32 v189, 0xbfb8aa3b, v198
	v_exp_f32_e32 v189, v189
	v_pk_fma_f32 v[200:201], v[200:201], s[94:95], 0.5 op_sel_hi:[1,0,0]
	s_nop 0
	v_cvt_u32_f32_e32 v197, v201
	v_add_f32_e32 v189, 1.0, v189
	v_rcp_f32_e32 v198, v189
	v_mul_f32_e32 v189, 0xbfb8aa3b, v199
	v_exp_f32_e32 v189, v189
	s_nop 0
	v_add_f32_e32 v189, 1.0, v189
	v_rcp_f32_e32 v199, v189
	v_cvt_u32_f32_e32 v189, v200
	v_pk_add_f32 v[200:201], v[32:33], v[128:129]
	v_pk_fma_f32 v[198:199], v[198:199], s[94:95], 0.5 op_sel_hi:[1,0,0]
	v_lshl_or_b32 v189, v197, 8, v189
	v_cvt_u32_f32_sdwa v197, v198 dst_sel:WORD_1 dst_unused:UNUSED_PAD src0_sel:DWORD
	v_cvt_u32_f32_sdwa v198, v199 dst_sel:BYTE_3 dst_unused:UNUSED_PAD src0_sel:DWORD
	s_nop 0
	v_or3_b32 v197, v189, v197, v198
	v_pk_add_f32 v[198:199], v[36:37], v[132:133]
	global_store_dwordx2 v[194:195], v[196:197], off
	v_mul_f32_e32 v189, 0xbfb8aa3b, v198
	v_exp_f32_e32 v189, v189
	v_pk_add_f32 v[196:197], v[38:39], v[134:135]
	v_add_f32_e32 v189, 1.0, v189
	v_rcp_f32_e32 v198, v189
	v_mul_f32_e32 v189, 0xbfb8aa3b, v199
	v_exp_f32_e32 v189, v189
	s_nop 0
	v_add_f32_e32 v189, 1.0, v189
	v_rcp_f32_e32 v199, v189
	v_mul_f32_e32 v189, 0xbfb8aa3b, v196
	v_exp_f32_e32 v189, v189
	v_pk_fma_f32 v[198:199], v[198:199], s[94:95], 0.5 op_sel_hi:[1,0,0]
	v_add_f32_e32 v189, 1.0, v189
	v_rcp_f32_e32 v196, v189
	v_mul_f32_e32 v189, 0xbfb8aa3b, v197
	v_exp_f32_e32 v189, v189
	s_nop 0
	v_add_f32_e32 v189, 1.0, v189
	v_rcp_f32_e32 v197, v189
	v_cvt_u32_f32_e32 v189, v198
	v_cvt_u32_f32_e32 v198, v199
	v_pk_fma_f32 v[196:197], v[196:197], s[94:95], 0.5 op_sel_hi:[1,0,0]
	s_nop 0
	v_cvt_u32_f32_sdwa v196, v196 dst_sel:WORD_1 dst_unused:UNUSED_PAD src0_sel:DWORD
	v_cvt_u32_f32_sdwa v197, v197 dst_sel:BYTE_3 dst_unused:UNUSED_PAD src0_sel:DWORD
	v_lshl_or_b32 v189, v198, 8, v189
	v_pk_add_f32 v[198:199], v[34:35], v[130:131]
	v_or3_b32 v196, v189, v196, v197
	v_mul_f32_e32 v189, 0xbfb8aa3b, v200
	v_exp_f32_e32 v189, v189
	s_nop 0
	v_add_f32_e32 v189, 1.0, v189
	v_rcp_f32_e32 v200, v189
	v_mul_f32_e32 v189, 0xbfb8aa3b, v201
	v_exp_f32_e32 v189, v189
	s_nop 0
	v_add_f32_e32 v189, 1.0, v189
	v_rcp_f32_e32 v201, v189
	v_mul_f32_e32 v189, 0xbfb8aa3b, v198
	v_exp_f32_e32 v189, v189
	v_pk_fma_f32 v[200:201], v[200:201], s[94:95], 0.5 op_sel_hi:[1,0,0]
	s_nop 0
	v_cvt_u32_f32_e32 v197, v201
	v_add_f32_e32 v189, 1.0, v189
	v_rcp_f32_e32 v198, v189
	v_mul_f32_e32 v189, 0xbfb8aa3b, v199
	v_exp_f32_e32 v189, v189
	s_nop 0
	v_add_f32_e32 v189, 1.0, v189
	v_rcp_f32_e32 v199, v189
	v_cvt_u32_f32_e32 v189, v200
	v_pk_add_f32 v[200:201], v[24:25], v[136:137]
	v_pk_add_f32 v[136:137], v[8:9], v[136:137]
	v_pk_fma_f32 v[198:199], v[198:199], s[94:95], 0.5 op_sel_hi:[1,0,0]
	v_lshl_or_b32 v189, v197, 8, v189
	v_cvt_u32_f32_sdwa v197, v198 dst_sel:WORD_1 dst_unused:UNUSED_PAD src0_sel:DWORD
	v_cvt_u32_f32_sdwa v198, v199 dst_sel:BYTE_3 dst_unused:UNUSED_PAD src0_sel:DWORD
	v_mul_f32_e32 v136, 0xbfb8aa3b, v136
	v_mul_f32_e32 v137, 0xbfb8aa3b, v137
	v_exp_f32_e32 v136, v136
	v_or3_b32 v197, v189, v197, v198
	v_add_u32_e32 v189, 0xa0, v190
	v_pk_add_f32 v[198:199], v[28:29], v[140:141]
	global_store_dwordx2 v[194:195], v[196:197], off offset:128
	v_mad_i64_i32 v[194:195], s[0:1], v189, s5, v[192:193]
	v_mul_f32_e32 v189, 0xbfb8aa3b, v198
	v_exp_f32_e32 v189, v189
	v_pk_add_f32 v[196:197], v[30:31], v[142:143]
	v_lshl_add_u64 v[194:195], v[194:195], 0, v[152:153]
	v_pk_add_f32 v[140:141], v[12:13], v[140:141]
	v_add_f32_e32 v189, 1.0, v189
	v_rcp_f32_e32 v198, v189
	v_mul_f32_e32 v189, 0xbfb8aa3b, v199
	v_exp_f32_e32 v189, v189
	v_mul_f32_e32 v140, 0xbfb8aa3b, v140
	v_mul_f32_e32 v141, 0xbfb8aa3b, v141
	v_exp_f32_e32 v140, v140
	v_add_f32_e32 v189, 1.0, v189
	v_rcp_f32_e32 v199, v189
	v_mul_f32_e32 v189, 0xbfb8aa3b, v196
	v_exp_f32_e32 v189, v189
	v_exp_f32_e32 v141, v141
	v_pk_fma_f32 v[198:199], v[198:199], s[94:95], 0.5 op_sel_hi:[1,0,0]
	v_exp_f32_e32 v137, v137
	v_add_f32_e32 v189, 1.0, v189
	v_rcp_f32_e32 v196, v189
	v_mul_f32_e32 v189, 0xbfb8aa3b, v197
	v_exp_f32_e32 v189, v189
	v_pk_add_f32 v[142:143], v[14:15], v[142:143]
	v_add_f32_e32 v140, 1.0, v140
	v_mul_f32_e32 v142, 0xbfb8aa3b, v142
	v_add_f32_e32 v189, 1.0, v189
	v_rcp_f32_e32 v197, v189
	v_cvt_u32_f32_e32 v189, v198
	v_cvt_u32_f32_e32 v198, v199
	v_mul_f32_e32 v143, 0xbfb8aa3b, v143
	v_pk_fma_f32 v[196:197], v[196:197], s[94:95], 0.5 op_sel_hi:[1,0,0]
	v_add_f32_e32 v141, 1.0, v141
	v_cvt_u32_f32_sdwa v196, v196 dst_sel:WORD_1 dst_unused:UNUSED_PAD src0_sel:DWORD
	v_cvt_u32_f32_sdwa v197, v197 dst_sel:BYTE_3 dst_unused:UNUSED_PAD src0_sel:DWORD
	v_lshl_or_b32 v189, v198, 8, v189
	v_pk_add_f32 v[198:199], v[26:27], v[138:139]
	v_pk_add_f32 v[138:139], v[10:11], v[138:139]
	v_or3_b32 v196, v189, v196, v197
	v_mul_f32_e32 v189, 0xbfb8aa3b, v200
	v_exp_f32_e32 v189, v189
	v_mul_f32_e32 v138, 0xbfb8aa3b, v138
	v_mul_f32_e32 v139, 0xbfb8aa3b, v139
	v_exp_f32_e32 v142, v142
	v_add_f32_e32 v189, 1.0, v189
	v_rcp_f32_e32 v200, v189
	v_mul_f32_e32 v189, 0xbfb8aa3b, v201
	v_exp_f32_e32 v189, v189
	v_exp_f32_e32 v143, v143
	v_add_f32_e32 v136, 1.0, v136
	v_add_f32_e32 v137, 1.0, v137
	v_add_f32_e32 v189, 1.0, v189
	v_rcp_f32_e32 v201, v189
	v_mul_f32_e32 v189, 0xbfb8aa3b, v198
	v_exp_f32_e32 v189, v189
	v_exp_f32_e32 v138, v138
	v_pk_fma_f32 v[200:201], v[200:201], s[94:95], 0.5 op_sel_hi:[1,0,0]
	v_exp_f32_e32 v139, v139
	v_add_f32_e32 v189, 1.0, v189
	v_rcp_f32_e32 v198, v189
	v_mul_f32_e32 v189, 0xbfb8aa3b, v199
	v_exp_f32_e32 v189, v189
	v_cvt_u32_f32_e32 v197, v201
	v_rcp_f32_e32 v140, v140
	v_rcp_f32_e32 v141, v141
	v_add_f32_e32 v189, 1.0, v189
	v_rcp_f32_e32 v199, v189
	v_cvt_u32_f32_e32 v189, v200
	v_pk_add_f32 v[200:201], v[16:17], v[128:129]
	v_pk_add_f32 v[128:129], v[0:1], v[128:129]
	v_pk_fma_f32 v[198:199], v[198:199], s[94:95], 0.5 op_sel_hi:[1,0,0]
	v_lshl_or_b32 v189, v197, 8, v189
	v_cvt_u32_f32_sdwa v197, v198 dst_sel:WORD_1 dst_unused:UNUSED_PAD src0_sel:DWORD
	v_cvt_u32_f32_sdwa v198, v199 dst_sel:BYTE_3 dst_unused:UNUSED_PAD src0_sel:DWORD
	v_mul_f32_e32 v128, 0xbfb8aa3b, v128
	v_mul_f32_e32 v129, 0xbfb8aa3b, v129
	v_exp_f32_e32 v128, v128
	v_or3_b32 v197, v189, v197, v198
	v_pk_add_f32 v[198:199], v[20:21], v[132:133]
	global_store_dwordx2 v[194:195], v[196:197], off
	v_mul_f32_e32 v189, 0xbfb8aa3b, v198
	v_exp_f32_e32 v189, v189
	v_pk_add_f32 v[196:197], v[22:23], v[134:135]
	v_pk_add_f32 v[132:133], v[4:5], v[132:133]
	v_exp_f32_e32 v129, v129
	v_add_f32_e32 v189, 1.0, v189
	v_rcp_f32_e32 v198, v189
	v_mul_f32_e32 v189, 0xbfb8aa3b, v199
	v_exp_f32_e32 v189, v189
	v_mul_f32_e32 v132, 0xbfb8aa3b, v132
	v_mul_f32_e32 v133, 0xbfb8aa3b, v133
	v_exp_f32_e32 v132, v132
	v_add_f32_e32 v189, 1.0, v189
	v_rcp_f32_e32 v199, v189
	v_mul_f32_e32 v189, 0xbfb8aa3b, v196
	v_exp_f32_e32 v189, v189
	v_exp_f32_e32 v133, v133
	v_pk_fma_f32 v[198:199], v[198:199], s[94:95], 0.5 op_sel_hi:[1,0,0]
	v_pk_add_f32 v[134:135], v[6:7], v[134:135]
	v_add_f32_e32 v189, 1.0, v189
	v_rcp_f32_e32 v196, v189
	v_mul_f32_e32 v189, 0xbfb8aa3b, v197
	v_exp_f32_e32 v189, v189
	v_mul_f32_e32 v134, 0xbfb8aa3b, v134
	v_mul_f32_e32 v135, 0xbfb8aa3b, v135
	v_add_f32_e32 v132, 1.0, v132
	v_add_f32_e32 v189, 1.0, v189
	v_rcp_f32_e32 v197, v189
	v_cvt_u32_f32_e32 v189, v198
	v_cvt_u32_f32_e32 v198, v199
	v_add_f32_e32 v133, 1.0, v133
	v_pk_fma_f32 v[196:197], v[196:197], s[94:95], 0.5 op_sel_hi:[1,0,0]
	v_exp_f32_e32 v134, v134
	v_cvt_u32_f32_sdwa v196, v196 dst_sel:WORD_1 dst_unused:UNUSED_PAD src0_sel:DWORD
	v_cvt_u32_f32_sdwa v197, v197 dst_sel:BYTE_3 dst_unused:UNUSED_PAD src0_sel:DWORD
	v_lshl_or_b32 v189, v198, 8, v189
	v_pk_add_f32 v[198:199], v[18:19], v[130:131]
	v_pk_add_f32 v[130:131], v[2:3], v[130:131]
	v_or3_b32 v196, v189, v196, v197
	v_mul_f32_e32 v189, 0xbfb8aa3b, v200
	v_exp_f32_e32 v189, v189
	v_mul_f32_e32 v130, 0xbfb8aa3b, v130
	v_mul_f32_e32 v131, 0xbfb8aa3b, v131
	v_exp_f32_e32 v135, v135
	v_add_f32_e32 v189, 1.0, v189
	v_rcp_f32_e32 v200, v189
	v_mul_f32_e32 v189, 0xbfb8aa3b, v201
	v_exp_f32_e32 v189, v189
	v_add_f32_e32 v128, 1.0, v128
	v_add_f32_e32 v129, 1.0, v129
	v_exp_f32_e32 v130, v130
	v_add_f32_e32 v189, 1.0, v189
	v_rcp_f32_e32 v201, v189
	v_mul_f32_e32 v189, 0xbfb8aa3b, v198
	v_exp_f32_e32 v189, v189
	v_exp_f32_e32 v131, v131
	v_rcp_f32_e32 v136, v136
	v_rcp_f32_e32 v137, v137
	v_add_f32_e32 v189, 1.0, v189
	v_rcp_f32_e32 v198, v189
	v_mul_f32_e32 v189, 0xbfb8aa3b, v199
	v_exp_f32_e32 v189, v189
	v_rcp_f32_e32 v132, v132
	v_rcp_f32_e32 v133, v133
	v_rcp_f32_e32 v128, v128
	v_rcp_f32_e32 v129, v129
	v_add_f32_e32 v189, 1.0, v189
	v_rcp_f32_e32 v199, v189
	v_pk_fma_f32 v[200:201], v[200:201], s[94:95], 0.5 op_sel_hi:[1,0,0]
	v_add_f32_e32 v142, 1.0, v142
	v_cvt_u32_f32_e32 v189, v200
	v_cvt_u32_f32_e32 v197, v201
	v_add_f32_e32 v143, 1.0, v143
	v_add_f32_e32 v138, 1.0, v138
	v_add_f32_e32 v139, 1.0, v139
	v_add_f32_e32 v134, 1.0, v134
	v_add_f32_e32 v135, 1.0, v135
	v_add_f32_e32 v130, 1.0, v130
	v_add_f32_e32 v131, 1.0, v131
	v_rcp_f32_e32 v142, v142
	v_rcp_f32_e32 v143, v143
	v_pk_fma_f32 v[140:141], v[140:141], s[94:95], 0.5 op_sel_hi:[1,0,0]
	v_rcp_f32_e32 v138, v138
	v_rcp_f32_e32 v139, v139
	v_pk_fma_f32 v[136:137], v[136:137], s[94:95], 0.5 op_sel_hi:[1,0,0]
	v_rcp_f32_e32 v134, v134
	v_rcp_f32_e32 v135, v135
	v_pk_fma_f32 v[132:133], v[132:133], s[94:95], 0.5 op_sel_hi:[1,0,0]
	v_rcp_f32_e32 v130, v130
	v_rcp_f32_e32 v131, v131
	v_pk_fma_f32 v[128:129], v[128:129], s[94:95], 0.5 op_sel_hi:[1,0,0]
	v_cvt_u32_f32_e32 v140, v140
	v_cvt_u32_f32_e32 v141, v141
	v_cvt_u32_f32_e32 v136, v136
	v_cvt_u32_f32_e32 v137, v137
	v_cvt_u32_f32_e32 v132, v132
	v_cvt_u32_f32_e32 v133, v133
	v_cvt_u32_f32_e32 v128, v128
	v_cvt_u32_f32_e32 v129, v129
	v_pk_fma_f32 v[198:199], v[198:199], s[94:95], 0.5 op_sel_hi:[1,0,0]
	v_lshl_or_b32 v189, v197, 8, v189
	v_cvt_u32_f32_sdwa v197, v198 dst_sel:WORD_1 dst_unused:UNUSED_PAD src0_sel:DWORD
	v_cvt_u32_f32_sdwa v198, v199 dst_sel:BYTE_3 dst_unused:UNUSED_PAD src0_sel:DWORD
	v_pk_fma_f32 v[142:143], v[142:143], s[94:95], 0.5 op_sel_hi:[1,0,0]
	v_pk_fma_f32 v[138:139], v[138:139], s[94:95], 0.5 op_sel_hi:[1,0,0]
	v_pk_fma_f32 v[134:135], v[134:135], s[94:95], 0.5 op_sel_hi:[1,0,0]
	v_pk_fma_f32 v[130:131], v[130:131], s[94:95], 0.5 op_sel_hi:[1,0,0]
	v_lshl_or_b32 v140, v141, 8, v140
	v_cvt_u32_f32_sdwa v141, v142 dst_sel:WORD_1 dst_unused:UNUSED_PAD src0_sel:DWORD
	v_cvt_u32_f32_sdwa v142, v143 dst_sel:BYTE_3 dst_unused:UNUSED_PAD src0_sel:DWORD
	v_lshl_or_b32 v136, v137, 8, v136
	v_cvt_u32_f32_sdwa v137, v138 dst_sel:WORD_1 dst_unused:UNUSED_PAD src0_sel:DWORD
	v_cvt_u32_f32_sdwa v138, v139 dst_sel:BYTE_3 dst_unused:UNUSED_PAD src0_sel:DWORD
	v_lshl_or_b32 v132, v133, 8, v132
	v_cvt_u32_f32_sdwa v133, v134 dst_sel:WORD_1 dst_unused:UNUSED_PAD src0_sel:DWORD
	v_cvt_u32_f32_sdwa v134, v135 dst_sel:BYTE_3 dst_unused:UNUSED_PAD src0_sel:DWORD
	v_lshl_or_b32 v128, v129, 8, v128
	v_cvt_u32_f32_sdwa v129, v130 dst_sel:WORD_1 dst_unused:UNUSED_PAD src0_sel:DWORD
	v_cvt_u32_f32_sdwa v130, v131 dst_sel:BYTE_3 dst_unused:UNUSED_PAD src0_sel:DWORD
	v_or3_b32 v197, v189, v197, v198
	v_add_u32_e32 v189, 0xb0, v190
	v_mad_i64_i32 v[192:193], s[0:1], v189, s5, v[192:193]
	v_lshl_add_u64 v[192:193], v[192:193], 0, v[152:153]
	v_or3_b32 v140, v140, v141, v142
	v_or3_b32 v141, v136, v137, v138
	v_or3_b32 v132, v132, v133, v134
	v_or3_b32 v133, v128, v129, v130
	global_store_dwordx2 v[194:195], v[196:197], off offset:128
	global_store_dwordx2 v[192:193], v[140:141], off
	global_store_dwordx2 v[192:193], v[132:133], off offset:128
	s_mov_b64 s[0:1], 0

.LBB0_1368:
	ds_read_b128 v[70:73], v19
	ds_read_b128 v[74:77], v19 offset:64
	v_add_u32_e32 v20, 0x900, v19
	v_cmp_gt_u32_e32 vcc, 7, v34
	s_and_b64 vcc, s[2:3], vcc
	s_waitcnt lgkmcnt(1)
	v_mfma_f32_16x16x32_bf16 v[70:73], v[70:73], v[8:11], 0
	s_waitcnt lgkmcnt(0)
	v_mfma_f32_16x16x32_bf16 v[70:73], v[74:77], v[12:15], v[70:73]
	ds_read_b128 v[74:77], v19 offset:2304
	ds_read_b128 v[78:81], v19 offset:2368
	s_waitcnt lgkmcnt(1)
	v_mfma_f32_16x16x32_bf16 v[74:77], v[74:77], v[8:11], 0
	s_waitcnt lgkmcnt(0)
	v_mfma_f32_16x16x32_bf16 v[74:77], v[78:81], v[12:15], v[74:77]
	ds_read_b128 v[78:81], v19 offset:4608
	ds_read_b128 v[82:85], v19 offset:4672
	s_waitcnt lgkmcnt(1)
	v_mfma_f32_16x16x32_bf16 v[78:81], v[78:81], v[8:11], 0
	s_waitcnt lgkmcnt(0)
	v_mfma_f32_16x16x32_bf16 v[78:81], v[82:85], v[12:15], v[78:81]
	ds_read_b128 v[82:85], v19 offset:6912
	ds_read_b128 v[86:89], v19 offset:6976
	s_waitcnt lgkmcnt(1)
	v_mfma_f32_16x16x32_bf16 v[82:85], v[82:85], v[8:11], 0
	s_waitcnt lgkmcnt(0)
	v_mfma_f32_16x16x32_bf16 v[82:85], v[86:89], v[12:15], v[82:85]
	ds_read_b128 v[86:89], v19 offset:9216
	ds_read_b128 v[90:93], v19 offset:9280
	s_waitcnt lgkmcnt(1)
	v_mfma_f32_16x16x32_bf16 v[86:89], v[86:89], v[8:11], 0
	s_waitcnt lgkmcnt(0)
	v_mfma_f32_16x16x32_bf16 v[86:89], v[90:93], v[12:15], v[86:89]
	ds_read_b128 v[90:93], v19 offset:11520
	ds_read_b128 v[94:97], v19 offset:11584
	s_waitcnt lgkmcnt(1)
	v_mfma_f32_16x16x32_bf16 v[90:93], v[90:93], v[8:11], 0
	s_waitcnt lgkmcnt(0)
	v_mfma_f32_16x16x32_bf16 v[90:93], v[94:97], v[12:15], v[90:93]
	ds_read_b128 v[94:97], v19 offset:13824
	ds_read_b128 v[98:101], v19 offset:13888
	s_waitcnt lgkmcnt(1)
	v_mfma_f32_16x16x32_bf16 v[94:97], v[94:97], v[8:11], 0
	s_waitcnt lgkmcnt(0)
	v_mfma_f32_16x16x32_bf16 v[94:97], v[98:101], v[12:15], v[94:97]
	ds_read_b128 v[98:101], v19 offset:16128
	ds_read_b128 v[102:105], v19 offset:16192
	s_waitcnt lgkmcnt(1)
	v_mfma_f32_16x16x32_bf16 v[98:101], v[98:101], v[8:11], 0
	s_waitcnt lgkmcnt(0)
	v_mfma_f32_16x16x32_bf16 v[98:101], v[102:105], v[12:15], v[98:101]
	ds_read_b128 v[102:105], v19 offset:18432
	ds_read_b128 v[106:109], v19 offset:18496
	v_add_f32_e32 v19, v40, v73
	v_cndmask_b32_e64 v19, v33, v19, s[16:17]
	s_waitcnt lgkmcnt(1)
	v_mfma_f32_16x16x32_bf16 v[8:11], v[102:105], v[8:11], 0
	v_cndmask_b32_e64 v19, v19, v33, s[2:3]
	v_add_f32_e32 v73, v44, v77
	v_cndmask_b32_e32 v73, v73, v33, vcc
	s_waitcnt lgkmcnt(0)
	v_mfma_f32_16x16x32_bf16 v[8:11], v[106:109], v[12:15], v[8:11]
	v_add_f32_e32 v12, v37, v70
	v_add_f32_e32 v13, v38, v71
	v_cndmask_b32_e64 v12, v33, v12, s[10:11]
	v_cndmask_b32_e64 v13, v33, v13, s[12:13]
	v_add_f32_e32 v15, v39, v72
	v_cndmask_b32_e64 v12, v12, v33, s[2:3]
	v_cndmask_b32_e64 v13, v13, v33, s[2:3]
	v_cndmask_b32_e64 v15, v33, v15, s[14:15]
	s_waitcnt vmcnt(2)
	v_max3_f32 v14, v24, v12, v13
	v_cndmask_b32_e64 v15, v15, v33, s[2:3]
	v_add_f32_e32 v70, v41, v74
	v_add_f32_e32 v71, v42, v75
	v_add_f32_e32 v72, v43, v76
	v_max3_f32 v14, v14, v15, v19
	v_cndmask_b32_e32 v70, v70, v33, vcc
	v_cndmask_b32_e32 v71, v71, v33, vcc
	v_cndmask_b32_e32 v72, v72, v33, vcc
	v_cmp_gt_u32_e32 vcc, 6, v34
	v_max3_f32 v14, v14, v70, v71
	s_and_b64 vcc, s[2:3], vcc
	v_add_f32_e32 v74, v45, v78
	v_add_f32_e32 v75, v46, v79
	v_add_f32_e32 v76, v47, v80
	v_add_f32_e32 v77, v48, v81
	v_max3_f32 v14, v14, v72, v73
	v_cndmask_b32_e32 v74, v74, v33, vcc
	v_cndmask_b32_e32 v75, v75, v33, vcc
	v_cndmask_b32_e32 v76, v76, v33, vcc
	v_cndmask_b32_e32 v77, v77, v33, vcc
	v_cmp_gt_u32_e32 vcc, 5, v34
	v_max3_f32 v14, v14, v74, v75
	s_and_b64 vcc, s[2:3], vcc
	v_add_f32_e32 v78, v49, v82
	v_add_f32_e32 v79, v50, v83
	v_add_f32_e32 v80, v51, v84
	v_add_f32_e32 v81, v52, v85
	v_max3_f32 v14, v14, v76, v77
	v_cndmask_b32_e32 v78, v78, v33, vcc
	v_cndmask_b32_e32 v79, v79, v33, vcc
	v_cndmask_b32_e32 v80, v80, v33, vcc
	v_cndmask_b32_e32 v81, v81, v33, vcc
	v_cmp_gt_u32_e32 vcc, 4, v34
	v_max3_f32 v14, v14, v78, v79
	s_and_b64 vcc, s[2:3], vcc
	v_add_f32_e32 v82, v53, v86
	v_add_f32_e32 v83, v54, v87
	v_add_f32_e32 v84, v55, v88
	v_add_f32_e32 v85, v56, v89
	v_max3_f32 v14, v14, v80, v81
	v_cndmask_b32_e32 v82, v82, v33, vcc
	v_cndmask_b32_e32 v83, v83, v33, vcc
	v_cndmask_b32_e32 v84, v84, v33, vcc
	v_cndmask_b32_e32 v85, v85, v33, vcc
	v_cmp_gt_u32_e32 vcc, 3, v34
	v_max3_f32 v14, v14, v82, v83
	s_and_b64 vcc, s[2:3], vcc
	v_add_f32_e32 v86, v57, v90
	v_add_f32_e32 v87, v58, v91
	v_add_f32_e32 v88, v59, v92
	v_add_f32_e32 v89, v60, v93
	v_max3_f32 v14, v14, v84, v85
	v_cndmask_b32_e32 v86, v86, v33, vcc
	v_cndmask_b32_e32 v87, v87, v33, vcc
	v_cndmask_b32_e32 v88, v88, v33, vcc
	v_cndmask_b32_e32 v89, v89, v33, vcc
	v_cmp_gt_u32_e32 vcc, 2, v34
	v_max3_f32 v14, v14, v86, v87
	s_and_b64 vcc, s[2:3], vcc
	v_add_f32_e32 v90, v61, v94
	v_add_f32_e32 v91, v62, v95
	v_max3_f32 v14, v14, v88, v89
	v_cndmask_b32_e32 v90, v90, v33, vcc
	v_cndmask_b32_e32 v91, v91, v33, vcc
	v_add_f32_e32 v92, v63, v96
	v_add_f32_e32 v93, v64, v97
	v_or_b32_e32 v94, s59, v34
	v_max3_f32 v14, v14, v90, v91
	v_cndmask_b32_e32 v92, v92, v33, vcc
	v_cndmask_b32_e32 v93, v93, v33, vcc
	v_cmp_eq_u32_e32 vcc, 0, v94
	v_add_f32_e32 v94, v65, v98
	v_add_f32_e32 v95, v66, v99
	v_max3_f32 v14, v14, v92, v93
	v_cndmask_b32_e32 v94, v94, v33, vcc
	v_cndmask_b32_e32 v95, v95, v33, vcc
	v_add_f32_e32 v96, v67, v100
	v_add_f32_e32 v97, v68, v101
	v_max3_f32 v14, v14, v94, v95
	v_cndmask_b32_e32 v96, v96, v33, vcc
	v_cndmask_b32_e32 v97, v97, v33, vcc
	v_add_f32_e32 v8, v25, v8
	v_add_f32_e32 v9, v26, v9
	v_add_f32_e32 v10, v27, v10
	v_max3_f32 v14, v14, v96, v97
	v_cndmask_b32_e64 v8, v8, v33, s[10:11]
	v_cndmask_b32_e64 v9, v9, v33, s[12:13]
	v_cndmask_b32_e64 v98, v10, v33, s[14:15]
	v_add_f32_e32 v10, v28, v11
	v_max3_f32 v14, v14, v8, v9
	v_cndmask_b32_e64 v99, v10, v33, s[16:17]
	v_max3_f32 v10, v14, v98, v99
	ds_bpermute_b32 v11, v35, v10
	s_add_u32 s50, s50, 0x8000
	s_addc_u32 s51, s51, 0
	v_add_u32_e32 v34, 1, v34
	s_cmp_lg_u32 s50, 0x20000
	s_waitcnt lgkmcnt(0)
	v_max_f32_e32 v11, v11, v11
	v_max_f32_e32 v10, v10, v11
	ds_bpermute_b32 v11, v36, v10
	s_waitcnt lgkmcnt(0)
	v_max_f32_e32 v11, v11, v11
	v_max_f32_e32 v100, v10, v11
	v_sub_f32_e32 v11, v13, v100
	v_mul_f32_e32 v11, 0x3fb8aa3b, v11
	v_exp_f32_e32 v102, v11
	v_sub_f32_e32 v11, v15, v100
	v_mul_f32_e32 v11, 0x3fb8aa3b, v11
	v_exp_f32_e32 v103, v11
	v_sub_f32_e32 v11, v19, v100
	v_mul_f32_e32 v11, 0x3fb8aa3b, v11
	v_exp_f32_e32 v104, v11
	v_sub_f32_e32 v11, v70, v100
	v_mul_f32_e32 v11, 0x3fb8aa3b, v11
	v_exp_f32_e32 v105, v11
	v_sub_f32_e32 v11, v71, v100
	v_mul_f32_e32 v11, 0x3fb8aa3b, v11
	v_exp_f32_e32 v106, v11
	v_sub_f32_e32 v11, v72, v100
	v_mul_f32_e32 v11, 0x3fb8aa3b, v11
	v_exp_f32_e32 v107, v11
	v_sub_f32_e32 v11, v73, v100
	v_mul_f32_e32 v11, 0x3fb8aa3b, v11
	v_exp_f32_e32 v73, v11
	v_sub_f32_e32 v11, v74, v100
	v_mul_f32_e32 v11, 0x3fb8aa3b, v11
	v_exp_f32_e32 v108, v11
	v_sub_f32_e32 v11, v75, v100
	v_mul_f32_e32 v11, 0x3fb8aa3b, v11
	v_exp_f32_e32 v109, v11
	v_sub_f32_e32 v11, v76, v100
	v_mul_f32_e32 v11, 0x3fb8aa3b, v11
	v_exp_f32_e32 v110, v11
	v_sub_f32_e32 v11, v77, v100
	v_mul_f32_e32 v11, 0x3fb8aa3b, v11
	v_exp_f32_e32 v111, v11
	v_sub_f32_e32 v11, v78, v100
	v_mul_f32_e32 v11, 0x3fb8aa3b, v11
	v_exp_f32_e32 v112, v11
	v_sub_f32_e32 v11, v79, v100
	v_mul_f32_e32 v11, 0x3fb8aa3b, v11
	v_exp_f32_e32 v113, v11
	v_sub_f32_e32 v11, v80, v100
	v_mul_f32_e32 v11, 0x3fb8aa3b, v11
	v_exp_f32_e32 v114, v11
	v_sub_f32_e32 v11, v81, v100
	v_sub_f32_e32 v10, v12, v100
	v_mul_f32_e32 v11, 0x3fb8aa3b, v11
	v_mul_f32_e32 v10, 0x3fb8aa3b, v10
	v_exp_f32_e32 v115, v11
	v_sub_f32_e32 v11, v82, v100
	v_exp_f32_e32 v101, v10
	v_mul_f32_e32 v11, 0x3fb8aa3b, v11
	v_exp_f32_e32 v71, v11
	v_sub_f32_e32 v11, v83, v100
	v_mul_f32_e32 v11, 0x3fb8aa3b, v11
	v_exp_f32_e32 v116, v11
	v_sub_f32_e32 v11, v84, v100
	v_add_f32_e32 v10, 0, v101
	v_mul_f32_e32 v11, 0x3fb8aa3b, v11
	v_add_f32_e32 v10, v102, v10
	v_exp_f32_e32 v117, v11
	v_sub_f32_e32 v11, v85, v100
	v_add_f32_e32 v10, v103, v10
	v_mul_f32_e32 v11, 0x3fb8aa3b, v11
	v_add_f32_e32 v10, v104, v10
	v_exp_f32_e32 v118, v11
	v_sub_f32_e32 v11, v86, v100
	v_add_f32_e32 v10, v105, v10
	v_mul_f32_e32 v11, 0x3fb8aa3b, v11
	v_add_f32_e32 v10, v106, v10
	v_exp_f32_e32 v119, v11
	v_sub_f32_e32 v11, v87, v100
	v_add_f32_e32 v10, v107, v10
	v_mul_f32_e32 v11, 0x3fb8aa3b, v11
	v_add_f32_e32 v10, v73, v10
	v_exp_f32_e32 v120, v11
	v_sub_f32_e32 v11, v88, v100
	v_add_f32_e32 v10, v108, v10
	v_mul_f32_e32 v11, 0x3fb8aa3b, v11
	v_add_f32_e32 v10, v109, v10
	v_exp_f32_e32 v121, v11
	v_sub_f32_e32 v11, v89, v100
	v_add_f32_e32 v10, v110, v10
	v_mul_f32_e32 v11, 0x3fb8aa3b, v11
	v_add_f32_e32 v10, v111, v10
	v_exp_f32_e32 v122, v11
	v_sub_f32_e32 v11, v90, v100
	v_add_f32_e32 v10, v112, v10
	v_mul_f32_e32 v11, 0x3fb8aa3b, v11
	v_add_f32_e32 v10, v113, v10
	v_exp_f32_e32 v14, v11
	v_sub_f32_e32 v11, v91, v100
	v_add_f32_e32 v10, v114, v10
	v_mul_f32_e32 v11, 0x3fb8aa3b, v11
	v_add_f32_e32 v10, v115, v10
	v_exp_f32_e32 v15, v11
	v_sub_f32_e32 v11, v92, v100
	v_add_f32_e32 v10, v71, v10
	v_mul_f32_e32 v11, 0x3fb8aa3b, v11
	v_add_f32_e32 v10, v116, v10
	v_exp_f32_e32 v70, v11
	v_sub_f32_e32 v11, v93, v100
	v_add_f32_e32 v10, v117, v10
	v_mul_f32_e32 v11, 0x3fb8aa3b, v11
	v_add_f32_e32 v10, v118, v10
	v_exp_f32_e32 v72, v11
	v_sub_f32_e32 v11, v94, v100
	v_add_f32_e32 v10, v119, v10
	v_mul_f32_e32 v11, 0x3fb8aa3b, v11
	v_add_f32_e32 v10, v120, v10
	v_exp_f32_e32 v123, v11
	v_sub_f32_e32 v11, v95, v100
	v_add_f32_e32 v10, v121, v10
	v_mul_f32_e32 v11, 0x3fb8aa3b, v11
	v_add_f32_e32 v10, v122, v10
	v_exp_f32_e32 v124, v11
	v_sub_f32_e32 v11, v96, v100
	v_add_f32_e32 v10, v14, v10
	v_mul_f32_e32 v11, 0x3fb8aa3b, v11
	v_add_f32_e32 v10, v15, v10
	v_exp_f32_e32 v125, v11
	v_sub_f32_e32 v11, v97, v100
	v_add_f32_e32 v10, v70, v10
	v_mul_f32_e32 v11, 0x3fb8aa3b, v11
	v_add_f32_e32 v10, v72, v10
	v_exp_f32_e32 v126, v11
	v_add_f32_e32 v10, v123, v10
	v_add_f32_e32 v10, v124, v10
	v_sub_f32_e32 v8, v8, v100
	v_add_f32_e32 v10, v125, v10
	v_mul_f32_e32 v8, 0x3fb8aa3b, v8
	v_add_f32_e32 v11, v126, v10
	v_exp_f32_e32 v10, v8
	v_sub_f32_e32 v9, v9, v100
	v_mul_f32_e32 v9, 0x3fb8aa3b, v9
	s_nop 1
	v_cvt_pk_bf16_f32 v74, v101, v102
	v_add_f32_e32 v8, v10, v11
	v_exp_f32_e32 v11, v9
	v_sub_f32_e32 v9, v98, v100
	v_mul_f32_e32 v9, 0x3fb8aa3b, v9
	v_exp_f32_e32 v12, v9
	v_sub_f32_e32 v9, v99, v100
	v_mul_f32_e32 v9, 0x3fb8aa3b, v9
	v_exp_f32_e32 v13, v9
	v_add_f32_e32 v8, v11, v8
	v_add_f32_e32 v8, v12, v8
	v_add_u32_e32 v98, 0x2000, v69
	v_add_f32_e32 v8, v13, v8
	ds_bpermute_b32 v9, v35, v8
	v_add_u32_e32 v99, 0x4000, v69
	s_nop 1
	v_cvt_pk_bf16_f32 v75, v103, v104
	s_nop 1
	v_cvt_pk_bf16_f32 v76, v105, v106
	s_nop 1
	v_cvt_pk_bf16_f32 v77, v107, v73
	s_waitcnt lgkmcnt(0)
	v_add_f32_e32 v8, v8, v9
	ds_bpermute_b32 v9, v36, v8
	ds_read2_b64 v[78:81], v69 offset1:4
	ds_read2_b64 v[82:85], v98 offset0:32 offset1:36
	ds_read2_b64 v[86:89], v99 offset0:64 offset1:68
	s_waitcnt lgkmcnt(2)
	v_mfma_f32_16x16x32_bf16 v[78:81], v[78:81], v[74:77], 0
	v_add_f32_e32 v8, v8, v9
	v_sub_f32_e32 v9, v24, v100
	v_add_u32_e32 v100, 0x6000, v69
	ds_read2_b64 v[90:93], v100 offset0:96 offset1:100
	s_waitcnt lgkmcnt(2)
	v_mfma_f32_16x16x32_bf16 v[82:85], v[82:85], v[74:77], 0
	v_mul_f32_e32 v9, 0x3fb8aa3b, v9
	v_exp_f32_e32 v9, v9
	v_ashrrev_i32_e32 v19, 31, v18
	s_waitcnt lgkmcnt(1)
	v_mfma_f32_16x16x32_bf16 v[86:89], v[86:89], v[74:77], 0
	v_add_f32_e32 v8, v9, v8
	v_add_u32_e32 v9, 32, v69
	s_waitcnt lgkmcnt(0)
	v_mfma_f32_16x16x32_bf16 v[74:77], v[90:93], v[74:77], 0
	s_nop 1
	v_cvt_pk_bf16_f32 v90, v108, v109
	s_nop 1
	v_cvt_pk_bf16_f32 v91, v110, v111
	s_nop 1
	v_cvt_pk_bf16_f32 v92, v112, v113
	s_nop 1
	v_cvt_pk_bf16_f32 v93, v114, v115
	ds_read2_b64 v[94:97], v69 offset0:8 offset1:12
	s_waitcnt lgkmcnt(0)
	v_mfma_f32_16x16x32_bf16 v[78:81], v[94:97], v[90:93], v[78:81]
	ds_read2_b64 v[94:97], v98 offset0:40 offset1:44
	s_waitcnt lgkmcnt(0)
	v_mfma_f32_16x16x32_bf16 v[82:85], v[94:97], v[90:93], v[82:85]
	ds_read2_b64 v[94:97], v99 offset0:72 offset1:76
	s_waitcnt lgkmcnt(0)
	v_mfma_f32_16x16x32_bf16 v[86:89], v[94:97], v[90:93], v[86:89]
	ds_read2_b64 v[94:97], v100 offset0:104 offset1:108
	s_waitcnt lgkmcnt(0)
	v_mfma_f32_16x16x32_bf16 v[74:77], v[94:97], v[90:93], v[74:77]
	s_nop 1
	v_cvt_pk_bf16_f32 v90, v71, v116
	s_nop 1
	v_cvt_pk_bf16_f32 v91, v117, v118
	s_nop 1
	v_cvt_pk_bf16_f32 v92, v119, v120
	s_nop 1
	v_cvt_pk_bf16_f32 v93, v121, v122
	ds_read2_b64 v[94:97], v69 offset0:16 offset1:20
	s_waitcnt lgkmcnt(0)
	v_mfma_f32_16x16x32_bf16 v[78:81], v[94:97], v[90:93], v[78:81]
	ds_read2_b64 v[94:97], v98 offset0:48 offset1:52
	s_waitcnt lgkmcnt(0)
	v_mfma_f32_16x16x32_bf16 v[82:85], v[94:97], v[90:93], v[82:85]
	ds_read2_b64 v[94:97], v99 offset0:80 offset1:84
	s_waitcnt lgkmcnt(0)
	v_mfma_f32_16x16x32_bf16 v[86:89], v[94:97], v[90:93], v[86:89]
	ds_read2_b64 v[94:97], v100 offset0:112 offset1:116
	s_waitcnt lgkmcnt(0)
	v_mfma_f32_16x16x32_bf16 v[74:77], v[94:97], v[90:93], v[74:77]
	s_nop 1
	v_cvt_pk_bf16_f32 v90, v14, v15
	s_nop 1
	v_cvt_pk_bf16_f32 v91, v70, v72
	s_nop 1
	v_cvt_pk_bf16_f32 v92, v123, v124
	s_nop 1
	v_cvt_pk_bf16_f32 v93, v125, v126
	ds_read2_b64 v[70:73], v69 offset0:24 offset1:28
	s_waitcnt lgkmcnt(0)
	v_mfma_f32_16x16x32_bf16 v[70:73], v[70:73], v[90:93], v[78:81]
	s_nop 2
	ds_read2_b64 v[78:81], v98 offset0:56 offset1:60
	v_div_scale_f32 v14, s[8:9], v8, v8, 1.0
	s_waitcnt lgkmcnt(0)
	v_mfma_f32_16x16x32_bf16 v[78:81], v[78:81], v[90:93], v[82:85]
	s_nop 2
	ds_read2_b64 v[82:85], v99 offset0:88 offset1:92
	v_rcp_f32_e32 v15, v14
	s_waitcnt lgkmcnt(0)
	v_mfma_f32_16x16x32_bf16 v[82:85], v[82:85], v[90:93], v[86:89]
	s_nop 2
	ds_read2_b64 v[86:89], v100 offset0:120 offset1:124
	s_nop 1
	v_cvt_pk_bf16_f32 v10, v10, v11
	s_nop 1
	v_cvt_pk_bf16_f32 v11, v12, v13
	s_waitcnt lgkmcnt(0)
	v_mfma_f32_16x16x32_bf16 v[74:77], v[86:89], v[90:93], v[74:77]
	s_nop 1
	v_cvt_pk_bf16_f32 v12, v21, v21
	s_nop 1
	v_cvt_pk_bf16_f32 v13, v21, v21
	ds_read_b64 v[86:87], v69 offset:256
	s_waitcnt lgkmcnt(0)
	v_mov_b32_e32 v88, v86
	v_mov_b32_e32 v89, v87
	s_nop 1
	v_mfma_f32_16x16x32_bf16 v[70:73], v[86:89], v[10:13], v[70:73]
	ds_read_b64 v[86:87], v69 offset:8704
	s_waitcnt lgkmcnt(0)
	v_mov_b32_e32 v88, v86
	v_mov_b32_e32 v89, v87
	s_nop 1
	v_mfma_f32_16x16x32_bf16 v[78:81], v[86:89], v[10:13], v[78:81]
	ds_read_b64 v[86:87], v69 offset:17152
	s_waitcnt lgkmcnt(0)
	v_mov_b32_e32 v88, v86
	v_mov_b32_e32 v89, v87
	s_nop 1
	v_mfma_f32_16x16x32_bf16 v[82:85], v[86:89], v[10:13], v[82:85]
	ds_read_b64 v[86:87], v69 offset:25600
	v_fma_f32 v69, -v14, v15, 1.0
	v_fmac_f32_e32 v15, v69, v15
	v_div_scale_f32 v69, vcc, 1.0, v8, 1.0
	s_waitcnt lgkmcnt(0)
	v_mov_b32_e32 v88, v86
	v_mov_b32_e32 v89, v87
	s_nop 1
	v_mfma_f32_16x16x32_bf16 v[10:13], v[86:89], v[10:13], v[74:77]
	s_nop 2
	v_mul_f32_e32 v74, v69, v15
	v_fma_f32 v75, -v14, v74, v69
	v_fmac_f32_e32 v74, v75, v15
	v_fma_f32 v14, -v14, v74, v69
	v_div_fmas_f32 v14, v14, v15, v74
	v_div_fixup_f32 v8, v14, v8, 1.0
	v_lshlrev_b64 v[14:15], 11, v[18:19]
	v_pk_mul_f32 v[72:73], v[8:9], v[72:73] op_sel_hi:[0,1]
	v_pk_mul_f32 v[70:71], v[8:9], v[70:71] op_sel_hi:[0,1]
	s_nop 1
	v_cvt_pk_bf16_f32 v70, v70, v71
	s_nop 1
	v_cvt_pk_bf16_f32 v71, v72, v73
	v_lshl_add_u64 v[14:15], v[16:17], 0, v[14:15]
	v_pk_mul_f32 v[72:73], v[8:9], v[78:79] op_sel_hi:[0,1]
	global_store_dwordx2 v[14:15], v[70:71], off
	v_pk_mul_f32 v[70:71], v[8:9], v[80:81] op_sel_hi:[0,1]
	s_nop 1
	v_cvt_pk_bf16_f32 v72, v72, v73
	s_nop 1
	v_cvt_pk_bf16_f32 v73, v70, v71
	global_store_dwordx2 v[14:15], v[72:73], off offset:32
	v_pk_mul_f32 v[72:73], v[8:9], v[82:83] op_sel_hi:[0,1]
	v_pk_mul_f32 v[10:11], v[8:9], v[10:11] op_sel_hi:[0,1]
	v_pk_mul_f32 v[70:71], v[8:9], v[84:85] op_sel_hi:[0,1]
	s_nop 1
	v_cvt_pk_bf16_f32 v72, v72, v73
	s_nop 1
	v_cvt_pk_bf16_f32 v73, v70, v71
	global_store_dwordx2 v[14:15], v[72:73], off offset:64
	v_pk_mul_f32 v[12:13], v[8:9], v[12:13] op_sel_hi:[0,1]
	s_nop 1
	v_cvt_pk_bf16_f32 v10, v10, v11
	s_nop 1
	v_cvt_pk_bf16_f32 v11, v12, v13
	global_store_dwordx2 v[14:15], v[10:11], off offset:96
	v_mov_b32_e32 v69, v9
	s_waitcnt vmcnt(4)
	v_mov_b64_e32 v[10:11], v[6:7]
	v_mov_b64_e32 v[14:15], v[2:3]
	v_add_u32_e32 v18, 16, v18
	v_mov_b32_e32 v19, v20
	v_mov_b64_e32 v[8:9], v[4:5]
	v_mov_b64_e32 v[12:13], v[0:1]
	s_cbranch_scc0 .LBB0_1354

.LBB0_1844:
	s_cmp_eq_u32 s55, 28
	s_cselect_b64 s[8:9], -1, 0
	s_cmp_lg_u32 s55, 28
	s_cbranch_scc1 .LBB0_1843
	global_load_dword v144, v[162:163], off
	global_load_dword v146, v[162:163], off offset:64
	global_load_dword v148, v[162:163], off offset:128
	global_load_dword v150, v[162:163], off offset:192
	global_load_dword v152, v[162:163], off offset:512
	global_load_dword v154, v[162:163], off offset:576
	global_load_dword v156, v[162:163], off offset:640
	global_load_dword v158, v[162:163], off offset:704
	s_branch .LBB0_1843

.LBB0_1848:
	s_waitcnt vmcnt(8)
	v_pk_mul_f32 v[124:125], v[144:145], v[124:125] op_sel_hi:[0,1]
	v_pk_mul_f32 v[162:163], v[144:145], v[106:107] op_sel_hi:[0,1]
	v_pk_mul_f32 v[106:107], v[146:147], v[114:115] op_sel_hi:[0,1]
	v_pk_mul_f32 v[114:115], v[146:147], v[92:93] op_sel_hi:[0,1]
	v_pk_mul_f32 v[92:93], v[148:149], v[74:75] op_sel_hi:[0,1]
	v_pk_mul_f32 v[74:75], v[150:151], v[82:83] op_sel_hi:[0,1]
	v_pk_mul_f32 v[82:83], v[150:151], v[68:69] op_sel_hi:[0,1]
	v_pk_mul_f32 v[68:69], v[152:153], v[62:63] op_sel_hi:[0,1]
	v_pk_mul_f32 v[62:63], v[152:153], v[40:41] op_sel_hi:[0,1]
	v_pk_mul_f32 v[40:41], v[154:155], v[48:49] op_sel_hi:[0,1]
	v_pk_mul_f32 v[48:49], v[154:155], v[30:31] op_sel_hi:[0,1]
	v_pk_mul_f32 v[30:31], v[156:157], v[8:9] op_sel_hi:[0,1]
	v_pk_mul_f32 v[8:9], v[158:159], v[16:17] op_sel_hi:[0,1]
	v_mul_f32_e32 v16, 0xbfb8aa3b, v124
	v_mul_f32_e32 v17, 0xbfb8aa3b, v125
	v_exp_f32_e32 v16, v16
	v_exp_f32_e32 v17, v17
	v_pk_mul_f32 v[126:127], v[144:145], v[126:127] op_sel_hi:[0,1]
	v_pk_mul_f32 v[164:165], v[144:145], v[104:105] op_sel_hi:[0,1]
	v_add_f32_e32 v16, 1.0, v16
	v_add_f32_e32 v17, 1.0, v17
	v_rcp_f32_e32 v16, v16
	v_rcp_f32_e32 v17, v17
	v_pk_mul_f32 v[104:105], v[146:147], v[112:113] op_sel_hi:[0,1]
	v_pk_mul_f32 v[112:113], v[146:147], v[94:95] op_sel_hi:[0,1]
	v_pk_mul_f32 v[94:95], v[148:149], v[72:73] op_sel_hi:[0,1]
	v_pk_mul_f32 v[72:73], v[150:151], v[80:81] op_sel_hi:[0,1]
	v_pk_mul_f32 v[80:81], v[150:151], v[70:71] op_sel_hi:[0,1]
	v_pk_mul_f32 v[70:71], v[152:153], v[60:61] op_sel_hi:[0,1]
	v_pk_mul_f32 v[60:61], v[152:153], v[42:43] op_sel_hi:[0,1]
	v_pk_mul_f32 v[42:43], v[154:155], v[50:51] op_sel_hi:[0,1]
	v_pk_mul_f32 v[50:51], v[154:155], v[28:29] op_sel_hi:[0,1]
	v_pk_mul_f32 v[28:29], v[156:157], v[10:11] op_sel_hi:[0,1]
	v_pk_mul_f32 v[10:11], v[158:159], v[18:19] op_sel_hi:[0,1]
	v_mul_f32_e32 v19, 0xbfb8aa3b, v126
	v_pk_mul_f32 v[122:123], v[144:145], v[122:123] op_sel_hi:[0,1]
	v_pk_mul_f32 v[168:169], v[146:147], v[88:89] op_sel_hi:[0,1]
	v_pk_mul_f32 v[88:89], v[148:149], v[96:97] op_sel_hi:[0,1]
	v_pk_mul_f32 v[96:97], v[148:149], v[78:79] op_sel_hi:[0,1]
	v_pk_mul_f32 v[78:79], v[150:151], v[64:65] op_sel_hi:[0,1]
	v_pk_mul_f32 v[64:65], v[152:153], v[46:47] op_sel_hi:[0,1]
	v_pk_mul_f32 v[46:47], v[154:155], v[24:25] op_sel_hi:[0,1]
	v_pk_mul_f32 v[24:25], v[156:157], v[32:33] op_sel_hi:[0,1]
	v_pk_mul_f32 v[32:33], v[156:157], v[14:15] op_sel_hi:[0,1]
	v_pk_mul_f32 v[14:15], v[158:159], v[20:21] op_sel_hi:[0,1]
	v_exp_f32_e32 v19, v19
	v_mul_f32_e32 v20, 0xbfb8aa3b, v127
	v_exp_f32_e32 v21, v20
	v_pk_mul_f32 v[16:17], v[124:125], v[16:17]
	v_mul_f32_e32 v124, 0xbfb8aa3b, v122
	v_mul_f32_e32 v125, 0xbfb8aa3b, v123
	v_exp_f32_e32 v124, v124
	v_exp_f32_e32 v125, v125
	v_add_f32_e32 v19, 1.0, v19
	v_rcp_f32_e32 v20, v19
	v_add_f32_e32 v19, 1.0, v21
	v_rcp_f32_e32 v21, v19
	v_add_f32_e32 v124, 1.0, v124
	v_add_f32_e32 v125, 1.0, v125
	v_pk_mul_f32 v[120:121], v[144:145], v[120:121] op_sel_hi:[0,1]
	v_rcp_f32_e32 v124, v124
	v_rcp_f32_e32 v125, v125
	v_pk_mul_f32 v[166:167], v[146:147], v[90:91] op_sel_hi:[0,1]
	v_pk_mul_f32 v[90:91], v[148:149], v[98:99] op_sel_hi:[0,1]
	v_pk_mul_f32 v[98:99], v[148:149], v[76:77] op_sel_hi:[0,1]
	v_pk_mul_f32 v[76:77], v[150:151], v[66:67] op_sel_hi:[0,1]
	v_pk_mul_f32 v[66:67], v[152:153], v[44:45] op_sel_hi:[0,1]
	v_pk_mul_f32 v[44:45], v[154:155], v[26:27] op_sel_hi:[0,1]
	v_pk_mul_f32 v[26:27], v[156:157], v[34:35] op_sel_hi:[0,1]
	v_pk_mul_f32 v[34:35], v[156:157], v[12:13] op_sel_hi:[0,1]
	v_pk_mul_f32 v[12:13], v[158:159], v[22:23] op_sel_hi:[0,1]
	v_mul_f32_e32 v19, 0xbfb8aa3b, v120
	v_mul_f32_e32 v23, 0xbfb8aa3b, v121
	v_exp_f32_e32 v22, v19
	v_exp_f32_e32 v23, v23
	v_pk_mul_f32 v[110:111], v[144:145], v[110:111] op_sel_hi:[0,1]
	v_pk_mul_f32 v[20:21], v[126:127], v[20:21]
	v_pk_mul_f32 v[108:109], v[144:145], v[108:109] op_sel_hi:[0,1]
	v_pk_mul_f32 v[116:117], v[146:147], v[116:117] op_sel_hi:[0,1]
	v_pk_mul_f32 v[110:111], v[20:21], v[110:111]
	v_pk_mul_f32 v[20:21], v[122:123], v[124:125]
	v_pk_mul_f32 v[16:17], v[16:17], v[108:109]
	v_pk_mul_f32 v[108:109], v[20:21], v[162:163]
	s_nop 1
	v_cvt_pk_bf16_f32 v20, v16, v17
	s_nop 1
	v_cvt_pk_bf16_f32 v21, v110, v111
	v_mul_f32_e32 v110, 0xbfb8aa3b, v116
	v_mul_f32_e32 v111, 0xbfb8aa3b, v117
	v_add_f32_e32 v22, 1.0, v22
	v_add_f32_e32 v23, 1.0, v23
	v_exp_f32_e32 v110, v110
	v_exp_f32_e32 v111, v111
	v_rcp_f32_e32 v22, v22
	v_rcp_f32_e32 v23, v23
	v_add_f32_e32 v110, 1.0, v110
	v_add_f32_e32 v111, 1.0, v111
	v_lshl_or_b32 v18, s50, 7, v149
	v_pk_mul_f32 v[22:23], v[120:121], v[22:23]
	v_rcp_f32_e32 v110, v110
	v_rcp_f32_e32 v111, v111
	v_ashrrev_i32_e32 v19, 31, v18
	v_pk_mul_f32 v[22:23], v[22:23], v[164:165]
	v_mov_b64_e32 v[16:17], s[4:5]
	v_pk_mul_f32 v[118:119], v[146:147], v[118:119] op_sel_hi:[0,1]
	s_nop 1
	v_cvt_pk_bf16_f32 v22, v22, v23
	s_nop 1
	v_cvt_pk_bf16_f32 v23, v108, v109
	v_mad_i64_i32 v[108:109], s[8:9], v160, s49, v[16:17]
	v_lshlrev_b64 v[18:19], 1, v[18:19]
	v_lshl_add_u64 v[108:109], v[108:109], 0, v[18:19]
	v_mul_f32_e32 v120, 0xbfb8aa3b, v118
	v_mul_f32_e32 v121, 0xbfb8aa3b, v119
	v_exp_f32_e32 v120, v120
	v_exp_f32_e32 v121, v121
	v_mul_f32_e32 v122, 0xbfb8aa3b, v104
	global_store_dwordx4 v[108:109], v[20:23], off
	v_mul_f32_e32 v109, 0xbfb8aa3b, v105
	v_exp_f32_e32 v122, v122
	v_pk_mul_f32 v[22:23], v[116:117], v[110:111]
	v_mul_f32_e32 v110, 0xbfb8aa3b, v106
	v_mul_f32_e32 v111, 0xbfb8aa3b, v107
	v_exp_f32_e32 v109, v109
	v_exp_f32_e32 v110, v110
	v_exp_f32_e32 v111, v111
	v_add_f32_e32 v120, 1.0, v120
	v_add_f32_e32 v121, 1.0, v121
	v_rcp_f32_e32 v120, v120
	v_rcp_f32_e32 v121, v121
	v_add_f32_e32 v108, 1.0, v122
	v_add_f32_e32 v109, 1.0, v109
	v_add_f32_e32 v110, 1.0, v110
	v_add_f32_e32 v111, 1.0, v111
	v_rcp_f32_e32 v108, v108
	v_rcp_f32_e32 v110, v110
	v_rcp_f32_e32 v111, v111
	v_rcp_f32_e32 v109, v109
	v_pk_mul_f32 v[20:21], v[118:119], v[120:121]
	v_pk_mul_f32 v[102:103], v[148:149], v[102:103] op_sel_hi:[0,1]
	v_pk_mul_f32 v[112:113], v[20:21], v[112:113]
	v_pk_mul_f32 v[20:21], v[22:23], v[114:115]
	v_pk_mul_f32 v[22:23], v[106:107], v[110:111]
	v_pk_mul_f32 v[104:105], v[104:105], v[108:109]
	v_pk_mul_f32 v[100:101], v[148:149], v[100:101] op_sel_hi:[0,1]
	v_pk_mul_f32 v[106:107], v[22:23], v[166:167]
	v_pk_mul_f32 v[22:23], v[104:105], v[168:169]
	s_nop 1
	v_cvt_pk_bf16_f32 v20, v20, v21
	s_nop 1
	v_cvt_pk_bf16_f32 v21, v112, v113
	v_mul_f32_e32 v108, 0xbfb8aa3b, v102
	s_nop 1
	v_cvt_pk_bf16_f32 v22, v22, v23
	s_nop 1
	v_cvt_pk_bf16_f32 v23, v106, v107
	v_mul_f32_e32 v106, 0xbfb8aa3b, v100
	v_mul_f32_e32 v107, 0xbfb8aa3b, v101
	v_mul_f32_e32 v109, 0xbfb8aa3b, v103
	v_exp_f32_e32 v106, v106
	v_exp_f32_e32 v107, v107
	v_exp_f32_e32 v108, v108
	v_exp_f32_e32 v109, v109
	v_add_f32_e32 v106, 1.0, v106
	v_add_f32_e32 v107, 1.0, v107
	v_add_f32_e32 v108, 1.0, v108
	v_add_f32_e32 v109, 1.0, v109
	v_rcp_f32_e32 v106, v106
	v_rcp_f32_e32 v107, v107
	v_rcp_f32_e32 v108, v108
	v_rcp_f32_e32 v109, v109
	v_or_b32_e32 v104, 16, v160
	v_mad_i64_i32 v[104:105], s[8:9], v104, s49, v[16:17]
	v_lshl_add_u64 v[104:105], v[104:105], 0, v[18:19]
	v_mul_f32_e32 v110, 0xbfb8aa3b, v88
	global_store_dwordx4 v[104:105], v[20:23], off
	v_exp_f32_e32 v110, v110
	v_pk_mul_f32 v[86:87], v[150:151], v[86:87] op_sel_hi:[0,1]
	v_pk_mul_f32 v[20:21], v[102:103], v[108:109]
	v_pk_mul_f32 v[22:23], v[100:101], v[106:107]
	v_mul_f32_e32 v101, 0xbfb8aa3b, v89
	v_mul_f32_e32 v102, 0xbfb8aa3b, v90
	v_mul_f32_e32 v103, 0xbfb8aa3b, v91
	v_exp_f32_e32 v101, v101
	v_exp_f32_e32 v102, v102
	v_exp_f32_e32 v103, v103
	v_add_f32_e32 v100, 1.0, v110
	v_add_f32_e32 v101, 1.0, v101
	v_add_f32_e32 v102, 1.0, v102
	v_add_f32_e32 v103, 1.0, v103
	v_rcp_f32_e32 v100, v100
	v_rcp_f32_e32 v102, v102
	v_rcp_f32_e32 v103, v103
	v_rcp_f32_e32 v101, v101
	v_pk_mul_f32 v[96:97], v[20:21], v[96:97]
	v_pk_mul_f32 v[20:21], v[22:23], v[98:99]
	v_pk_mul_f32 v[22:23], v[90:91], v[102:103]
	v_pk_mul_f32 v[88:89], v[88:89], v[100:101]
	v_pk_mul_f32 v[84:85], v[150:151], v[84:85] op_sel_hi:[0,1]
	v_pk_mul_f32 v[90:91], v[22:23], v[92:93]
	v_pk_mul_f32 v[22:23], v[88:89], v[94:95]
	s_nop 1
	v_cvt_pk_bf16_f32 v20, v20, v21
	s_nop 1
	v_cvt_pk_bf16_f32 v21, v96, v97
	v_mul_f32_e32 v92, 0xbfb8aa3b, v86
	s_nop 1
	v_cvt_pk_bf16_f32 v22, v22, v23
	s_nop 1
	v_cvt_pk_bf16_f32 v23, v90, v91
	v_mul_f32_e32 v90, 0xbfb8aa3b, v84
	v_mul_f32_e32 v91, 0xbfb8aa3b, v85
	v_mul_f32_e32 v93, 0xbfb8aa3b, v87
	v_exp_f32_e32 v90, v90
	v_exp_f32_e32 v91, v91
	v_exp_f32_e32 v92, v92
	v_exp_f32_e32 v93, v93
	v_add_f32_e32 v90, 1.0, v90
	v_add_f32_e32 v91, 1.0, v91
	v_add_f32_e32 v92, 1.0, v92
	v_add_f32_e32 v93, 1.0, v93
	v_rcp_f32_e32 v90, v90
	v_rcp_f32_e32 v91, v91
	v_rcp_f32_e32 v92, v92
	v_rcp_f32_e32 v93, v93
	v_or_b32_e32 v88, 32, v160
	v_mad_i64_i32 v[88:89], s[8:9], v88, s49, v[16:17]
	v_lshl_add_u64 v[88:89], v[88:89], 0, v[18:19]
	v_mul_f32_e32 v94, 0xbfb8aa3b, v72
	global_store_dwordx4 v[88:89], v[20:23], off
	v_exp_f32_e32 v94, v94
	v_pk_mul_f32 v[58:59], v[152:153], v[58:59] op_sel_hi:[0,1]
	v_pk_mul_f32 v[20:21], v[86:87], v[92:93]
	v_pk_mul_f32 v[22:23], v[84:85], v[90:91]
	v_mul_f32_e32 v85, 0xbfb8aa3b, v73
	v_mul_f32_e32 v86, 0xbfb8aa3b, v74
	v_mul_f32_e32 v87, 0xbfb8aa3b, v75
	v_exp_f32_e32 v85, v85
	v_exp_f32_e32 v86, v86
	v_exp_f32_e32 v87, v87
	v_add_f32_e32 v84, 1.0, v94
	v_add_f32_e32 v85, 1.0, v85
	v_add_f32_e32 v86, 1.0, v86
	v_add_f32_e32 v87, 1.0, v87
	v_rcp_f32_e32 v84, v84
	v_rcp_f32_e32 v86, v86
	v_rcp_f32_e32 v87, v87
	v_rcp_f32_e32 v85, v85
	v_pk_mul_f32 v[80:81], v[20:21], v[80:81]
	v_pk_mul_f32 v[20:21], v[22:23], v[82:83]
	v_pk_mul_f32 v[22:23], v[74:75], v[86:87]
	v_pk_mul_f32 v[72:73], v[72:73], v[84:85]
	v_pk_mul_f32 v[74:75], v[22:23], v[76:77]
	v_pk_mul_f32 v[22:23], v[72:73], v[78:79]
	v_or_b32_e32 v72, 48, v160
	v_mad_i64_i32 v[72:73], s[8:9], v72, s49, v[16:17]
	s_nop 1
	v_cvt_pk_bf16_f32 v20, v20, v21
	s_nop 1
	v_cvt_pk_bf16_f32 v21, v80, v81
	s_nop 1
	v_cvt_pk_bf16_f32 v22, v22, v23
	s_nop 1
	v_cvt_pk_bf16_f32 v23, v74, v75
	v_lshl_add_u64 v[72:73], v[72:73], 0, v[18:19]
	v_mul_f32_e32 v74, 0xbfb8aa3b, v70
	v_mul_f32_e32 v75, 0xbfb8aa3b, v71
	v_exp_f32_e32 v74, v74
	v_exp_f32_e32 v75, v75
	global_store_dwordx4 v[72:73], v[20:23], off
	v_pk_mul_f32 v[56:57], v[152:153], v[56:57] op_sel_hi:[0,1]
	v_mul_f32_e32 v72, 0xbfb8aa3b, v56
	v_mul_f32_e32 v22, 0xbfb8aa3b, v68
	v_mul_f32_e32 v23, 0xbfb8aa3b, v69
	v_exp_f32_e32 v22, v22
	v_exp_f32_e32 v23, v23
	v_add_f32_e32 v20, 1.0, v74
	v_add_f32_e32 v21, 1.0, v75
	v_rcp_f32_e32 v20, v20
	v_rcp_f32_e32 v21, v21
	v_add_f32_e32 v22, 1.0, v22
	v_add_f32_e32 v23, 1.0, v23
	v_rcp_f32_e32 v22, v22
	v_rcp_f32_e32 v23, v23
	v_pk_mul_f32 v[20:21], v[70:71], v[20:21]
	v_mul_f32_e32 v70, 0xbfb8aa3b, v58
	v_mul_f32_e32 v71, 0xbfb8aa3b, v59
	v_pk_mul_f32 v[22:23], v[68:69], v[22:23]
	v_mul_f32_e32 v69, 0xbfb8aa3b, v57
	v_exp_f32_e32 v70, v70
	v_exp_f32_e32 v71, v71
	v_exp_f32_e32 v72, v72
	v_exp_f32_e32 v69, v69
	v_add_f32_e32 v70, 1.0, v70
	v_add_f32_e32 v71, 1.0, v71
	v_add_f32_e32 v68, 1.0, v72
	v_add_f32_e32 v69, 1.0, v69
	v_rcp_f32_e32 v70, v70
	v_rcp_f32_e32 v71, v71
	v_rcp_f32_e32 v68, v68
	v_rcp_f32_e32 v69, v69
	v_pk_mul_f32 v[54:55], v[154:155], v[54:55] op_sel_hi:[0,1]
	v_pk_mul_f32 v[58:59], v[58:59], v[70:71]
	v_pk_mul_f32 v[52:53], v[154:155], v[52:53] op_sel_hi:[0,1]
	v_pk_mul_f32 v[22:23], v[22:23], v[64:65]
	v_pk_mul_f32 v[20:21], v[20:21], v[66:67]
	v_pk_mul_f32 v[56:57], v[56:57], v[68:69]
	v_pk_mul_f32 v[58:59], v[58:59], v[60:61]
	v_pk_mul_f32 v[56:57], v[56:57], v[62:63]
	s_nop 1
	v_cvt_pk_bf16_f32 v20, v20, v21
	s_nop 1
	v_cvt_pk_bf16_f32 v21, v22, v23
	v_mul_f32_e32 v60, 0xbfb8aa3b, v54
	s_nop 1
	v_cvt_pk_bf16_f32 v22, v56, v57
	s_nop 1
	v_cvt_pk_bf16_f32 v23, v58, v59
	v_mul_f32_e32 v58, 0xbfb8aa3b, v52
	v_mul_f32_e32 v59, 0xbfb8aa3b, v53
	v_mul_f32_e32 v61, 0xbfb8aa3b, v55
	v_exp_f32_e32 v58, v58
	v_exp_f32_e32 v59, v59
	v_exp_f32_e32 v60, v60
	v_exp_f32_e32 v61, v61
	v_add_f32_e32 v58, 1.0, v58
	v_add_f32_e32 v59, 1.0, v59
	v_add_f32_e32 v60, 1.0, v60
	v_add_f32_e32 v61, 1.0, v61
	v_rcp_f32_e32 v58, v58
	v_rcp_f32_e32 v59, v59
	v_rcp_f32_e32 v60, v60
	v_rcp_f32_e32 v61, v61
	v_add_u32_e32 v73, 0x80, v160
	v_mad_i64_i32 v[56:57], s[8:9], v73, s49, v[16:17]
	v_lshl_add_u64 v[56:57], v[56:57], 0, v[18:19]
	v_mul_f32_e32 v62, 0xbfb8aa3b, v40
	global_store_dwordx4 v[56:57], v[20:23], off
	v_exp_f32_e32 v62, v62
	v_pk_mul_f32 v[38:39], v[156:157], v[38:39] op_sel_hi:[0,1]
	v_pk_mul_f32 v[20:21], v[54:55], v[60:61]
	v_pk_mul_f32 v[22:23], v[52:53], v[58:59]
	v_mul_f32_e32 v53, 0xbfb8aa3b, v41
	v_mul_f32_e32 v54, 0xbfb8aa3b, v42
	v_mul_f32_e32 v55, 0xbfb8aa3b, v43
	v_exp_f32_e32 v53, v53
	v_exp_f32_e32 v54, v54
	v_exp_f32_e32 v55, v55
	v_add_f32_e32 v52, 1.0, v62
	v_add_f32_e32 v53, 1.0, v53
	v_add_f32_e32 v54, 1.0, v54
	v_add_f32_e32 v55, 1.0, v55
	v_rcp_f32_e32 v52, v52
	v_rcp_f32_e32 v54, v54
	v_rcp_f32_e32 v55, v55
	v_rcp_f32_e32 v53, v53
	v_pk_mul_f32 v[48:49], v[20:21], v[48:49]
	v_pk_mul_f32 v[20:21], v[22:23], v[50:51]
	v_pk_mul_f32 v[22:23], v[42:43], v[54:55]
	v_pk_mul_f32 v[40:41], v[40:41], v[52:53]
	v_pk_mul_f32 v[36:37], v[156:157], v[36:37] op_sel_hi:[0,1]
	v_pk_mul_f32 v[42:43], v[22:23], v[44:45]
	v_pk_mul_f32 v[22:23], v[40:41], v[46:47]
	s_nop 1
	v_cvt_pk_bf16_f32 v20, v20, v21
	s_nop 1
	v_cvt_pk_bf16_f32 v21, v48, v49
	v_mul_f32_e32 v44, 0xbfb8aa3b, v38
	s_nop 1
	v_cvt_pk_bf16_f32 v22, v22, v23
	s_nop 1
	v_cvt_pk_bf16_f32 v23, v42, v43
	v_mul_f32_e32 v42, 0xbfb8aa3b, v36
	v_mul_f32_e32 v43, 0xbfb8aa3b, v37
	v_mul_f32_e32 v45, 0xbfb8aa3b, v39
	v_exp_f32_e32 v42, v42
	v_exp_f32_e32 v43, v43
	v_exp_f32_e32 v44, v44
	v_exp_f32_e32 v45, v45
	v_add_f32_e32 v42, 1.0, v42
	v_add_f32_e32 v43, 1.0, v43
	v_add_f32_e32 v44, 1.0, v44
	v_add_f32_e32 v45, 1.0, v45
	v_rcp_f32_e32 v42, v42
	v_rcp_f32_e32 v43, v43
	v_rcp_f32_e32 v44, v44
	v_rcp_f32_e32 v45, v45
	v_add_u32_e32 v40, 0x90, v160
	v_mad_i64_i32 v[40:41], s[8:9], v40, s49, v[16:17]
	v_lshl_add_u64 v[40:41], v[40:41], 0, v[18:19]
	v_mul_f32_e32 v46, 0xbfb8aa3b, v24
	global_store_dwordx4 v[40:41], v[20:23], off
	v_exp_f32_e32 v46, v46
	v_pk_mul_f32 v[4:5], v[158:159], v[4:5] op_sel_hi:[0,1]
	v_pk_mul_f32 v[20:21], v[38:39], v[44:45]
	v_pk_mul_f32 v[22:23], v[36:37], v[42:43]
	v_mul_f32_e32 v37, 0xbfb8aa3b, v25
	v_mul_f32_e32 v38, 0xbfb8aa3b, v26
	v_mul_f32_e32 v39, 0xbfb8aa3b, v27
	v_exp_f32_e32 v37, v37
	v_exp_f32_e32 v38, v38
	v_exp_f32_e32 v39, v39
	v_add_f32_e32 v36, 1.0, v46
	v_add_f32_e32 v37, 1.0, v37
	v_add_f32_e32 v38, 1.0, v38
	v_add_f32_e32 v39, 1.0, v39
	v_rcp_f32_e32 v36, v36
	v_rcp_f32_e32 v38, v38
	v_rcp_f32_e32 v39, v39
	v_rcp_f32_e32 v37, v37
	v_pk_mul_f32 v[32:33], v[20:21], v[32:33]
	v_pk_mul_f32 v[20:21], v[22:23], v[34:35]
	v_pk_mul_f32 v[22:23], v[26:27], v[38:39]
	v_pk_mul_f32 v[24:25], v[24:25], v[36:37]
	v_pk_mul_f32 v[26:27], v[22:23], v[28:29]
	v_pk_mul_f32 v[22:23], v[24:25], v[30:31]
	v_add_u32_e32 v24, 0xa0, v160
	v_mad_i64_i32 v[24:25], s[8:9], v24, s49, v[16:17]
	s_nop 1
	v_cvt_pk_bf16_f32 v20, v20, v21
	s_nop 1
	v_cvt_pk_bf16_f32 v21, v32, v33
	s_nop 1
	v_cvt_pk_bf16_f32 v22, v22, v23
	s_nop 1
	v_cvt_pk_bf16_f32 v23, v26, v27
	v_mul_f32_e32 v26, 0xbfb8aa3b, v14
	v_mul_f32_e32 v27, 0xbfb8aa3b, v15
	v_lshl_add_u64 v[24:25], v[24:25], 0, v[18:19]
	v_exp_f32_e32 v26, v26
	v_exp_f32_e32 v27, v27
	v_mul_f32_e32 v30, 0xbfb8aa3b, v8
	global_store_dwordx4 v[24:25], v[20:23], off
	v_exp_f32_e32 v30, v30
	v_mul_f32_e32 v28, 0xbfb8aa3b, v12
	v_mul_f32_e32 v21, 0xbfb8aa3b, v9
	v_mul_f32_e32 v22, 0xbfb8aa3b, v10
	v_mul_f32_e32 v23, 0xbfb8aa3b, v11
	v_exp_f32_e32 v21, v21
	v_exp_f32_e32 v22, v22
	v_exp_f32_e32 v23, v23
	v_mul_f32_e32 v29, 0xbfb8aa3b, v13
	v_add_f32_e32 v26, 1.0, v26
	v_add_f32_e32 v27, 1.0, v27
	v_exp_f32_e32 v28, v28
	v_exp_f32_e32 v29, v29
	v_rcp_f32_e32 v26, v26
	v_rcp_f32_e32 v27, v27
	v_add_f32_e32 v20, 1.0, v30
	v_add_f32_e32 v21, 1.0, v21
	v_add_f32_e32 v22, 1.0, v22
	v_add_f32_e32 v23, 1.0, v23
	v_rcp_f32_e32 v20, v20
	v_rcp_f32_e32 v22, v22
	v_rcp_f32_e32 v23, v23
	v_rcp_f32_e32 v21, v21
	v_add_f32_e32 v28, 1.0, v28
	v_add_f32_e32 v29, 1.0, v29
	v_rcp_f32_e32 v28, v28
	v_rcp_f32_e32 v29, v29
	v_pk_mul_f32 v[14:15], v[14:15], v[26:27]
	v_pk_mul_f32 v[2:3], v[158:159], v[2:3] op_sel_hi:[0,1]
	v_pk_mul_f32 v[0:1], v[158:159], v[0:1] op_sel_hi:[0,1]
	v_pk_mul_f32 v[4:5], v[14:15], v[4:5]
	v_pk_mul_f32 v[10:11], v[10:11], v[22:23]
	v_pk_mul_f32 v[8:9], v[8:9], v[20:21]
	v_pk_mul_f32 v[10:11], v[10:11], v[2:3]
	v_pk_mul_f32 v[2:3], v[8:9], v[0:1]
	s_nop 1
	v_cvt_pk_bf16_f32 v0, v4, v5
	v_add_u32_e32 v4, 0xb0, v160
	v_mad_i64_i32 v[4:5], s[8:9], v4, s49, v[16:17]
	v_pk_mul_f32 v[6:7], v[158:159], v[6:7] op_sel_hi:[0,1]
	v_pk_mul_f32 v[12:13], v[12:13], v[28:29]
	v_lshl_add_u64 v[4:5], v[4:5], 0, v[18:19]
	s_andn2_b64 vcc, exec, s[2:3]
	s_mov_b64 s[2:3], -1
	v_pk_mul_f32 v[6:7], v[12:13], v[6:7]
	s_nop 0
	s_nop 1
	v_cvt_pk_bf16_f32 v1, v6, v7
	s_nop 1
	v_cvt_pk_bf16_f32 v2, v2, v3
	s_nop 1
	v_cvt_pk_bf16_f32 v3, v10, v11
	global_store_dwordx4 v[4:5], v[0:3], off
	s_cbranch_vccnz .LBB0_1835
	s_andn2_b64 vcc, exec, s[0:1]
	s_cbranch_vccnz .LBB0_1834
	s_barrier
	s_branch .LBB0_1834
